# on top of balanced loads: last LDS-DMA of each load segment issued in the middle of the following MFMA segment (3 per load segment + 1 per MFMA segment), waits N-1
# baseline (speedup 1.0000x reference)
; #define PG8_STAGE(bufoff, gbase, voff) do { _Pragma("unroll") for (int _i = 0; _i < 2; ++_i) \
;         __builtin_amdgcn_global_load_lds((const unsigned*)((const char*)(gbase) + (voff)[_i]), (LAS unsigned*)(lds + (bufoff) + ldsw + _i * 8192), 16, 0, ((voff) == voffA ? AUXA : 0)); } while (0)
; #define PG8_LDA(dst, b, h) do { _Pragma("unroll") for (int m = 0; m < 4; ++m) _Pragma("unroll") for (int k = 0; k < 2; ++k) dst[m][k] = *(const LAS bf16x8*)(lds + PG8_SA(b, h) + aoff + m * 2048 + k * 1024); } while (0)
; #define PG8_LDB(dst, b, h) do { _Pragma("unroll") for (int n = 0; n < 2; ++n) _Pragma("unroll") for (int k = 0; k < 2; ++k) dst[n][k] = *(const LAS bf16x8*)(lds + PG8_SB(b, h) + boff + n * 2048 + k * 1024); } while (0)
; #define PG8_MMA(ai, bj, At, Bt) do { __builtin_amdgcn_s_setprio(1); _Pragma("unroll") for (int m = 0; m < 4; ++m) _Pragma("unroll") for (int n = 0; n < 2; ++n) _Pragma("unroll") for (int k = 0; k < 2; ++k) \
;         acc[ai][bj][m][n] = __builtin_amdgcn_mfma_f32_16x16x32_bf16(Bt[n][k], At[m][k], acc[ai][bj][m][n], 0, 0, 0); __builtin_amdgcn_s_setprio(0); } while (0)
; #define PG8_WAIT_V(n) asm volatile("s_waitcnt vmcnt(" #n ")" ::: "memory")
;     ...
;             PG8_LDB(B0, 0, 0); PG8_LDB(B1, 0, 1); PG8_SCHED; PG8_LDA(At, 0, 0); PG8_STAGE(PG8_SA(1, 1), a1 + hsA, voffA);
;             if (Epi::NPRE != 0 && last) { E.pre(sv, cur, wr, fr); PG8_WAIT_V(16); } else { PG8_WAIT_V(8); }
;             PG8_WAIT_L(0); PG8_BAR; PG8_MMA(0, 0, At, B0); PG8_MMA(0, 1, At, B1); PG8_BAR; PG8_SCHED;
;             PG8_LDA(At, 0, 1); PG8_STAGE(PG8_SB(0, 0), b2, voffB); PG8_STAGE(PG8_SB(0, 1), b2 + hsB, voffB); PG8_STAGE(PG8_SA(0, 0), a2, voffA);
;             if (Epi::NPRE != 0 && last) { PG8_WAIT_V(16); } else { PG8_WAIT_V(8); }
;             PG8_WAIT_L(0); PG8_BAR; PG8_MMA(1, 0, At, B0); PG8_MMA(1, 1, At, B1); PG8_BAR; PG8_SCHED;
;             PG8_LDB(B0, 1, 0); PG8_LDB(B1, 1, 1); PG8_SCHED; PG8_LDA(At, 1, 0); PG8_STAGE(PG8_SA(0, 1), a2 + hsA, voffA);
;             PG8_WAIT_V(8); PG8_WAIT_L(0); PG8_BAR; PG8_MMA(0, 0, At, B0); PG8_MMA(0, 1, At, B1); PG8_BAR; PG8_SCHED;
;             PG8_LDA(At, 1, 1); PG8_STAGE(PG8_SB(1, 0), b3, voffB); PG8_STAGE(PG8_SB(1, 1), b3 + hsB, voffB); PG8_STAGE(PG8_SA(1, 0), a3, voffA);
;             PG8_WAIT_V(8); PG8_WAIT_L(0); PG8_BAR; PG8_MMA(1, 0, At, B0); PG8_MMA(1, 1, At, B1); PG8_BAR; PG8_SCHED;
.LBB0_148:
	s_waitcnt lgkmcnt(0)
	s_add_i32 s61, s61, 2
	s_setprio 1
	s_barrier
	v_mfma_f32_16x16x32_bf16 v[60:63], v[144:147], v[184:187], v[60:63]
	v_mfma_f32_16x16x32_bf16 v[52:55], v[152:155], v[184:187], v[52:55]
	v_mfma_f32_16x16x32_bf16 v[44:47], v[144:147], v[176:179], v[44:47]
	v_mfma_f32_16x16x32_bf16 v[36:39], v[152:155], v[176:179], v[36:39]
	v_mfma_f32_16x16x32_bf16 v[28:31], v[144:147], v[168:171], v[28:31]
	v_mfma_f32_16x16x32_bf16 v[20:23], v[152:155], v[168:171], v[20:23]
	v_mfma_f32_16x16x32_bf16 v[12:15], v[144:147], v[160:163], v[12:15]
	v_mfma_f32_16x16x32_bf16 v[4:7], v[152:155], v[160:163], v[4:7]
	v_mfma_f32_16x16x32_bf16 v[60:63], v[148:151], v[188:191], v[60:63]
	v_mfma_f32_16x16x32_bf16 v[52:55], v[156:159], v[188:191], v[52:55]
	v_mfma_f32_16x16x32_bf16 v[44:47], v[148:151], v[180:183], v[44:47]
	v_mfma_f32_16x16x32_bf16 v[36:39], v[156:159], v[180:183], v[36:39]
	v_mfma_f32_16x16x32_bf16 v[28:31], v[148:151], v[172:175], v[28:31]
	v_mfma_f32_16x16x32_bf16 v[20:23], v[156:159], v[172:175], v[20:23]
	v_mfma_f32_16x16x32_bf16 v[12:15], v[148:151], v[164:167], v[12:15]
	v_mfma_f32_16x16x32_bf16 v[4:7], v[156:159], v[164:167], v[4:7]
	s_mov_b32 m0, s44
	s_nop 0
	global_load_lds_dwordx4 v194, s[100:101]
	v_mfma_f32_16x16x32_bf16 v[56:59], v[128:131], v[184:187], v[56:59]
	v_mfma_f32_16x16x32_bf16 v[48:51], v[136:139], v[184:187], v[48:51]
	v_mfma_f32_16x16x32_bf16 v[40:43], v[128:131], v[176:179], v[40:43]
	v_mfma_f32_16x16x32_bf16 v[32:35], v[136:139], v[176:179], v[32:35]
	v_mfma_f32_16x16x32_bf16 v[24:27], v[128:131], v[168:171], v[24:27]
	v_mfma_f32_16x16x32_bf16 v[16:19], v[136:139], v[168:171], v[16:19]
	v_mfma_f32_16x16x32_bf16 v[8:11], v[128:131], v[160:163], v[8:11]
	v_mfma_f32_16x16x32_bf16 v[0:3], v[136:139], v[160:163], v[0:3]
	v_mfma_f32_16x16x32_bf16 v[56:59], v[132:135], v[188:191], v[56:59]
	v_mfma_f32_16x16x32_bf16 v[48:51], v[140:143], v[188:191], v[48:51]
	v_mfma_f32_16x16x32_bf16 v[40:43], v[132:135], v[180:183], v[40:43]
	v_mfma_f32_16x16x32_bf16 v[32:35], v[140:143], v[180:183], v[32:35]
	v_mfma_f32_16x16x32_bf16 v[24:27], v[132:135], v[172:175], v[24:27]
	v_mfma_f32_16x16x32_bf16 v[16:19], v[140:143], v[172:175], v[16:19]
	v_mfma_f32_16x16x32_bf16 v[8:11], v[132:135], v[164:167], v[8:11]
	v_mfma_f32_16x16x32_bf16 v[0:3], v[140:143], v[164:167], v[0:3]
	s_barrier
	s_mov_b32 m0, s40
	s_nop 0
	global_load_lds_dwordx4 v200, s[34:35]
	s_mov_b32 m0, s45
	s_nop 0
	global_load_lds_dwordx4 v196, s[34:35]
	s_setprio 0
	s_add_i32 s36, 0, 0x18000
	s_add_i32 s37, 0, 0x1c000
	v_add_u32_e32 v140, s36, v222
	v_add_u32_e32 v156, s37, v222
	ds_read_b128 v[128:131], v140
	ds_read_b128 v[132:135], v140 offset:1024
	ds_read_b128 v[136:139], v140 offset:2048
	ds_read_b128 v[140:143], v140 offset:3072
	ds_read_b128 v[144:147], v156
	ds_read_b128 v[148:151], v156 offset:1024
	ds_read_b128 v[152:155], v156 offset:2048
	ds_read_b128 v[156:159], v156 offset:3072
	s_add_u32 s34, s34, 0x80000
	s_addc_u32 s35, s35, 0
	s_mov_b32 m0, s46
	ds_read_b128 v[160:163], v226 offset:32768
	ds_read_b128 v[164:167], v226 offset:33792
	ds_read_b128 v[168:171], v226 offset:34816
	ds_read_b128 v[172:175], v226 offset:35840
	ds_read_b128 v[176:179], v226 offset:36864
	ds_read_b128 v[180:183], v226 offset:37888
	ds_read_b128 v[184:187], v226 offset:38912
	ds_read_b128 v[188:191], v226 offset:39936
	global_load_lds_dwordx4 v200, s[34:35]
	s_waitcnt vmcnt(7)
	s_waitcnt lgkmcnt(0)
	s_setprio 1
	s_barrier
	v_mfma_f32_16x16x32_bf16 v[124:127], v[128:131], v[160:163], v[124:127]
	v_mfma_f32_16x16x32_bf16 v[116:119], v[136:139], v[160:163], v[116:119]
	v_mfma_f32_16x16x32_bf16 v[108:111], v[128:131], v[168:171], v[108:111]
	v_mfma_f32_16x16x32_bf16 v[100:103], v[136:139], v[168:171], v[100:103]
	v_mfma_f32_16x16x32_bf16 v[92:95], v[128:131], v[176:179], v[92:95]
	v_mfma_f32_16x16x32_bf16 v[84:87], v[136:139], v[176:179], v[84:87]
	v_mfma_f32_16x16x32_bf16 v[76:79], v[128:131], v[184:187], v[76:79]
	v_mfma_f32_16x16x32_bf16 v[68:71], v[136:139], v[184:187], v[68:71]
	v_mfma_f32_16x16x32_bf16 v[124:127], v[132:135], v[164:167], v[124:127]
	v_mfma_f32_16x16x32_bf16 v[116:119], v[140:143], v[164:167], v[116:119]
	v_mfma_f32_16x16x32_bf16 v[108:111], v[132:135], v[172:175], v[108:111]
	v_mfma_f32_16x16x32_bf16 v[100:103], v[140:143], v[172:175], v[100:103]
	v_mfma_f32_16x16x32_bf16 v[92:95], v[132:135], v[180:183], v[92:95]
	v_mfma_f32_16x16x32_bf16 v[84:87], v[140:143], v[180:183], v[84:87]
	v_mfma_f32_16x16x32_bf16 v[76:79], v[132:135], v[188:191], v[76:79]
	v_mfma_f32_16x16x32_bf16 v[68:71], v[140:143], v[188:191], v[68:71]
	s_mov_b32 m0, s47
	s_nop 0
	global_load_lds_dwordx4 v196, s[34:35]
	v_mfma_f32_16x16x32_bf16 v[120:123], v[144:147], v[160:163], v[120:123]
	v_mfma_f32_16x16x32_bf16 v[112:115], v[152:155], v[160:163], v[112:115]
	v_mfma_f32_16x16x32_bf16 v[104:107], v[144:147], v[168:171], v[104:107]
	v_mfma_f32_16x16x32_bf16 v[96:99], v[152:155], v[168:171], v[96:99]
	v_mfma_f32_16x16x32_bf16 v[88:91], v[144:147], v[176:179], v[88:91]
	v_mfma_f32_16x16x32_bf16 v[80:83], v[152:155], v[176:179], v[80:83]
	v_mfma_f32_16x16x32_bf16 v[72:75], v[144:147], v[184:187], v[72:75]
	v_mfma_f32_16x16x32_bf16 v[64:67], v[152:155], v[184:187], v[64:67]
	v_mfma_f32_16x16x32_bf16 v[120:123], v[148:151], v[164:167], v[120:123]
	v_mfma_f32_16x16x32_bf16 v[112:115], v[156:159], v[164:167], v[112:115]
	v_mfma_f32_16x16x32_bf16 v[104:107], v[148:151], v[172:175], v[104:107]
	v_mfma_f32_16x16x32_bf16 v[96:99], v[156:159], v[172:175], v[96:99]
	v_mfma_f32_16x16x32_bf16 v[88:91], v[148:151], v[180:183], v[88:91]
	v_mfma_f32_16x16x32_bf16 v[80:83], v[156:159], v[180:183], v[80:83]
	v_mfma_f32_16x16x32_bf16 v[72:75], v[148:151], v[188:191], v[72:75]
	v_mfma_f32_16x16x32_bf16 v[64:67], v[156:159], v[188:191], v[64:67]
	s_barrier
; #define PG8_STAGE(bufoff, gbase, voff) do { _Pragma("unroll") for (int _i = 0; _i < 2; ++_i) \
;         __builtin_amdgcn_global_load_lds((const unsigned*)((const char*)(gbase) + (voff)[_i]), (LAS unsigned*)(lds + (bufoff) + ldsw + _i * 8192), 16, 0, ((voff) == voffA ? AUXA : 0)); } while (0)
; #define PG8_LDA(dst, b, h) do { _Pragma("unroll") for (int m = 0; m < 4; ++m) _Pragma("unroll") for (int k = 0; k < 2; ++k) dst[m][k] = *(const LAS bf16x8*)(lds + PG8_SA(b, h) + aoff + m * 2048 + k * 1024); } while (0)
; #define PG8_LDB(dst, b, h) do { _Pragma("unroll") for (int n = 0; n < 2; ++n) _Pragma("unroll") for (int k = 0; k < 2; ++k) dst[n][k] = *(const LAS bf16x8*)(lds + PG8_SB(b, h) + boff + n * 2048 + k * 1024); } while (0)
; #define PG8_MMA(ai, bj, At, Bt) do { __builtin_amdgcn_s_setprio(1); _Pragma("unroll") for (int m = 0; m < 4; ++m) _Pragma("unroll") for (int n = 0; n < 2; ++n) _Pragma("unroll") for (int k = 0; k < 2; ++k) \
;         acc[ai][bj][m][n] = __builtin_amdgcn_mfma_f32_16x16x32_bf16(Bt[n][k], At[m][k], acc[ai][bj][m][n], 0, 0, 0); __builtin_amdgcn_s_setprio(0); } while (0)
; #define PG8_WAIT_V(n) asm volatile("s_waitcnt vmcnt(" #n ")" ::: "memory")
; #define PG8_WAIT_L(n) asm volatile("s_waitcnt lgkmcnt(" #n ")" ::: "memory")
; #define PG8_BAR __builtin_amdgcn_s_barrier()
; #define PG8_SCHED __builtin_amdgcn_sched_barrier(0)
;     ...
;             const bool last = (t == nt - 2);
;             const char* a1 = cA + (size_t)(t + 1) * kstep;
;             const char* a2 = last ? nA : cA + (size_t)(t + 2) * kstep; const char* b2 = last ? nB : cB + (size_t)(t + 2) * kstep;
;             const char* a3 = a2 + kstep; const char* b3 = b2 + kstep;
;             PG8_LDB(B0, 0, 0); PG8_LDB(B1, 0, 1); PG8_SCHED; PG8_LDA(At, 0, 0); PG8_STAGE(PG8_SA(1, 1), a1 + hsA, voffA);
;             if (Epi::NPRE != 0 && last) { E.pre(sv, cur, wr, fr); PG8_WAIT_V(16); } else { PG8_WAIT_V(8); }
;     ...
;             PG8_LDA(At, 1, 1); PG8_STAGE(PG8_SB(1, 0), b3, voffB); PG8_STAGE(PG8_SB(1, 1), b3 + hsB, voffB); PG8_STAGE(PG8_SA(1, 0), a3, voffA);
;             PG8_WAIT_V(8); PG8_WAIT_L(0); PG8_BAR; PG8_MMA(1, 0, At, B0); PG8_MMA(1, 1, At, B1); PG8_BAR; PG8_SCHED;
;         }
	s_setprio 0
	s_add_i32 s34, s36, s3
	s_mov_b32 m0, s34
	ds_read_b128 v[160:163], v226 offset:49152
	ds_read_b128 v[164:167], v226 offset:50176
	ds_read_b128 v[168:171], v226 offset:51200
	ds_read_b128 v[172:175], v226 offset:52224
	ds_read_b128 v[176:179], v226 offset:53248
	ds_read_b128 v[180:183], v226 offset:54272
	ds_read_b128 v[184:187], v226 offset:55296
	ds_read_b128 v[188:191], v226 offset:56320
	global_load_lds_dwordx4 v198, s[98:99]
	s_add_i32 m0, s34, 0x2000
	s_add_u32 s30, s30, 0x80080
	s_addc_u32 s31, s31, 0
	s_add_i32 s34, s37, s3
	global_load_lds_dwordx4 v194, s[98:99]
	s_mov_b32 m0, s34
	s_nop 0
	global_load_lds_dwordx4 v198, s[30:31]
	s_waitcnt vmcnt(5)
	s_waitcnt lgkmcnt(0)
	s_setprio 1
	s_barrier
	v_mfma_f32_16x16x32_bf16 v[60:63], v[128:131], v[160:163], v[60:63]
	v_mfma_f32_16x16x32_bf16 v[52:55], v[136:139], v[160:163], v[52:55]
	v_mfma_f32_16x16x32_bf16 v[44:47], v[128:131], v[168:171], v[44:47]
	v_mfma_f32_16x16x32_bf16 v[36:39], v[136:139], v[168:171], v[36:39]
	v_mfma_f32_16x16x32_bf16 v[28:31], v[128:131], v[176:179], v[28:31]
	v_mfma_f32_16x16x32_bf16 v[20:23], v[136:139], v[176:179], v[20:23]
	v_mfma_f32_16x16x32_bf16 v[12:15], v[128:131], v[184:187], v[12:15]
	v_mfma_f32_16x16x32_bf16 v[4:7], v[136:139], v[184:187], v[4:7]
	v_mfma_f32_16x16x32_bf16 v[60:63], v[132:135], v[164:167], v[60:63]
	v_mfma_f32_16x16x32_bf16 v[52:55], v[140:143], v[164:167], v[52:55]
	v_mfma_f32_16x16x32_bf16 v[44:47], v[132:135], v[172:175], v[44:47]
	v_mfma_f32_16x16x32_bf16 v[36:39], v[140:143], v[172:175], v[36:39]
	v_mfma_f32_16x16x32_bf16 v[28:31], v[132:135], v[180:183], v[28:31]
	v_mfma_f32_16x16x32_bf16 v[20:23], v[140:143], v[180:183], v[20:23]
	v_mfma_f32_16x16x32_bf16 v[12:15], v[132:135], v[188:191], v[12:15]
	v_mfma_f32_16x16x32_bf16 v[4:7], v[140:143], v[188:191], v[4:7]
	s_add_i32 m0, s34, 0x2000
	s_nop 0
	global_load_lds_dwordx4 v194, s[30:31]
	v_mfma_f32_16x16x32_bf16 v[56:59], v[144:147], v[160:163], v[56:59]
	v_mfma_f32_16x16x32_bf16 v[48:51], v[152:155], v[160:163], v[48:51]
	v_mfma_f32_16x16x32_bf16 v[40:43], v[144:147], v[168:171], v[40:43]
	v_mfma_f32_16x16x32_bf16 v[32:35], v[152:155], v[168:171], v[32:35]
	v_mfma_f32_16x16x32_bf16 v[24:27], v[144:147], v[176:179], v[24:27]
	v_mfma_f32_16x16x32_bf16 v[16:19], v[152:155], v[176:179], v[16:19]
	v_mfma_f32_16x16x32_bf16 v[8:11], v[144:147], v[184:187], v[8:11]
	v_mfma_f32_16x16x32_bf16 v[0:3], v[152:155], v[184:187], v[0:3]
	v_mfma_f32_16x16x32_bf16 v[56:59], v[148:151], v[164:167], v[56:59]
	v_mfma_f32_16x16x32_bf16 v[48:51], v[156:159], v[164:167], v[48:51]
	v_mfma_f32_16x16x32_bf16 v[40:43], v[148:151], v[172:175], v[40:43]
	v_mfma_f32_16x16x32_bf16 v[32:35], v[156:159], v[172:175], v[32:35]
	v_mfma_f32_16x16x32_bf16 v[24:27], v[148:151], v[180:183], v[24:27]
	v_mfma_f32_16x16x32_bf16 v[16:19], v[156:159], v[180:183], v[16:19]
	v_mfma_f32_16x16x32_bf16 v[8:11], v[148:151], v[188:191], v[8:11]
	v_mfma_f32_16x16x32_bf16 v[0:3], v[156:159], v[188:191], v[0:3]
	s_barrier
	s_setprio 0
	s_add_u32 s28, s28, 0x100
	s_addc_u32 s29, s29, 0
	s_add_u32 s59, s59, 0x100
	s_addc_u32 s60, s60, 0
	s_cmp_ge_i32 s61, s49
	s_cbranch_scc1 .LBB0_158
.LBB0_149:
	s_add_u32 s98, s28, 0xfff80000
	s_addc_u32 s99, s29, -1
	s_mov_b32 m0, s50
	s_nop 0
	global_load_lds_dwordx4 v200, s[98:99]
	s_mov_b32 m0, s51
	s_nop 0
	global_load_lds_dwordx4 v196, s[98:99]
	ds_read_b128 v[144:147], v224
	ds_read_b128 v[148:151], v224 offset:1024
	ds_read_b128 v[152:155], v224 offset:2048
	ds_read_b128 v[156:159], v224 offset:3072
	ds_read_b128 v[128:131], v225
	ds_read_b128 v[132:135], v225 offset:1024
	ds_read_b128 v[136:139], v225 offset:2048
	ds_read_b128 v[140:143], v225 offset:3072
	s_cmp_eq_u32 s52, s61
	s_cselect_b64 s[30:31], -1, 0
	s_cmp_lg_u32 s52, s61
	s_cselect_b64 s[36:37], -1, 0
	s_add_i32 m0, s40, 0xc000
	ds_read_b128 v[184:187], v226
	ds_read_b128 v[188:191], v226 offset:1024
	ds_read_b128 v[176:179], v226 offset:2048
	ds_read_b128 v[180:183], v226 offset:3072
	ds_read_b128 v[168:171], v226 offset:4096
	ds_read_b128 v[172:175], v226 offset:5120
	ds_read_b128 v[160:163], v226 offset:6144
	ds_read_b128 v[164:167], v226 offset:7168
	global_load_lds_dwordx4 v202, s[28:29]
	s_mov_b64 s[34:35], -1
	s_and_b64 vcc, exec, s[36:37]
	s_cbranch_vccz .LBB0_151
	s_waitcnt vmcnt(7)
	s_mov_b64 s[34:35], 0
; #define PG8_STAGE(bufoff, gbase, voff) do { _Pragma("unroll") for (int _i = 0; _i < 2; ++_i) \
;         __builtin_amdgcn_global_load_lds((const unsigned*)((const char*)(gbase) + (voff)[_i]), (LAS unsigned*)(lds + (bufoff) + ldsw + _i * 8192), 16, 0, ((voff) == voffA ? AUXA : 0)); } while (0)
; #define PG8_LDA(dst, b, h) do { _Pragma("unroll") for (int m = 0; m < 4; ++m) _Pragma("unroll") for (int k = 0; k < 2; ++k) dst[m][k] = *(const LAS bf16x8*)(lds + PG8_SA(b, h) + aoff + m * 2048 + k * 1024); } while (0)
; #define PG8_MMA(ai, bj, At, Bt) do { __builtin_amdgcn_s_setprio(1); _Pragma("unroll") for (int m = 0; m < 4; ++m) _Pragma("unroll") for (int n = 0; n < 2; ++n) _Pragma("unroll") for (int k = 0; k < 2; ++k) \
;         acc[ai][bj][m][n] = __builtin_amdgcn_mfma_f32_16x16x32_bf16(Bt[n][k], At[m][k], acc[ai][bj][m][n], 0, 0, 0); __builtin_amdgcn_s_setprio(0); } while (0)
; #define PG8_WAIT_V(n) asm volatile("s_waitcnt vmcnt(" #n ")" ::: "memory")
; #define PG8_WAIT_L(n) asm volatile("s_waitcnt lgkmcnt(" #n ")" ::: "memory")
; #define PG8_BAR __builtin_amdgcn_s_barrier()
; #define PG8_SCHED __builtin_amdgcn_sched_barrier(0)
;     ...
;             if (Epi::NPRE != 0 && last) { E.pre(sv, cur, wr, fr); PG8_WAIT_V(16); } else { PG8_WAIT_V(8); }
;             PG8_WAIT_L(0); PG8_BAR; PG8_MMA(0, 0, At, B0); PG8_MMA(0, 1, At, B1); PG8_BAR; PG8_SCHED;
;             PG8_LDA(At, 0, 1); PG8_STAGE(PG8_SB(0, 0), b2, voffB); PG8_STAGE(PG8_SB(0, 1), b2 + hsB, voffB); PG8_STAGE(PG8_SA(0, 0), a2, voffA);
;             if (Epi::NPRE != 0 && last) { PG8_WAIT_V(16); } else { PG8_WAIT_V(8); }
;     __device__ __forceinline__ void pre(float (&sv)[8], const Unit& u, int wr, int fr) const {
; #pragma unroll
;         for (int i = 0; i < 8; ++i) sv[i] = ss[u.pm * 256 + wr * 64 + fr + (i >> 2) * 128 + (i & 3) * 16]; }
.LBB0_151:
	s_andn2_b64 vcc, exec, s[34:35]
	s_cbranch_vccnz .LBB0_153
	global_load_dword v236, v[212:213], off
	global_load_dword v235, v[212:213], off offset:64
	global_load_dword v233, v[212:213], off offset:128
	global_load_dword v232, v[212:213], off offset:192
	global_load_dword v231, v[212:213], off offset:512
	global_load_dword v230, v[212:213], off offset:576
	global_load_dword v229, v[212:213], off offset:640
	global_load_dword v228, v[212:213], off offset:704
	s_waitcnt vmcnt(15)
.LBB0_153:
	s_add_u32 s34, s28, 0xfff80080
	s_addc_u32 s35, s29, -1
	s_waitcnt lgkmcnt(0)
	s_and_b64 s[30:31], s[30:31], exec
	s_cselect_b32 s35, s21, s35
	s_cselect_b32 s34, s23, s34
	s_cselect_b32 s31, s57, s60
	s_cselect_b32 s30, s58, s59
	s_setprio 1
	s_barrier
	v_mfma_f32_16x16x32_bf16 v[124:127], v[144:147], v[184:187], v[124:127]
	v_mfma_f32_16x16x32_bf16 v[116:119], v[152:155], v[184:187], v[116:119]
	v_mfma_f32_16x16x32_bf16 v[108:111], v[144:147], v[176:179], v[108:111]
	v_mfma_f32_16x16x32_bf16 v[100:103], v[152:155], v[176:179], v[100:103]
	v_mfma_f32_16x16x32_bf16 v[92:95], v[144:147], v[168:171], v[92:95]
	v_mfma_f32_16x16x32_bf16 v[84:87], v[152:155], v[168:171], v[84:87]
	v_mfma_f32_16x16x32_bf16 v[76:79], v[144:147], v[160:163], v[76:79]
	v_mfma_f32_16x16x32_bf16 v[68:71], v[152:155], v[160:163], v[68:71]
	v_mfma_f32_16x16x32_bf16 v[124:127], v[148:151], v[188:191], v[124:127]
	v_mfma_f32_16x16x32_bf16 v[116:119], v[156:159], v[188:191], v[116:119]
	v_mfma_f32_16x16x32_bf16 v[108:111], v[148:151], v[180:183], v[108:111]
	v_mfma_f32_16x16x32_bf16 v[100:103], v[156:159], v[180:183], v[100:103]
	v_mfma_f32_16x16x32_bf16 v[92:95], v[148:151], v[172:175], v[92:95]
	v_mfma_f32_16x16x32_bf16 v[84:87], v[156:159], v[172:175], v[84:87]
	v_mfma_f32_16x16x32_bf16 v[76:79], v[148:151], v[164:167], v[76:79]
	v_mfma_f32_16x16x32_bf16 v[68:71], v[156:159], v[164:167], v[68:71]
	s_add_i32 m0, s40, 0xe000
	s_nop 0
	global_load_lds_dwordx4 v204, s[28:29]
	v_mfma_f32_16x16x32_bf16 v[120:123], v[128:131], v[184:187], v[120:123]
	v_mfma_f32_16x16x32_bf16 v[112:115], v[136:139], v[184:187], v[112:115]
	v_mfma_f32_16x16x32_bf16 v[104:107], v[128:131], v[176:179], v[104:107]
	v_mfma_f32_16x16x32_bf16 v[96:99], v[136:139], v[176:179], v[96:99]
	v_mfma_f32_16x16x32_bf16 v[88:91], v[128:131], v[168:171], v[88:91]
	v_mfma_f32_16x16x32_bf16 v[80:83], v[136:139], v[168:171], v[80:83]
	v_mfma_f32_16x16x32_bf16 v[72:75], v[128:131], v[160:163], v[72:75]
	v_mfma_f32_16x16x32_bf16 v[64:67], v[136:139], v[160:163], v[64:67]
	v_mfma_f32_16x16x32_bf16 v[120:123], v[132:135], v[188:191], v[120:123]
	v_mfma_f32_16x16x32_bf16 v[112:115], v[140:143], v[188:191], v[112:115]
	v_mfma_f32_16x16x32_bf16 v[104:107], v[132:135], v[180:183], v[104:107]
	v_mfma_f32_16x16x32_bf16 v[96:99], v[140:143], v[180:183], v[96:99]
	v_mfma_f32_16x16x32_bf16 v[88:91], v[132:135], v[172:175], v[88:91]
	v_mfma_f32_16x16x32_bf16 v[80:83], v[140:143], v[172:175], v[80:83]
	v_mfma_f32_16x16x32_bf16 v[72:75], v[132:135], v[164:167], v[72:75]
	v_mfma_f32_16x16x32_bf16 v[64:67], v[140:143], v[164:167], v[64:67]
	s_barrier
	s_setprio 0
	s_add_u32 s98, s30, s16
	s_addc_u32 s99, s31, s17
	s_add_u32 s100, s34, s16
	s_addc_u32 s101, s35, s17
	s_mov_b32 m0, s41
	s_add_u32 s38, s30, 0x80000
	ds_read_b128 v[184:187], v226 offset:16384
	ds_read_b128 v[188:191], v226 offset:17408
	ds_read_b128 v[176:179], v226 offset:18432
	ds_read_b128 v[180:183], v226 offset:19456
	ds_read_b128 v[168:171], v226 offset:20480
	ds_read_b128 v[172:175], v226 offset:21504
	ds_read_b128 v[160:163], v226 offset:22528
	ds_read_b128 v[164:167], v226 offset:23552
	global_load_lds_dwordx4 v198, s[30:31]
	s_mov_b32 m0, s42
	s_addc_u32 s39, s31, 0
	global_load_lds_dwordx4 v194, s[30:31]
	s_mov_b32 m0, s43
	s_nop 0
	global_load_lds_dwordx4 v198, s[38:39]
	s_mov_b64 s[100:101], s[38:39]
	s_mov_b64 s[38:39], -1
	s_and_b64 vcc, exec, s[36:37]
	s_cbranch_vccz .LBB0_155
	s_waitcnt vmcnt(5)
	s_mov_b64 s[38:39], 0
.LBB0_155:
	s_andn2_b64 vcc, exec, s[38:39]
	s_cbranch_vccnz .LBB0_148
	s_waitcnt vmcnt(13)
	s_branch .LBB0_148

; #define PG8_STAGE(bufoff, gbase, voff) do { _Pragma("unroll") for (int _i = 0; _i < 2; ++_i) \
;         __builtin_amdgcn_global_load_lds((const unsigned*)((const char*)(gbase) + (voff)[_i]), (LAS unsigned*)(lds + (bufoff) + ldsw + _i * 8192), 16, 0, ((voff) == voffA ? AUXA : 0)); } while (0)
; #define PG8_LDA(dst, b, h) do { _Pragma("unroll") for (int m = 0; m < 4; ++m) _Pragma("unroll") for (int k = 0; k < 2; ++k) dst[m][k] = *(const LAS bf16x8*)(lds + PG8_SA(b, h) + aoff + m * 2048 + k * 1024); } while (0)
; #define PG8_LDB(dst, b, h) do { _Pragma("unroll") for (int n = 0; n < 2; ++n) _Pragma("unroll") for (int k = 0; k < 2; ++k) dst[n][k] = *(const LAS bf16x8*)(lds + PG8_SB(b, h) + boff + n * 2048 + k * 1024); } while (0)
; #define PG8_MMA(ai, bj, At, Bt) do { __builtin_amdgcn_s_setprio(1); _Pragma("unroll") for (int m = 0; m < 4; ++m) _Pragma("unroll") for (int n = 0; n < 2; ++n) _Pragma("unroll") for (int k = 0; k < 2; ++k) \
;         acc[ai][bj][m][n] = __builtin_amdgcn_mfma_f32_16x16x32_bf16(Bt[n][k], At[m][k], acc[ai][bj][m][n], 0, 0, 0); __builtin_amdgcn_s_setprio(0); } while (0)
; #define PG8_WAIT_V(n) asm volatile("s_waitcnt vmcnt(" #n ")" ::: "memory")
; #define PG8_WAIT_L(n) asm volatile("s_waitcnt lgkmcnt(" #n ")" ::: "memory")
; #define PG8_BAR __builtin_amdgcn_s_barrier()
; #define PG8_SCHED __builtin_amdgcn_sched_barrier(0)
;     ...
;             const bool last = (t == nt - 2);
;             const char* a1 = cA + (size_t)(t + 1) * kstep;
;             const char* a2 = last ? nA : cA + (size_t)(t + 2) * kstep; const char* b2 = last ? nB : cB + (size_t)(t + 2) * kstep;
;             const char* a3 = a2 + kstep; const char* b3 = b2 + kstep;
;             PG8_LDB(B0, 0, 0); PG8_LDB(B1, 0, 1); PG8_SCHED; PG8_LDA(At, 0, 0); PG8_STAGE(PG8_SA(1, 1), a1 + hsA, voffA);
;             if (Epi::NPRE != 0 && last) { E.pre(sv, cur, wr, fr); PG8_WAIT_V(16); } else { PG8_WAIT_V(8); }
;             PG8_WAIT_L(0); PG8_BAR; PG8_MMA(0, 0, At, B0); PG8_MMA(0, 1, At, B1); PG8_BAR; PG8_SCHED;
;             PG8_LDA(At, 0, 1); PG8_STAGE(PG8_SB(0, 0), b2, voffB); PG8_STAGE(PG8_SB(0, 1), b2 + hsB, voffB); PG8_STAGE(PG8_SA(0, 0), a2, voffA);
;             if (Epi::NPRE != 0 && last) { PG8_WAIT_V(16); } else { PG8_WAIT_V(8); }
;             PG8_WAIT_L(0); PG8_BAR; PG8_MMA(1, 0, At, B0); PG8_MMA(1, 1, At, B1); PG8_BAR; PG8_SCHED;
.LBB0_246:
	s_add_u32 s98, s24, 0xffea0000
	s_addc_u32 s99, s25, -1
	s_mov_b32 m0, s39
	s_nop 0
	global_load_lds_dwordx4 v128, s[98:99]
	s_mov_b32 m0, s40
	s_nop 0
	global_load_lds_dwordx4 v132, s[98:99]
	ds_read_b128 v[144:147], v208
	ds_read_b128 v[148:151], v208 offset:1024
	ds_read_b128 v[152:155], v208 offset:2048
	ds_read_b128 v[156:159], v208 offset:3072
	ds_read_b128 v[160:163], v209
	ds_read_b128 v[164:167], v209 offset:1024
	ds_read_b128 v[168:171], v209 offset:2048
	ds_read_b128 v[172:175], v209 offset:3072
	s_add_i32 s52, s26, 2
	s_add_u32 s27, s24, 0xffea0080
	s_addc_u32 s28, s25, -1
	s_cmp_eq_u32 s41, s26
	s_cselect_b32 s26, s22, s50
	s_cselect_b32 s29, s11, s28
	s_cselect_b32 s28, s10, s27
	s_cselect_b32 s27, s23, s51
	s_add_i32 m0, s30, 0xc000
	ds_read_b128 v[176:179], v210
	ds_read_b128 v[180:183], v210 offset:1024
	ds_read_b128 v[184:187], v210 offset:2048
	ds_read_b128 v[188:191], v210 offset:3072
	ds_read_b128 v[194:197], v210 offset:4096
	ds_read_b128 v[198:201], v210 offset:5120
	ds_read_b128 v[202:205], v210 offset:6144
	ds_read_b128 v[212:215], v210 offset:7168
	global_load_lds_dwordx4 v136, s[24:25]
	s_waitcnt vmcnt(7)
	s_waitcnt lgkmcnt(0)
	s_setprio 1
	s_barrier
	v_mfma_f32_16x16x32_bf16 v[124:127], v[144:147], v[176:179], v[124:127]
	v_mfma_f32_16x16x32_bf16 v[120:123], v[152:155], v[176:179], v[120:123]
	v_mfma_f32_16x16x32_bf16 v[116:119], v[144:147], v[184:187], v[116:119]
	v_mfma_f32_16x16x32_bf16 v[112:115], v[152:155], v[184:187], v[112:115]
	v_mfma_f32_16x16x32_bf16 v[104:107], v[144:147], v[194:197], v[104:107]
	v_mfma_f32_16x16x32_bf16 v[96:99], v[152:155], v[194:197], v[96:99]
	v_mfma_f32_16x16x32_bf16 v[88:91], v[144:147], v[202:205], v[88:91]
	v_mfma_f32_16x16x32_bf16 v[80:83], v[152:155], v[202:205], v[80:83]
	v_mfma_f32_16x16x32_bf16 v[124:127], v[148:151], v[180:183], v[124:127]
	v_mfma_f32_16x16x32_bf16 v[120:123], v[156:159], v[180:183], v[120:123]
	v_mfma_f32_16x16x32_bf16 v[116:119], v[148:151], v[188:191], v[116:119]
	v_mfma_f32_16x16x32_bf16 v[112:115], v[156:159], v[188:191], v[112:115]
	v_mfma_f32_16x16x32_bf16 v[104:107], v[148:151], v[198:201], v[104:107]
	v_mfma_f32_16x16x32_bf16 v[96:99], v[156:159], v[198:201], v[96:99]
	v_mfma_f32_16x16x32_bf16 v[88:91], v[148:151], v[212:215], v[88:91]
	v_mfma_f32_16x16x32_bf16 v[80:83], v[156:159], v[212:215], v[80:83]
	s_add_i32 m0, s30, 0xe000
	s_nop 0
	global_load_lds_dwordx4 v138, s[24:25]
	v_mfma_f32_16x16x32_bf16 v[108:111], v[160:163], v[176:179], v[108:111]
	v_mfma_f32_16x16x32_bf16 v[100:103], v[168:171], v[176:179], v[100:103]
	v_mfma_f32_16x16x32_bf16 v[92:95], v[160:163], v[184:187], v[92:95]
	v_mfma_f32_16x16x32_bf16 v[84:87], v[168:171], v[184:187], v[84:87]
	v_mfma_f32_16x16x32_bf16 v[76:79], v[160:163], v[194:197], v[76:79]
	v_mfma_f32_16x16x32_bf16 v[72:75], v[168:171], v[194:197], v[72:75]
	v_mfma_f32_16x16x32_bf16 v[68:71], v[160:163], v[202:205], v[68:71]
	v_mfma_f32_16x16x32_bf16 v[64:67], v[168:171], v[202:205], v[64:67]
	v_mfma_f32_16x16x32_bf16 v[108:111], v[164:167], v[180:183], v[108:111]
	v_mfma_f32_16x16x32_bf16 v[100:103], v[172:175], v[180:183], v[100:103]
	v_mfma_f32_16x16x32_bf16 v[92:95], v[164:167], v[188:191], v[92:95]
	v_mfma_f32_16x16x32_bf16 v[84:87], v[172:175], v[188:191], v[84:87]
	v_mfma_f32_16x16x32_bf16 v[76:79], v[164:167], v[198:201], v[76:79]
	v_mfma_f32_16x16x32_bf16 v[72:75], v[172:175], v[198:201], v[72:75]
	v_mfma_f32_16x16x32_bf16 v[68:71], v[164:167], v[212:215], v[68:71]
	v_mfma_f32_16x16x32_bf16 v[64:67], v[172:175], v[212:215], v[64:67]
	s_barrier
	s_setprio 0
	s_add_u32 s98, s26, s16
	s_addc_u32 s99, s27, s17
	s_add_u32 s100, s28, s16
	s_addc_u32 s101, s29, s17
	s_add_i32 s53, s44, s5
	s_mov_b32 m0, s53
	ds_read_b128 v[176:179], v210 offset:16384
	ds_read_b128 v[180:183], v210 offset:17408
	ds_read_b128 v[184:187], v210 offset:18432
	ds_read_b128 v[188:191], v210 offset:19456
	ds_read_b128 v[194:197], v210 offset:20480
	ds_read_b128 v[198:201], v210 offset:21504
	ds_read_b128 v[202:205], v210 offset:22528
	ds_read_b128 v[212:215], v210 offset:23552
	global_load_lds_dwordx4 v130, s[26:27]
	s_add_i32 m0, s53, 0x2000
	s_add_u32 s54, s26, 0x160000
	s_addc_u32 s55, s27, 0
	s_add_i32 s53, s45, s5
	global_load_lds_dwordx4 v134, s[26:27]
	s_mov_b32 m0, s53
	s_nop 0
	global_load_lds_dwordx4 v130, s[54:55]
	s_waitcnt vmcnt(5)
	s_waitcnt lgkmcnt(0)
	s_setprio 1
	s_barrier
	v_mfma_f32_16x16x32_bf16 v[60:63], v[144:147], v[176:179], v[60:63]
	v_mfma_f32_16x16x32_bf16 v[56:59], v[152:155], v[176:179], v[56:59]
	v_mfma_f32_16x16x32_bf16 v[52:55], v[144:147], v[184:187], v[52:55]
	v_mfma_f32_16x16x32_bf16 v[48:51], v[152:155], v[184:187], v[48:51]
	v_mfma_f32_16x16x32_bf16 v[40:43], v[144:147], v[194:197], v[40:43]
	v_mfma_f32_16x16x32_bf16 v[32:35], v[152:155], v[194:197], v[32:35]
	v_mfma_f32_16x16x32_bf16 v[24:27], v[144:147], v[202:205], v[24:27]
	v_mfma_f32_16x16x32_bf16 v[16:19], v[152:155], v[202:205], v[16:19]
	v_mfma_f32_16x16x32_bf16 v[60:63], v[148:151], v[180:183], v[60:63]
	v_mfma_f32_16x16x32_bf16 v[56:59], v[156:159], v[180:183], v[56:59]
	v_mfma_f32_16x16x32_bf16 v[52:55], v[148:151], v[188:191], v[52:55]
	v_mfma_f32_16x16x32_bf16 v[48:51], v[156:159], v[188:191], v[48:51]
	v_mfma_f32_16x16x32_bf16 v[40:43], v[148:151], v[198:201], v[40:43]
	v_mfma_f32_16x16x32_bf16 v[32:35], v[156:159], v[198:201], v[32:35]
	v_mfma_f32_16x16x32_bf16 v[24:27], v[148:151], v[212:215], v[24:27]
	v_mfma_f32_16x16x32_bf16 v[16:19], v[156:159], v[212:215], v[16:19]
	s_add_i32 m0, s53, 0x2000
	s_nop 0
	global_load_lds_dwordx4 v134, s[54:55]
	v_mfma_f32_16x16x32_bf16 v[44:47], v[160:163], v[176:179], v[44:47]
	v_mfma_f32_16x16x32_bf16 v[36:39], v[168:171], v[176:179], v[36:39]
	v_mfma_f32_16x16x32_bf16 v[28:31], v[160:163], v[184:187], v[28:31]
	v_mfma_f32_16x16x32_bf16 v[20:23], v[168:171], v[184:187], v[20:23]
	v_mfma_f32_16x16x32_bf16 v[12:15], v[160:163], v[194:197], v[12:15]
	v_mfma_f32_16x16x32_bf16 v[8:11], v[168:171], v[194:197], v[8:11]
	v_mfma_f32_16x16x32_bf16 v[4:7], v[160:163], v[202:205], v[4:7]
	v_mfma_f32_16x16x32_bf16 v[0:3], v[168:171], v[202:205], v[0:3]
	v_mfma_f32_16x16x32_bf16 v[44:47], v[164:167], v[180:183], v[44:47]
	v_mfma_f32_16x16x32_bf16 v[36:39], v[172:175], v[180:183], v[36:39]
	v_mfma_f32_16x16x32_bf16 v[28:31], v[164:167], v[188:191], v[28:31]
	v_mfma_f32_16x16x32_bf16 v[20:23], v[172:175], v[188:191], v[20:23]
	v_mfma_f32_16x16x32_bf16 v[12:15], v[164:167], v[198:201], v[12:15]
	v_mfma_f32_16x16x32_bf16 v[8:11], v[172:175], v[198:201], v[8:11]
	v_mfma_f32_16x16x32_bf16 v[4:7], v[164:167], v[212:215], v[4:7]
	v_mfma_f32_16x16x32_bf16 v[0:3], v[172:175], v[212:215], v[0:3]
	s_barrier
; #define PG8_STAGE(bufoff, gbase, voff) do { _Pragma("unroll") for (int _i = 0; _i < 2; ++_i) \
;         __builtin_amdgcn_global_load_lds((const unsigned*)((const char*)(gbase) + (voff)[_i]), (LAS unsigned*)(lds + (bufoff) + ldsw + _i * 8192), 16, 0, ((voff) == voffA ? AUXA : 0)); } while (0)
; #define PG8_LDA(dst, b, h) do { _Pragma("unroll") for (int m = 0; m < 4; ++m) _Pragma("unroll") for (int k = 0; k < 2; ++k) dst[m][k] = *(const LAS bf16x8*)(lds + PG8_SA(b, h) + aoff + m * 2048 + k * 1024); } while (0)
; #define PG8_LDB(dst, b, h) do { _Pragma("unroll") for (int n = 0; n < 2; ++n) _Pragma("unroll") for (int k = 0; k < 2; ++k) dst[n][k] = *(const LAS bf16x8*)(lds + PG8_SB(b, h) + boff + n * 2048 + k * 1024); } while (0)
; #define PG8_MMA(ai, bj, At, Bt) do { __builtin_amdgcn_s_setprio(1); _Pragma("unroll") for (int m = 0; m < 4; ++m) _Pragma("unroll") for (int n = 0; n < 2; ++n) _Pragma("unroll") for (int k = 0; k < 2; ++k) \
;         acc[ai][bj][m][n] = __builtin_amdgcn_mfma_f32_16x16x32_bf16(Bt[n][k], At[m][k], acc[ai][bj][m][n], 0, 0, 0); __builtin_amdgcn_s_setprio(0); } while (0)
; #define PG8_WAIT_V(n) asm volatile("s_waitcnt vmcnt(" #n ")" ::: "memory")
; #define PG8_WAIT_L(n) asm volatile("s_waitcnt lgkmcnt(" #n ")" ::: "memory")
; #define PG8_BAR __builtin_amdgcn_s_barrier()
; #define PG8_SCHED __builtin_amdgcn_sched_barrier(0)
;     ...
;             PG8_LDB(B0, 1, 0); PG8_LDB(B1, 1, 1); PG8_SCHED; PG8_LDA(At, 1, 0); PG8_STAGE(PG8_SA(0, 1), a2 + hsA, voffA);
;             PG8_WAIT_V(8); PG8_WAIT_L(0); PG8_BAR; PG8_MMA(0, 0, At, B0); PG8_MMA(0, 1, At, B1); PG8_BAR; PG8_SCHED;
;             PG8_LDA(At, 1, 1); PG8_STAGE(PG8_SB(1, 0), b3, voffB); PG8_STAGE(PG8_SB(1, 1), b3 + hsB, voffB); PG8_STAGE(PG8_SA(1, 0), a3, voffA);
	s_mov_b32 m0, s30
	s_nop 0
	global_load_lds_dwordx4 v128, s[28:29]
	s_mov_b32 m0, s31
	s_nop 0
	global_load_lds_dwordx4 v132, s[28:29]
	s_setprio 0
	s_add_i32 s53, 0, 0x18000
	s_add_i32 s54, 0, 0x1c000
	v_add_u32_e32 v156, s53, v206
	v_add_u32_e32 v172, s54, v206
	ds_read_b128 v[144:147], v156
	ds_read_b128 v[148:151], v156 offset:1024
	ds_read_b128 v[152:155], v156 offset:2048
	ds_read_b128 v[156:159], v156 offset:3072
	ds_read_b128 v[160:163], v172
	ds_read_b128 v[164:167], v172 offset:1024
	ds_read_b128 v[168:171], v172 offset:2048
	ds_read_b128 v[172:175], v172 offset:3072
	s_add_u32 s28, s28, 0x160000
	s_addc_u32 s29, s29, 0
	s_mov_b32 m0, s34
	ds_read_b128 v[176:179], v210 offset:32768
	ds_read_b128 v[180:183], v210 offset:33792
	ds_read_b128 v[184:187], v210 offset:34816
	ds_read_b128 v[188:191], v210 offset:35840
	ds_read_b128 v[194:197], v210 offset:36864
	ds_read_b128 v[198:201], v210 offset:37888
	ds_read_b128 v[202:205], v210 offset:38912
	ds_read_b128 v[212:215], v210 offset:39936
	global_load_lds_dwordx4 v128, s[28:29]
	s_waitcnt vmcnt(7)
	s_waitcnt lgkmcnt(0)
	s_setprio 1
	s_barrier
	v_mfma_f32_16x16x32_bf16 v[124:127], v[144:147], v[176:179], v[124:127]
	v_mfma_f32_16x16x32_bf16 v[120:123], v[152:155], v[176:179], v[120:123]
	v_mfma_f32_16x16x32_bf16 v[116:119], v[144:147], v[184:187], v[116:119]
	v_mfma_f32_16x16x32_bf16 v[112:115], v[152:155], v[184:187], v[112:115]
	v_mfma_f32_16x16x32_bf16 v[104:107], v[144:147], v[194:197], v[104:107]
	v_mfma_f32_16x16x32_bf16 v[96:99], v[152:155], v[194:197], v[96:99]
	v_mfma_f32_16x16x32_bf16 v[88:91], v[144:147], v[202:205], v[88:91]
	v_mfma_f32_16x16x32_bf16 v[80:83], v[152:155], v[202:205], v[80:83]
	v_mfma_f32_16x16x32_bf16 v[124:127], v[148:151], v[180:183], v[124:127]
	v_mfma_f32_16x16x32_bf16 v[120:123], v[156:159], v[180:183], v[120:123]
	v_mfma_f32_16x16x32_bf16 v[116:119], v[148:151], v[188:191], v[116:119]
	v_mfma_f32_16x16x32_bf16 v[112:115], v[156:159], v[188:191], v[112:115]
	v_mfma_f32_16x16x32_bf16 v[104:107], v[148:151], v[198:201], v[104:107]
	v_mfma_f32_16x16x32_bf16 v[96:99], v[156:159], v[198:201], v[96:99]
	v_mfma_f32_16x16x32_bf16 v[88:91], v[148:151], v[212:215], v[88:91]
	v_mfma_f32_16x16x32_bf16 v[80:83], v[156:159], v[212:215], v[80:83]
	s_mov_b32 m0, s35
	s_nop 0
	global_load_lds_dwordx4 v132, s[28:29]
	v_mfma_f32_16x16x32_bf16 v[108:111], v[160:163], v[176:179], v[108:111]
	v_mfma_f32_16x16x32_bf16 v[100:103], v[168:171], v[176:179], v[100:103]
	v_mfma_f32_16x16x32_bf16 v[92:95], v[160:163], v[184:187], v[92:95]
	v_mfma_f32_16x16x32_bf16 v[84:87], v[168:171], v[184:187], v[84:87]
	v_mfma_f32_16x16x32_bf16 v[76:79], v[160:163], v[194:197], v[76:79]
	v_mfma_f32_16x16x32_bf16 v[72:75], v[168:171], v[194:197], v[72:75]
	v_mfma_f32_16x16x32_bf16 v[68:71], v[160:163], v[202:205], v[68:71]
	v_mfma_f32_16x16x32_bf16 v[64:67], v[168:171], v[202:205], v[64:67]
	v_mfma_f32_16x16x32_bf16 v[108:111], v[164:167], v[180:183], v[108:111]
	v_mfma_f32_16x16x32_bf16 v[100:103], v[172:175], v[180:183], v[100:103]
	v_mfma_f32_16x16x32_bf16 v[92:95], v[164:167], v[188:191], v[92:95]
	v_mfma_f32_16x16x32_bf16 v[84:87], v[172:175], v[188:191], v[84:87]
	v_mfma_f32_16x16x32_bf16 v[76:79], v[164:167], v[198:201], v[76:79]
	v_mfma_f32_16x16x32_bf16 v[72:75], v[172:175], v[198:201], v[72:75]
	v_mfma_f32_16x16x32_bf16 v[68:71], v[164:167], v[212:215], v[68:71]
	v_mfma_f32_16x16x32_bf16 v[64:67], v[172:175], v[212:215], v[64:67]
	s_barrier
	s_setprio 0
	s_add_i32 s28, s53, s5
	s_mov_b32 m0, s28
	ds_read_b128 v[176:179], v210 offset:49152
	ds_read_b128 v[180:183], v210 offset:50176
	ds_read_b128 v[184:187], v210 offset:51200
	ds_read_b128 v[188:191], v210 offset:52224
	ds_read_b128 v[194:197], v210 offset:53248
	ds_read_b128 v[198:201], v210 offset:54272
	ds_read_b128 v[202:205], v210 offset:55296
	ds_read_b128 v[212:215], v210 offset:56320
	global_load_lds_dwordx4 v130, s[98:99]
	s_add_i32 m0, s28, 0x2000
	s_add_u32 s26, s26, 0x160080
	s_addc_u32 s27, s27, 0
	s_add_i32 s28, s54, s5
	global_load_lds_dwordx4 v134, s[98:99]
	s_mov_b32 m0, s28
	s_nop 0
	global_load_lds_dwordx4 v130, s[26:27]
	s_waitcnt vmcnt(5)
	s_waitcnt lgkmcnt(0)
	s_setprio 1
	s_barrier
; #define PG8_MMA(ai, bj, At, Bt) do { __builtin_amdgcn_s_setprio(1); _Pragma("unroll") for (int m = 0; m < 4; ++m) _Pragma("unroll") for (int n = 0; n < 2; ++n) _Pragma("unroll") for (int k = 0; k < 2; ++k) \
;         acc[ai][bj][m][n] = __builtin_amdgcn_mfma_f32_16x16x32_bf16(Bt[n][k], At[m][k], acc[ai][bj][m][n], 0, 0, 0); __builtin_amdgcn_s_setprio(0); } while (0)
; #define PG8_WAIT_V(n) asm volatile("s_waitcnt vmcnt(" #n ")" ::: "memory")
; #define PG8_WAIT_L(n) asm volatile("s_waitcnt lgkmcnt(" #n ")" ::: "memory")
; #define PG8_BAR __builtin_amdgcn_s_barrier()
; #define PG8_SCHED __builtin_amdgcn_sched_barrier(0)
;     ...
;             PG8_WAIT_V(8); PG8_WAIT_L(0); PG8_BAR; PG8_MMA(1, 0, At, B0); PG8_MMA(1, 1, At, B1); PG8_BAR; PG8_SCHED;
;         }
;     __device__ __forceinline__ void operator()(const Acc& acc, const Unit& u, int wr, int wc, int fr, int fq, const float (&sv8)[8]) const {
;     ...
;                 for (int bj = 0; bj < 2; ++bj) {
;                     const int col = colb + bj * 128;
;                     const f32x4 y0 = xr[m][bj][0] + acc[ai][bj][m][0] * scale, y1 = xr[m][bj][1] + acc[ai][bj][m][1] * scale;
	v_mfma_f32_16x16x32_bf16 v[60:63], v[144:147], v[176:179], v[60:63]
	v_mfma_f32_16x16x32_bf16 v[56:59], v[152:155], v[176:179], v[56:59]
	v_mfma_f32_16x16x32_bf16 v[52:55], v[144:147], v[184:187], v[52:55]
	v_mfma_f32_16x16x32_bf16 v[48:51], v[152:155], v[184:187], v[48:51]
	v_mfma_f32_16x16x32_bf16 v[40:43], v[144:147], v[194:197], v[40:43]
	v_mfma_f32_16x16x32_bf16 v[32:35], v[152:155], v[194:197], v[32:35]
	v_mfma_f32_16x16x32_bf16 v[24:27], v[144:147], v[202:205], v[24:27]
	v_mfma_f32_16x16x32_bf16 v[16:19], v[152:155], v[202:205], v[16:19]
	v_mfma_f32_16x16x32_bf16 v[60:63], v[148:151], v[180:183], v[60:63]
	v_mfma_f32_16x16x32_bf16 v[56:59], v[156:159], v[180:183], v[56:59]
	v_mfma_f32_16x16x32_bf16 v[52:55], v[148:151], v[188:191], v[52:55]
	v_mfma_f32_16x16x32_bf16 v[48:51], v[156:159], v[188:191], v[48:51]
	v_mfma_f32_16x16x32_bf16 v[40:43], v[148:151], v[198:201], v[40:43]
	v_mfma_f32_16x16x32_bf16 v[32:35], v[156:159], v[198:201], v[32:35]
	v_mfma_f32_16x16x32_bf16 v[24:27], v[148:151], v[212:215], v[24:27]
	v_mfma_f32_16x16x32_bf16 v[16:19], v[156:159], v[212:215], v[16:19]
	s_add_i32 m0, s28, 0x2000
	s_nop 0
	global_load_lds_dwordx4 v134, s[26:27]
	v_mfma_f32_16x16x32_bf16 v[44:47], v[160:163], v[176:179], v[44:47]
	v_mfma_f32_16x16x32_bf16 v[36:39], v[168:171], v[176:179], v[36:39]
	v_mfma_f32_16x16x32_bf16 v[28:31], v[160:163], v[184:187], v[28:31]
	v_mfma_f32_16x16x32_bf16 v[20:23], v[168:171], v[184:187], v[20:23]
	v_mfma_f32_16x16x32_bf16 v[12:15], v[160:163], v[194:197], v[12:15]
	v_mfma_f32_16x16x32_bf16 v[8:11], v[168:171], v[194:197], v[8:11]
	v_mfma_f32_16x16x32_bf16 v[4:7], v[160:163], v[202:205], v[4:7]
	v_mfma_f32_16x16x32_bf16 v[0:3], v[168:171], v[202:205], v[0:3]
	v_mfma_f32_16x16x32_bf16 v[44:47], v[164:167], v[180:183], v[44:47]
	v_mfma_f32_16x16x32_bf16 v[36:39], v[172:175], v[180:183], v[36:39]
	v_mfma_f32_16x16x32_bf16 v[28:31], v[164:167], v[188:191], v[28:31]
	v_mfma_f32_16x16x32_bf16 v[20:23], v[172:175], v[188:191], v[20:23]
	v_mfma_f32_16x16x32_bf16 v[12:15], v[164:167], v[198:201], v[12:15]
	v_mfma_f32_16x16x32_bf16 v[8:11], v[172:175], v[198:201], v[8:11]
	v_mfma_f32_16x16x32_bf16 v[4:7], v[164:167], v[212:215], v[4:7]
	v_mfma_f32_16x16x32_bf16 v[0:3], v[172:175], v[212:215], v[0:3]
	s_barrier
	s_setprio 0
	s_add_u32 s24, s24, 0x100
	s_addc_u32 s25, s25, 0
	s_add_u32 s50, s50, 0x100
	s_addc_u32 s51, s51, 0
	s_cmp_ge_i32 s52, s38
	s_mov_b32 s26, s52
	s_cbranch_scc0 .LBB0_246
	v_pk_mul_f32 v[178:179], v[126:127], 0.5 op_sel_hi:[1,0]
	v_pk_mul_f32 v[184:185], v[124:125], 0.5 op_sel_hi:[1,0]
	v_pk_mul_f32 v[182:183], v[122:123], 0.5 op_sel_hi:[1,0]
	v_pk_mul_f32 v[180:181], v[120:121], 0.5 op_sel_hi:[1,0]
	v_pk_mul_f32 v[194:195], v[110:111], 0.5 op_sel_hi:[1,0]
	v_pk_mul_f32 v[190:191], v[108:109], 0.5 op_sel_hi:[1,0]
	v_pk_mul_f32 v[188:189], v[102:103], 0.5 op_sel_hi:[1,0]
	v_pk_mul_f32 v[186:187], v[100:101], 0.5 op_sel_hi:[1,0]
	v_pk_mul_f32 v[168:169], v[118:119], 0.5 op_sel_hi:[1,0]
	v_pk_mul_f32 v[166:167], v[116:117], 0.5 op_sel_hi:[1,0]
	v_pk_mul_f32 v[164:165], v[114:115], 0.5 op_sel_hi:[1,0]
	v_pk_mul_f32 v[162:163], v[112:113], 0.5 op_sel_hi:[1,0]
	v_pk_mul_f32 v[176:177], v[94:95], 0.5 op_sel_hi:[1,0]
	v_pk_mul_f32 v[174:175], v[92:93], 0.5 op_sel_hi:[1,0]
	v_pk_mul_f32 v[172:173], v[86:87], 0.5 op_sel_hi:[1,0]
	v_pk_mul_f32 v[170:171], v[84:85], 0.5 op_sel_hi:[1,0]
	v_pk_mul_f32 v[152:153], v[106:107], 0.5 op_sel_hi:[1,0]
	v_pk_mul_f32 v[150:151], v[104:105], 0.5 op_sel_hi:[1,0]
	v_pk_mul_f32 v[148:149], v[98:99], 0.5 op_sel_hi:[1,0]
	v_pk_mul_f32 v[146:147], v[96:97], 0.5 op_sel_hi:[1,0]
	v_pk_mul_f32 v[160:161], v[78:79], 0.5 op_sel_hi:[1,0]
	v_pk_mul_f32 v[158:159], v[76:77], 0.5 op_sel_hi:[1,0]
	v_pk_mul_f32 v[156:157], v[74:75], 0.5 op_sel_hi:[1,0]
	v_pk_mul_f32 v[154:155], v[72:73], 0.5 op_sel_hi:[1,0]
	v_pk_mul_f32 v[120:121], v[90:91], 0.5 op_sel_hi:[1,0]
	v_pk_mul_f32 v[118:119], v[88:89], 0.5 op_sel_hi:[1,0]
	v_pk_mul_f32 v[116:117], v[82:83], 0.5 op_sel_hi:[1,0]
	v_pk_mul_f32 v[114:115], v[80:81], 0.5 op_sel_hi:[1,0]
	v_pk_mul_f32 v[144:145], v[70:71], 0.5 op_sel_hi:[1,0]
	v_pk_mul_f32 v[126:127], v[68:69], 0.5 op_sel_hi:[1,0]
	v_pk_mul_f32 v[124:125], v[66:67], 0.5 op_sel_hi:[1,0]
	v_pk_mul_f32 v[122:123], v[64:65], 0.5 op_sel_hi:[1,0]
	v_pk_mul_f32 v[102:103], v[62:63], 0.5 op_sel_hi:[1,0]
	v_pk_mul_f32 v[100:101], v[60:61], 0.5 op_sel_hi:[1,0]
	v_pk_mul_f32 v[98:99], v[58:59], 0.5 op_sel_hi:[1,0]
	v_pk_mul_f32 v[96:97], v[56:57], 0.5 op_sel_hi:[1,0]
	v_pk_mul_f32 v[110:111], v[46:47], 0.5 op_sel_hi:[1,0]
	v_pk_mul_f32 v[108:109], v[44:45], 0.5 op_sel_hi:[1,0]
	v_pk_mul_f32 v[106:107], v[38:39], 0.5 op_sel_hi:[1,0]
	v_pk_mul_f32 v[104:105], v[36:37], 0.5 op_sel_hi:[1,0]
	v_pk_mul_f32 v[86:87], v[54:55], 0.5 op_sel_hi:[1,0]
	v_pk_mul_f32 v[84:85], v[52:53], 0.5 op_sel_hi:[1,0]
	v_pk_mul_f32 v[82:83], v[50:51], 0.5 op_sel_hi:[1,0]
	v_pk_mul_f32 v[80:81], v[48:49], 0.5 op_sel_hi:[1,0]
	v_pk_mul_f32 v[94:95], v[30:31], 0.5 op_sel_hi:[1,0]
	v_pk_mul_f32 v[92:93], v[28:29], 0.5 op_sel_hi:[1,0]
	v_pk_mul_f32 v[90:91], v[22:23], 0.5 op_sel_hi:[1,0]
	v_pk_mul_f32 v[88:89], v[20:21], 0.5 op_sel_hi:[1,0]
	v_pk_mul_f32 v[70:71], v[42:43], 0.5 op_sel_hi:[1,0]
	v_pk_mul_f32 v[68:69], v[40:41], 0.5 op_sel_hi:[1,0]
	v_pk_mul_f32 v[66:67], v[34:35], 0.5 op_sel_hi:[1,0]
	v_pk_mul_f32 v[64:65], v[32:33], 0.5 op_sel_hi:[1,0]
	v_pk_mul_f32 v[78:79], v[14:15], 0.5 op_sel_hi:[1,0]
	v_pk_mul_f32 v[76:77], v[12:13], 0.5 op_sel_hi:[1,0]
	v_pk_mul_f32 v[74:75], v[10:11], 0.5 op_sel_hi:[1,0]
	v_pk_mul_f32 v[72:73], v[8:9], 0.5 op_sel_hi:[1,0]
	v_pk_mul_f32 v[54:55], v[26:27], 0.5 op_sel_hi:[1,0]
	v_pk_mul_f32 v[52:53], v[24:25], 0.5 op_sel_hi:[1,0]
	v_pk_mul_f32 v[50:51], v[18:19], 0.5 op_sel_hi:[1,0]
	v_pk_mul_f32 v[48:49], v[16:17], 0.5 op_sel_hi:[1,0]
	v_pk_mul_f32 v[62:63], v[6:7], 0.5 op_sel_hi:[1,0]
	v_pk_mul_f32 v[60:61], v[4:5], 0.5 op_sel_hi:[1,0]
	v_pk_mul_f32 v[58:59], v[2:3], 0.5 op_sel_hi:[1,0]
	v_pk_mul_f32 v[56:57], v[0:1], 0.5 op_sel_hi:[1,0]

; #define PG8_STAGE(bufoff, gbase, voff) do { _Pragma("unroll") for (int _i = 0; _i < 2; ++_i) \
;         __builtin_amdgcn_global_load_lds((const unsigned*)((const char*)(gbase) + (voff)[_i]), (LAS unsigned*)(lds + (bufoff) + ldsw + _i * 8192), 16, 0, ((voff) == voffA ? AUXA : 0)); } while (0)
; #define PG8_LDA(dst, b, h) do { _Pragma("unroll") for (int m = 0; m < 4; ++m) _Pragma("unroll") for (int k = 0; k < 2; ++k) dst[m][k] = *(const LAS bf16x8*)(lds + PG8_SA(b, h) + aoff + m * 2048 + k * 1024); } while (0)
; #define PG8_LDB(dst, b, h) do { _Pragma("unroll") for (int n = 0; n < 2; ++n) _Pragma("unroll") for (int k = 0; k < 2; ++k) dst[n][k] = *(const LAS bf16x8*)(lds + PG8_SB(b, h) + boff + n * 2048 + k * 1024); } while (0)
; #define PG8_MMA(ai, bj, At, Bt) do { __builtin_amdgcn_s_setprio(1); _Pragma("unroll") for (int m = 0; m < 4; ++m) _Pragma("unroll") for (int n = 0; n < 2; ++n) _Pragma("unroll") for (int k = 0; k < 2; ++k) \
;         acc[ai][bj][m][n] = __builtin_amdgcn_mfma_f32_16x16x32_bf16(Bt[n][k], At[m][k], acc[ai][bj][m][n], 0, 0, 0); __builtin_amdgcn_s_setprio(0); } while (0)
; #define PG8_WAIT_V(n) asm volatile("s_waitcnt vmcnt(" #n ")" ::: "memory")
; #define PG8_WAIT_L(n) asm volatile("s_waitcnt lgkmcnt(" #n ")" ::: "memory")
; #define PG8_BAR __builtin_amdgcn_s_barrier()
; #define PG8_SCHED __builtin_amdgcn_sched_barrier(0)
;     ...
;             PG8_WAIT_L(0); PG8_BAR; PG8_MMA(0, 0, At, B0); PG8_MMA(0, 1, At, B1); PG8_BAR; PG8_SCHED;
;             PG8_LDA(At, 0, 1); PG8_STAGE(PG8_SB(0, 0), b2, voffB); PG8_STAGE(PG8_SB(0, 1), b2 + hsB, voffB); PG8_STAGE(PG8_SA(0, 0), a2, voffA);
;             if (Epi::NPRE != 0 && last) { PG8_WAIT_V(16); } else { PG8_WAIT_V(8); }
;             PG8_WAIT_L(0); PG8_BAR; PG8_MMA(1, 0, At, B0); PG8_MMA(1, 1, At, B1); PG8_BAR; PG8_SCHED;
;             PG8_LDB(B0, 1, 0); PG8_LDB(B1, 1, 1); PG8_SCHED; PG8_LDA(At, 1, 0); PG8_STAGE(PG8_SA(0, 1), a2 + hsA, voffA);
;             PG8_WAIT_V(8); PG8_WAIT_L(0); PG8_BAR; PG8_MMA(0, 0, At, B0); PG8_MMA(0, 1, At, B1); PG8_BAR; PG8_SCHED;
;             PG8_LDA(At, 1, 1); PG8_STAGE(PG8_SB(1, 0), b3, voffB); PG8_STAGE(PG8_SB(1, 1), b3 + hsB, voffB); PG8_STAGE(PG8_SA(1, 0), a3, voffA);
;             PG8_WAIT_V(8); PG8_WAIT_L(0); PG8_BAR; PG8_MMA(1, 0, At, B0); PG8_MMA(1, 1, At, B1); PG8_BAR; PG8_SCHED;
.LBB0_370:
	s_waitcnt lgkmcnt(0)
	s_add_i32 s71, s71, 2
	s_setprio 1
	s_barrier
	v_mfma_f32_16x16x32_bf16 v[60:63], v[144:147], v[184:187], v[60:63]
	v_mfma_f32_16x16x32_bf16 v[56:59], v[152:155], v[184:187], v[56:59]
	v_mfma_f32_16x16x32_bf16 v[44:47], v[144:147], v[176:179], v[44:47]
	v_mfma_f32_16x16x32_bf16 v[40:43], v[152:155], v[176:179], v[40:43]
	v_mfma_f32_16x16x32_bf16 v[28:31], v[144:147], v[168:171], v[28:31]
	v_mfma_f32_16x16x32_bf16 v[24:27], v[152:155], v[168:171], v[24:27]
	v_mfma_f32_16x16x32_bf16 v[12:15], v[144:147], v[160:163], v[12:15]
	v_mfma_f32_16x16x32_bf16 v[8:11], v[152:155], v[160:163], v[8:11]
	v_mfma_f32_16x16x32_bf16 v[60:63], v[148:151], v[188:191], v[60:63]
	v_mfma_f32_16x16x32_bf16 v[56:59], v[156:159], v[188:191], v[56:59]
	v_mfma_f32_16x16x32_bf16 v[44:47], v[148:151], v[180:183], v[44:47]
	v_mfma_f32_16x16x32_bf16 v[40:43], v[156:159], v[180:183], v[40:43]
	v_mfma_f32_16x16x32_bf16 v[28:31], v[148:151], v[172:175], v[28:31]
	v_mfma_f32_16x16x32_bf16 v[24:27], v[156:159], v[172:175], v[24:27]
	v_mfma_f32_16x16x32_bf16 v[12:15], v[148:151], v[164:167], v[12:15]
	v_mfma_f32_16x16x32_bf16 v[8:11], v[156:159], v[164:167], v[8:11]
	s_mov_b32 m0, s43
	s_nop 0
	global_load_lds_dwordx4 v200, s[100:101]
	v_mfma_f32_16x16x32_bf16 v[52:55], v[128:131], v[184:187], v[52:55]
	v_mfma_f32_16x16x32_bf16 v[48:51], v[136:139], v[184:187], v[48:51]
	v_mfma_f32_16x16x32_bf16 v[36:39], v[128:131], v[176:179], v[36:39]
	v_mfma_f32_16x16x32_bf16 v[32:35], v[136:139], v[176:179], v[32:35]
	v_mfma_f32_16x16x32_bf16 v[20:23], v[128:131], v[168:171], v[20:23]
	v_mfma_f32_16x16x32_bf16 v[16:19], v[136:139], v[168:171], v[16:19]
	v_mfma_f32_16x16x32_bf16 v[4:7], v[128:131], v[160:163], v[4:7]
	v_mfma_f32_16x16x32_bf16 v[0:3], v[136:139], v[160:163], v[0:3]
	v_mfma_f32_16x16x32_bf16 v[52:55], v[132:135], v[188:191], v[52:55]
	v_mfma_f32_16x16x32_bf16 v[48:51], v[140:143], v[188:191], v[48:51]
	v_mfma_f32_16x16x32_bf16 v[36:39], v[132:135], v[180:183], v[36:39]
	v_mfma_f32_16x16x32_bf16 v[32:35], v[140:143], v[180:183], v[32:35]
	v_mfma_f32_16x16x32_bf16 v[20:23], v[132:135], v[172:175], v[20:23]
	v_mfma_f32_16x16x32_bf16 v[16:19], v[140:143], v[172:175], v[16:19]
	v_mfma_f32_16x16x32_bf16 v[4:7], v[132:135], v[164:167], v[4:7]
	v_mfma_f32_16x16x32_bf16 v[0:3], v[140:143], v[164:167], v[0:3]
	s_barrier
	s_mov_b32 m0, s13
	s_nop 0
	global_load_lds_dwordx4 v194, s[34:35]
	s_mov_b32 m0, s44
	s_nop 0
	global_load_lds_dwordx4 v198, s[34:35]
	s_setprio 0
	s_add_i32 s36, 0, 0x18000
	s_add_i32 s37, 0, 0x1c000
	v_add_u32_e32 v140, s36, v235
	v_add_u32_e32 v156, s37, v235
	ds_read_b128 v[128:131], v140
	ds_read_b128 v[132:135], v140 offset:1024
	ds_read_b128 v[136:139], v140 offset:2048
	ds_read_b128 v[140:143], v140 offset:3072
	ds_read_b128 v[144:147], v156
	ds_read_b128 v[148:151], v156 offset:1024
	ds_read_b128 v[152:155], v156 offset:2048
	ds_read_b128 v[156:159], v156 offset:3072
	s_add_u32 s34, s34, 0x80000
	s_addc_u32 s35, s35, 0
	s_mov_b32 m0, s45
	ds_read_b128 v[160:163], v239 offset:32768
	ds_read_b128 v[164:167], v239 offset:33792
	ds_read_b128 v[168:171], v239 offset:34816
	ds_read_b128 v[172:175], v239 offset:35840
	ds_read_b128 v[176:179], v239 offset:36864
	ds_read_b128 v[180:183], v239 offset:37888
	ds_read_b128 v[184:187], v239 offset:38912
	ds_read_b128 v[188:191], v239 offset:39936
	global_load_lds_dwordx4 v194, s[34:35]
	s_waitcnt vmcnt(7)
	s_waitcnt lgkmcnt(0)
	s_setprio 1
	s_barrier
	v_mfma_f32_16x16x32_bf16 v[124:127], v[128:131], v[160:163], v[124:127]
	v_mfma_f32_16x16x32_bf16 v[120:123], v[136:139], v[160:163], v[120:123]
	v_mfma_f32_16x16x32_bf16 v[108:111], v[128:131], v[168:171], v[108:111]
	v_mfma_f32_16x16x32_bf16 v[104:107], v[136:139], v[168:171], v[104:107]
	v_mfma_f32_16x16x32_bf16 v[92:95], v[128:131], v[176:179], v[92:95]
	v_mfma_f32_16x16x32_bf16 v[88:91], v[136:139], v[176:179], v[88:91]
	v_mfma_f32_16x16x32_bf16 v[76:79], v[128:131], v[184:187], v[76:79]
	v_mfma_f32_16x16x32_bf16 v[72:75], v[136:139], v[184:187], v[72:75]
	v_mfma_f32_16x16x32_bf16 v[124:127], v[132:135], v[164:167], v[124:127]
	v_mfma_f32_16x16x32_bf16 v[120:123], v[140:143], v[164:167], v[120:123]
	v_mfma_f32_16x16x32_bf16 v[108:111], v[132:135], v[172:175], v[108:111]
	v_mfma_f32_16x16x32_bf16 v[104:107], v[140:143], v[172:175], v[104:107]
	v_mfma_f32_16x16x32_bf16 v[92:95], v[132:135], v[180:183], v[92:95]
	v_mfma_f32_16x16x32_bf16 v[88:91], v[140:143], v[180:183], v[88:91]
	v_mfma_f32_16x16x32_bf16 v[76:79], v[132:135], v[188:191], v[76:79]
	v_mfma_f32_16x16x32_bf16 v[72:75], v[140:143], v[188:191], v[72:75]
	s_mov_b32 m0, s46
	s_nop 0
	global_load_lds_dwordx4 v198, s[34:35]
	v_mfma_f32_16x16x32_bf16 v[116:119], v[144:147], v[160:163], v[116:119]
	v_mfma_f32_16x16x32_bf16 v[112:115], v[152:155], v[160:163], v[112:115]
	v_mfma_f32_16x16x32_bf16 v[100:103], v[144:147], v[168:171], v[100:103]
	v_mfma_f32_16x16x32_bf16 v[96:99], v[152:155], v[168:171], v[96:99]
	v_mfma_f32_16x16x32_bf16 v[84:87], v[144:147], v[176:179], v[84:87]
	v_mfma_f32_16x16x32_bf16 v[80:83], v[152:155], v[176:179], v[80:83]
	v_mfma_f32_16x16x32_bf16 v[68:71], v[144:147], v[184:187], v[68:71]
	v_mfma_f32_16x16x32_bf16 v[64:67], v[152:155], v[184:187], v[64:67]
	v_mfma_f32_16x16x32_bf16 v[116:119], v[148:151], v[164:167], v[116:119]
	v_mfma_f32_16x16x32_bf16 v[112:115], v[156:159], v[164:167], v[112:115]
	v_mfma_f32_16x16x32_bf16 v[100:103], v[148:151], v[172:175], v[100:103]
	v_mfma_f32_16x16x32_bf16 v[96:99], v[156:159], v[172:175], v[96:99]
	v_mfma_f32_16x16x32_bf16 v[84:87], v[148:151], v[180:183], v[84:87]
	v_mfma_f32_16x16x32_bf16 v[80:83], v[156:159], v[180:183], v[80:83]
	v_mfma_f32_16x16x32_bf16 v[68:71], v[148:151], v[188:191], v[68:71]
	v_mfma_f32_16x16x32_bf16 v[64:67], v[156:159], v[188:191], v[64:67]
	s_barrier
; #define PG8_STAGE(bufoff, gbase, voff) do { _Pragma("unroll") for (int _i = 0; _i < 2; ++_i) \
;         __builtin_amdgcn_global_load_lds((const unsigned*)((const char*)(gbase) + (voff)[_i]), (LAS unsigned*)(lds + (bufoff) + ldsw + _i * 8192), 16, 0, ((voff) == voffA ? AUXA : 0)); } while (0)
; #define PG8_LDA(dst, b, h) do { _Pragma("unroll") for (int m = 0; m < 4; ++m) _Pragma("unroll") for (int k = 0; k < 2; ++k) dst[m][k] = *(const LAS bf16x8*)(lds + PG8_SA(b, h) + aoff + m * 2048 + k * 1024); } while (0)
; #define PG8_LDB(dst, b, h) do { _Pragma("unroll") for (int n = 0; n < 2; ++n) _Pragma("unroll") for (int k = 0; k < 2; ++k) dst[n][k] = *(const LAS bf16x8*)(lds + PG8_SB(b, h) + boff + n * 2048 + k * 1024); } while (0)
; #define PG8_MMA(ai, bj, At, Bt) do { __builtin_amdgcn_s_setprio(1); _Pragma("unroll") for (int m = 0; m < 4; ++m) _Pragma("unroll") for (int n = 0; n < 2; ++n) _Pragma("unroll") for (int k = 0; k < 2; ++k) \
;         acc[ai][bj][m][n] = __builtin_amdgcn_mfma_f32_16x16x32_bf16(Bt[n][k], At[m][k], acc[ai][bj][m][n], 0, 0, 0); __builtin_amdgcn_s_setprio(0); } while (0)
; #define PG8_WAIT_V(n) asm volatile("s_waitcnt vmcnt(" #n ")" ::: "memory")
; #define PG8_WAIT_L(n) asm volatile("s_waitcnt lgkmcnt(" #n ")" ::: "memory")
; #define PG8_BAR __builtin_amdgcn_s_barrier()
; #define PG8_SCHED __builtin_amdgcn_sched_barrier(0)
;     ...
;             const bool last = (t == nt - 2);
;             const char* a1 = cA + (size_t)(t + 1) * kstep;
;             const char* a2 = last ? nA : cA + (size_t)(t + 2) * kstep; const char* b2 = last ? nB : cB + (size_t)(t + 2) * kstep;
;             const char* a3 = a2 + kstep; const char* b3 = b2 + kstep;
;             PG8_LDB(B0, 0, 0); PG8_LDB(B1, 0, 1); PG8_SCHED; PG8_LDA(At, 0, 0); PG8_STAGE(PG8_SA(1, 1), a1 + hsA, voffA);
;             if (Epi::NPRE != 0 && last) { E.pre(sv, cur, wr, fr); PG8_WAIT_V(16); } else { PG8_WAIT_V(8); }
;     ...
;             PG8_LDA(At, 1, 1); PG8_STAGE(PG8_SB(1, 0), b3, voffB); PG8_STAGE(PG8_SB(1, 1), b3 + hsB, voffB); PG8_STAGE(PG8_SA(1, 0), a3, voffA);
;             PG8_WAIT_V(8); PG8_WAIT_L(0); PG8_BAR; PG8_MMA(1, 0, At, B0); PG8_MMA(1, 1, At, B1); PG8_BAR; PG8_SCHED;
;         }
	s_setprio 0
	s_add_i32 s34, s36, s5
	s_mov_b32 m0, s34
	ds_read_b128 v[160:163], v239 offset:49152
	ds_read_b128 v[164:167], v239 offset:50176
	ds_read_b128 v[168:171], v239 offset:51200
	ds_read_b128 v[172:175], v239 offset:52224
	ds_read_b128 v[176:179], v239 offset:53248
	ds_read_b128 v[180:183], v239 offset:54272
	ds_read_b128 v[184:187], v239 offset:55296
	ds_read_b128 v[188:191], v239 offset:56320
	global_load_lds_dwordx4 v196, s[98:99]
	s_add_i32 m0, s34, 0x2000
	s_add_u32 s30, s30, 0x80080
	s_addc_u32 s31, s31, 0
	s_add_i32 s34, s37, s5
	global_load_lds_dwordx4 v200, s[98:99]
	s_mov_b32 m0, s34
	s_nop 0
	global_load_lds_dwordx4 v196, s[30:31]
	s_waitcnt vmcnt(5)
	s_waitcnt lgkmcnt(0)
	s_setprio 1
	s_barrier
	v_mfma_f32_16x16x32_bf16 v[60:63], v[128:131], v[160:163], v[60:63]
	v_mfma_f32_16x16x32_bf16 v[56:59], v[136:139], v[160:163], v[56:59]
	v_mfma_f32_16x16x32_bf16 v[44:47], v[128:131], v[168:171], v[44:47]
	v_mfma_f32_16x16x32_bf16 v[40:43], v[136:139], v[168:171], v[40:43]
	v_mfma_f32_16x16x32_bf16 v[28:31], v[128:131], v[176:179], v[28:31]
	v_mfma_f32_16x16x32_bf16 v[24:27], v[136:139], v[176:179], v[24:27]
	v_mfma_f32_16x16x32_bf16 v[12:15], v[128:131], v[184:187], v[12:15]
	v_mfma_f32_16x16x32_bf16 v[8:11], v[136:139], v[184:187], v[8:11]
	v_mfma_f32_16x16x32_bf16 v[60:63], v[132:135], v[164:167], v[60:63]
	v_mfma_f32_16x16x32_bf16 v[56:59], v[140:143], v[164:167], v[56:59]
	v_mfma_f32_16x16x32_bf16 v[44:47], v[132:135], v[172:175], v[44:47]
	v_mfma_f32_16x16x32_bf16 v[40:43], v[140:143], v[172:175], v[40:43]
	v_mfma_f32_16x16x32_bf16 v[28:31], v[132:135], v[180:183], v[28:31]
	v_mfma_f32_16x16x32_bf16 v[24:27], v[140:143], v[180:183], v[24:27]
	v_mfma_f32_16x16x32_bf16 v[12:15], v[132:135], v[188:191], v[12:15]
	v_mfma_f32_16x16x32_bf16 v[8:11], v[140:143], v[188:191], v[8:11]
	s_add_i32 m0, s34, 0x2000
	s_nop 0
	global_load_lds_dwordx4 v200, s[30:31]
	v_mfma_f32_16x16x32_bf16 v[52:55], v[144:147], v[160:163], v[52:55]
	v_mfma_f32_16x16x32_bf16 v[48:51], v[152:155], v[160:163], v[48:51]
	v_mfma_f32_16x16x32_bf16 v[36:39], v[144:147], v[168:171], v[36:39]
	v_mfma_f32_16x16x32_bf16 v[32:35], v[152:155], v[168:171], v[32:35]
	v_mfma_f32_16x16x32_bf16 v[20:23], v[144:147], v[176:179], v[20:23]
	v_mfma_f32_16x16x32_bf16 v[16:19], v[152:155], v[176:179], v[16:19]
	v_mfma_f32_16x16x32_bf16 v[4:7], v[144:147], v[184:187], v[4:7]
	v_mfma_f32_16x16x32_bf16 v[0:3], v[152:155], v[184:187], v[0:3]
	v_mfma_f32_16x16x32_bf16 v[52:55], v[148:151], v[164:167], v[52:55]
	v_mfma_f32_16x16x32_bf16 v[48:51], v[156:159], v[164:167], v[48:51]
	v_mfma_f32_16x16x32_bf16 v[36:39], v[148:151], v[172:175], v[36:39]
	v_mfma_f32_16x16x32_bf16 v[32:35], v[156:159], v[172:175], v[32:35]
	v_mfma_f32_16x16x32_bf16 v[20:23], v[148:151], v[180:183], v[20:23]
	v_mfma_f32_16x16x32_bf16 v[16:19], v[156:159], v[180:183], v[16:19]
	v_mfma_f32_16x16x32_bf16 v[4:7], v[148:151], v[188:191], v[4:7]
	v_mfma_f32_16x16x32_bf16 v[0:3], v[156:159], v[188:191], v[0:3]
	s_barrier
	s_setprio 0
	s_add_u32 s28, s28, 0x100
	s_addc_u32 s29, s29, 0
	s_add_u32 s69, s69, 0x100
	s_addc_u32 s70, s70, 0
	s_cmp_ge_i32 s71, s48
	s_cbranch_scc1 .LBB0_380
.LBB0_371:
	s_add_u32 s98, s28, 0xfff80000
	s_addc_u32 s99, s29, -1
	s_mov_b32 m0, s50
	s_nop 0
	global_load_lds_dwordx4 v194, s[98:99]
	s_mov_b32 m0, s51
	s_nop 0
	global_load_lds_dwordx4 v198, s[98:99]
	ds_read_b128 v[144:147], v237
	ds_read_b128 v[148:151], v237 offset:1024
	ds_read_b128 v[152:155], v237 offset:2048
	ds_read_b128 v[156:159], v237 offset:3072
	ds_read_b128 v[128:131], v238
	ds_read_b128 v[132:135], v238 offset:1024
	ds_read_b128 v[136:139], v238 offset:2048
	ds_read_b128 v[140:143], v238 offset:3072
	s_cmp_eq_u32 s53, s71
	s_cselect_b64 s[30:31], -1, 0
	s_cmp_lg_u32 s53, s71
	s_cselect_b64 s[36:37], -1, 0
	s_add_i32 m0, s13, 0xc000
	ds_read_b128 v[184:187], v239
	ds_read_b128 v[188:191], v239 offset:1024
	ds_read_b128 v[176:179], v239 offset:2048
	ds_read_b128 v[180:183], v239 offset:3072
	ds_read_b128 v[168:171], v239 offset:4096
	ds_read_b128 v[172:175], v239 offset:5120
	ds_read_b128 v[160:163], v239 offset:6144
	ds_read_b128 v[164:167], v239 offset:7168
	global_load_lds_dwordx4 v216, s[28:29]
	s_mov_b64 s[34:35], -1
	s_and_b64 vcc, exec, s[36:37]
	s_cbranch_vccz .LBB0_373
	s_waitcnt vmcnt(7)
	s_mov_b64 s[34:35], 0
; #define PG8_STAGE(bufoff, gbase, voff) do { _Pragma("unroll") for (int _i = 0; _i < 2; ++_i) \
;         __builtin_amdgcn_global_load_lds((const unsigned*)((const char*)(gbase) + (voff)[_i]), (LAS unsigned*)(lds + (bufoff) + ldsw + _i * 8192), 16, 0, ((voff) == voffA ? AUXA : 0)); } while (0)
; #define PG8_LDA(dst, b, h) do { _Pragma("unroll") for (int m = 0; m < 4; ++m) _Pragma("unroll") for (int k = 0; k < 2; ++k) dst[m][k] = *(const LAS bf16x8*)(lds + PG8_SA(b, h) + aoff + m * 2048 + k * 1024); } while (0)
; #define PG8_MMA(ai, bj, At, Bt) do { __builtin_amdgcn_s_setprio(1); _Pragma("unroll") for (int m = 0; m < 4; ++m) _Pragma("unroll") for (int n = 0; n < 2; ++n) _Pragma("unroll") for (int k = 0; k < 2; ++k) \
;         acc[ai][bj][m][n] = __builtin_amdgcn_mfma_f32_16x16x32_bf16(Bt[n][k], At[m][k], acc[ai][bj][m][n], 0, 0, 0); __builtin_amdgcn_s_setprio(0); } while (0)
; #define PG8_WAIT_V(n) asm volatile("s_waitcnt vmcnt(" #n ")" ::: "memory")
; #define PG8_WAIT_L(n) asm volatile("s_waitcnt lgkmcnt(" #n ")" ::: "memory")
; #define PG8_BAR __builtin_amdgcn_s_barrier()
; #define PG8_SCHED __builtin_amdgcn_sched_barrier(0)
;     ...
;             if (Epi::NPRE != 0 && last) { E.pre(sv, cur, wr, fr); PG8_WAIT_V(16); } else { PG8_WAIT_V(8); }
;             PG8_WAIT_L(0); PG8_BAR; PG8_MMA(0, 0, At, B0); PG8_MMA(0, 1, At, B1); PG8_BAR; PG8_SCHED;
;             PG8_LDA(At, 0, 1); PG8_STAGE(PG8_SB(0, 0), b2, voffB); PG8_STAGE(PG8_SB(0, 1), b2 + hsB, voffB); PG8_STAGE(PG8_SA(0, 0), a2, voffA);
;             if (Epi::NPRE != 0 && last) { PG8_WAIT_V(16); } else { PG8_WAIT_V(8); }
;     __device__ __forceinline__ void pre(float (&sv)[8], const Unit& u, int wr, int fr) const {
; #pragma unroll
;         for (int i = 0; i < 8; ++i) sv[i] = ss[u.pm * 256 + wr * 64 + fr + (i >> 2) * 128 + (i & 3) * 16]; }
.LBB0_373:
	s_andn2_b64 vcc, exec, s[34:35]
	s_cbranch_vccnz .LBB0_375
	global_load_dword v248, v[224:225], off
	global_load_dword v247, v[224:225], off offset:64
	global_load_dword v246, v[224:225], off offset:128
	global_load_dword v245, v[224:225], off offset:192
	global_load_dword v244, v[224:225], off offset:512
	global_load_dword v243, v[224:225], off offset:576
	global_load_dword v242, v[224:225], off offset:640
	global_load_dword v241, v[224:225], off offset:704
	s_waitcnt vmcnt(15)
.LBB0_375:
	s_add_u32 s34, s28, 0xfff80080
	s_addc_u32 s35, s29, -1
	s_waitcnt lgkmcnt(0)
	s_and_b64 s[30:31], s[30:31], exec
	s_cselect_b32 s35, s7, s35
	s_cselect_b32 s34, s21, s34
	s_cselect_b32 s31, s23, s70
	s_cselect_b32 s30, s68, s69
	s_setprio 1
	s_barrier
	v_mfma_f32_16x16x32_bf16 v[124:127], v[144:147], v[184:187], v[124:127]
	v_mfma_f32_16x16x32_bf16 v[120:123], v[152:155], v[184:187], v[120:123]
	v_mfma_f32_16x16x32_bf16 v[108:111], v[144:147], v[176:179], v[108:111]
	v_mfma_f32_16x16x32_bf16 v[104:107], v[152:155], v[176:179], v[104:107]
	v_mfma_f32_16x16x32_bf16 v[92:95], v[144:147], v[168:171], v[92:95]
	v_mfma_f32_16x16x32_bf16 v[88:91], v[152:155], v[168:171], v[88:91]
	v_mfma_f32_16x16x32_bf16 v[76:79], v[144:147], v[160:163], v[76:79]
	v_mfma_f32_16x16x32_bf16 v[72:75], v[152:155], v[160:163], v[72:75]
	v_mfma_f32_16x16x32_bf16 v[124:127], v[148:151], v[188:191], v[124:127]
	v_mfma_f32_16x16x32_bf16 v[120:123], v[156:159], v[188:191], v[120:123]
	v_mfma_f32_16x16x32_bf16 v[108:111], v[148:151], v[180:183], v[108:111]
	v_mfma_f32_16x16x32_bf16 v[104:107], v[156:159], v[180:183], v[104:107]
	v_mfma_f32_16x16x32_bf16 v[92:95], v[148:151], v[172:175], v[92:95]
	v_mfma_f32_16x16x32_bf16 v[88:91], v[156:159], v[172:175], v[88:91]
	v_mfma_f32_16x16x32_bf16 v[76:79], v[148:151], v[164:167], v[76:79]
	v_mfma_f32_16x16x32_bf16 v[72:75], v[156:159], v[164:167], v[72:75]
	s_add_i32 m0, s13, 0xe000
	s_nop 0
	global_load_lds_dwordx4 v218, s[28:29]
	v_mfma_f32_16x16x32_bf16 v[116:119], v[128:131], v[184:187], v[116:119]
	v_mfma_f32_16x16x32_bf16 v[112:115], v[136:139], v[184:187], v[112:115]
	v_mfma_f32_16x16x32_bf16 v[100:103], v[128:131], v[176:179], v[100:103]
	v_mfma_f32_16x16x32_bf16 v[96:99], v[136:139], v[176:179], v[96:99]
	v_mfma_f32_16x16x32_bf16 v[84:87], v[128:131], v[168:171], v[84:87]
	v_mfma_f32_16x16x32_bf16 v[80:83], v[136:139], v[168:171], v[80:83]
	v_mfma_f32_16x16x32_bf16 v[68:71], v[128:131], v[160:163], v[68:71]
	v_mfma_f32_16x16x32_bf16 v[64:67], v[136:139], v[160:163], v[64:67]
	v_mfma_f32_16x16x32_bf16 v[116:119], v[132:135], v[188:191], v[116:119]
	v_mfma_f32_16x16x32_bf16 v[112:115], v[140:143], v[188:191], v[112:115]
	v_mfma_f32_16x16x32_bf16 v[100:103], v[132:135], v[180:183], v[100:103]
	v_mfma_f32_16x16x32_bf16 v[96:99], v[140:143], v[180:183], v[96:99]
	v_mfma_f32_16x16x32_bf16 v[84:87], v[132:135], v[172:175], v[84:87]
	v_mfma_f32_16x16x32_bf16 v[80:83], v[140:143], v[172:175], v[80:83]
	v_mfma_f32_16x16x32_bf16 v[68:71], v[132:135], v[164:167], v[68:71]
	v_mfma_f32_16x16x32_bf16 v[64:67], v[140:143], v[164:167], v[64:67]
	s_barrier
	s_setprio 0
	s_add_u32 s98, s30, s10
	s_addc_u32 s99, s31, s11
	s_add_u32 s100, s34, s10
	s_addc_u32 s101, s35, s11
	s_mov_b32 m0, s40
	s_add_u32 s38, s30, 0x80000
	ds_read_b128 v[184:187], v239 offset:16384
	ds_read_b128 v[188:191], v239 offset:17408
	ds_read_b128 v[176:179], v239 offset:18432
	ds_read_b128 v[180:183], v239 offset:19456
	ds_read_b128 v[168:171], v239 offset:20480
	ds_read_b128 v[172:175], v239 offset:21504
	ds_read_b128 v[160:163], v239 offset:22528
	ds_read_b128 v[164:167], v239 offset:23552
	global_load_lds_dwordx4 v196, s[30:31]
	s_mov_b32 m0, s41
	s_addc_u32 s39, s31, 0
	global_load_lds_dwordx4 v200, s[30:31]
	s_mov_b32 m0, s42
	s_nop 0
	global_load_lds_dwordx4 v196, s[38:39]
	s_mov_b64 s[100:101], s[38:39]
	s_mov_b64 s[38:39], -1
	s_and_b64 vcc, exec, s[36:37]
	s_cbranch_vccz .LBB0_377
	s_waitcnt vmcnt(5)
	s_mov_b64 s[38:39], 0

; #define PG8_STAGE(bufoff, gbase, voff) do { _Pragma("unroll") for (int _i = 0; _i < 2; ++_i) \
;         __builtin_amdgcn_global_load_lds((const unsigned*)((const char*)(gbase) + (voff)[_i]), (LAS unsigned*)(lds + (bufoff) + ldsw + _i * 8192), 16, 0, ((voff) == voffA ? AUXA : 0)); } while (0)
; #define PG8_LDA(dst, b, h) do { _Pragma("unroll") for (int m = 0; m < 4; ++m) _Pragma("unroll") for (int k = 0; k < 2; ++k) dst[m][k] = *(const LAS bf16x8*)(lds + PG8_SA(b, h) + aoff + m * 2048 + k * 1024); } while (0)
; #define PG8_LDB(dst, b, h) do { _Pragma("unroll") for (int n = 0; n < 2; ++n) _Pragma("unroll") for (int k = 0; k < 2; ++k) dst[n][k] = *(const LAS bf16x8*)(lds + PG8_SB(b, h) + boff + n * 2048 + k * 1024); } while (0)
; #define PG8_MMA(ai, bj, At, Bt) do { __builtin_amdgcn_s_setprio(1); _Pragma("unroll") for (int m = 0; m < 4; ++m) _Pragma("unroll") for (int n = 0; n < 2; ++n) _Pragma("unroll") for (int k = 0; k < 2; ++k) \
;         acc[ai][bj][m][n] = __builtin_amdgcn_mfma_f32_16x16x32_bf16(Bt[n][k], At[m][k], acc[ai][bj][m][n], 0, 0, 0); __builtin_amdgcn_s_setprio(0); } while (0)
; #define PG8_WAIT_V(n) asm volatile("s_waitcnt vmcnt(" #n ")" ::: "memory")
; #define PG8_WAIT_L(n) asm volatile("s_waitcnt lgkmcnt(" #n ")" ::: "memory")
; #define PG8_BAR __builtin_amdgcn_s_barrier()
; #define PG8_SCHED __builtin_amdgcn_sched_barrier(0)
;     ...
;             const bool last = (t == nt - 2);
;             const char* a1 = cA + (size_t)(t + 1) * kstep;
;             const char* a2 = last ? nA : cA + (size_t)(t + 2) * kstep; const char* b2 = last ? nB : cB + (size_t)(t + 2) * kstep;
;             const char* a3 = a2 + kstep; const char* b3 = b2 + kstep;
;             PG8_LDB(B0, 0, 0); PG8_LDB(B1, 0, 1); PG8_SCHED; PG8_LDA(At, 0, 0); PG8_STAGE(PG8_SA(1, 1), a1 + hsA, voffA);
;             if (Epi::NPRE != 0 && last) { E.pre(sv, cur, wr, fr); PG8_WAIT_V(16); } else { PG8_WAIT_V(8); }
;             PG8_WAIT_L(0); PG8_BAR; PG8_MMA(0, 0, At, B0); PG8_MMA(0, 1, At, B1); PG8_BAR; PG8_SCHED;
;             PG8_LDA(At, 0, 1); PG8_STAGE(PG8_SB(0, 0), b2, voffB); PG8_STAGE(PG8_SB(0, 1), b2 + hsB, voffB); PG8_STAGE(PG8_SA(0, 0), a2, voffA);
;             if (Epi::NPRE != 0 && last) { PG8_WAIT_V(16); } else { PG8_WAIT_V(8); }
;             PG8_WAIT_L(0); PG8_BAR; PG8_MMA(1, 0, At, B0); PG8_MMA(1, 1, At, B1); PG8_BAR; PG8_SCHED;
.LBB0_648:
	s_add_u32 s98, s22, 0xfffe0000
	s_addc_u32 s99, s23, -1
	s_mov_b32 m0, s36
	s_nop 0
	global_load_lds_dwordx4 v134, s[98:99]
	s_mov_b32 m0, s37
	s_nop 0
	global_load_lds_dwordx4 v130, s[98:99]
	ds_read_b128 v[148:151], v143
	ds_read_b128 v[152:155], v143 offset:1024
	ds_read_b128 v[156:159], v143 offset:2048
	ds_read_b128 v[160:163], v143 offset:3072
	ds_read_b128 v[164:167], v144
	ds_read_b128 v[168:171], v144 offset:1024
	ds_read_b128 v[172:175], v144 offset:2048
	ds_read_b128 v[176:179], v144 offset:3072
	s_add_i32 s56, s24, 2
	s_add_u32 s25, s22, 0xfffe0080
	s_addc_u32 s26, s23, -1
	s_cmp_eq_u32 s38, s24
	s_cselect_b32 s24, s53, s54
	s_cselect_b32 s27, s50, s26
	s_cselect_b32 s26, s51, s25
	s_cselect_b32 s25, s52, s55
	s_mov_b32 m0, s39
	ds_read_b128 v[180:183], v145
	ds_read_b128 v[184:187], v145 offset:1024
	ds_read_b128 v[188:191], v145 offset:2048
	ds_read_b128 v[194:197], v145 offset:3072
	ds_read_b128 v[198:201], v145 offset:4096
	ds_read_b128 v[202:205], v145 offset:5120
	ds_read_b128 v[206:209], v145 offset:6144
	ds_read_b128 v[210:213], v145 offset:7168
	global_load_lds_dwordx4 v138, s[22:23]
	s_waitcnt vmcnt(7)
	s_waitcnt lgkmcnt(0)
	s_setprio 1
	s_barrier
	v_mfma_f32_16x16x32_bf16 v[124:127], v[148:151], v[180:183], v[124:127]
	v_mfma_f32_16x16x32_bf16 v[120:123], v[156:159], v[180:183], v[120:123]
	v_mfma_f32_16x16x32_bf16 v[108:111], v[148:151], v[188:191], v[108:111]
	v_mfma_f32_16x16x32_bf16 v[104:107], v[156:159], v[188:191], v[104:107]
	v_mfma_f32_16x16x32_bf16 v[92:95], v[148:151], v[198:201], v[92:95]
	v_mfma_f32_16x16x32_bf16 v[88:91], v[156:159], v[198:201], v[88:91]
	v_mfma_f32_16x16x32_bf16 v[76:79], v[148:151], v[206:209], v[76:79]
	v_mfma_f32_16x16x32_bf16 v[72:75], v[156:159], v[206:209], v[72:75]
	v_mfma_f32_16x16x32_bf16 v[124:127], v[152:155], v[184:187], v[124:127]
	v_mfma_f32_16x16x32_bf16 v[120:123], v[160:163], v[184:187], v[120:123]
	v_mfma_f32_16x16x32_bf16 v[108:111], v[152:155], v[194:197], v[108:111]
	v_mfma_f32_16x16x32_bf16 v[104:107], v[160:163], v[194:197], v[104:107]
	v_mfma_f32_16x16x32_bf16 v[92:95], v[152:155], v[202:205], v[92:95]
	v_mfma_f32_16x16x32_bf16 v[88:91], v[160:163], v[202:205], v[88:91]
	v_mfma_f32_16x16x32_bf16 v[76:79], v[152:155], v[210:213], v[76:79]
	v_mfma_f32_16x16x32_bf16 v[72:75], v[160:163], v[210:213], v[72:75]
	s_mov_b32 m0, s40
	s_nop 0
	global_load_lds_dwordx4 v140, s[22:23]
	v_mfma_f32_16x16x32_bf16 v[116:119], v[164:167], v[180:183], v[116:119]
	v_mfma_f32_16x16x32_bf16 v[112:115], v[172:175], v[180:183], v[112:115]
	v_mfma_f32_16x16x32_bf16 v[100:103], v[164:167], v[188:191], v[100:103]
	v_mfma_f32_16x16x32_bf16 v[96:99], v[172:175], v[188:191], v[96:99]
	v_mfma_f32_16x16x32_bf16 v[84:87], v[164:167], v[198:201], v[84:87]
	v_mfma_f32_16x16x32_bf16 v[80:83], v[172:175], v[198:201], v[80:83]
	v_mfma_f32_16x16x32_bf16 v[68:71], v[164:167], v[206:209], v[68:71]
	v_mfma_f32_16x16x32_bf16 v[64:67], v[172:175], v[206:209], v[64:67]
	v_mfma_f32_16x16x32_bf16 v[116:119], v[168:171], v[184:187], v[116:119]
	v_mfma_f32_16x16x32_bf16 v[112:115], v[176:179], v[184:187], v[112:115]
	v_mfma_f32_16x16x32_bf16 v[100:103], v[168:171], v[194:197], v[100:103]
	v_mfma_f32_16x16x32_bf16 v[96:99], v[176:179], v[194:197], v[96:99]
	v_mfma_f32_16x16x32_bf16 v[84:87], v[168:171], v[202:205], v[84:87]
	v_mfma_f32_16x16x32_bf16 v[80:83], v[176:179], v[202:205], v[80:83]
	v_mfma_f32_16x16x32_bf16 v[68:71], v[168:171], v[210:213], v[68:71]
	v_mfma_f32_16x16x32_bf16 v[64:67], v[176:179], v[210:213], v[64:67]
	s_barrier
	s_setprio 0
	s_add_u32 s98, s24, s12
	s_addc_u32 s99, s25, s13
	s_add_u32 s100, s26, s12
	s_addc_u32 s101, s27, s13
	s_mov_b32 m0, s41
	s_add_u32 s66, s24, 0x10000
	ds_read_b128 v[180:183], v145 offset:16384
	ds_read_b128 v[184:187], v145 offset:17408
	ds_read_b128 v[188:191], v145 offset:18432
	ds_read_b128 v[194:197], v145 offset:19456
	ds_read_b128 v[198:201], v145 offset:20480
	ds_read_b128 v[202:205], v145 offset:21504
	ds_read_b128 v[206:209], v145 offset:22528
	ds_read_b128 v[210:213], v145 offset:23552
	global_load_lds_dwordx4 v132, s[24:25]
	s_mov_b32 m0, s42
	s_addc_u32 s67, s25, 0
	global_load_lds_dwordx4 v128, s[24:25]
	s_mov_b32 m0, s43
	s_nop 0
	global_load_lds_dwordx4 v132, s[66:67]
	s_waitcnt vmcnt(5)
	s_waitcnt lgkmcnt(0)
	s_setprio 1
	s_barrier
	v_mfma_f32_16x16x32_bf16 v[60:63], v[148:151], v[180:183], v[60:63]
	v_mfma_f32_16x16x32_bf16 v[56:59], v[156:159], v[180:183], v[56:59]
	v_mfma_f32_16x16x32_bf16 v[44:47], v[148:151], v[188:191], v[44:47]
	v_mfma_f32_16x16x32_bf16 v[40:43], v[156:159], v[188:191], v[40:43]
	v_mfma_f32_16x16x32_bf16 v[28:31], v[148:151], v[198:201], v[28:31]
	v_mfma_f32_16x16x32_bf16 v[24:27], v[156:159], v[198:201], v[24:27]
	v_mfma_f32_16x16x32_bf16 v[12:15], v[148:151], v[206:209], v[12:15]
	v_mfma_f32_16x16x32_bf16 v[8:11], v[156:159], v[206:209], v[8:11]
	v_mfma_f32_16x16x32_bf16 v[60:63], v[152:155], v[184:187], v[60:63]
	v_mfma_f32_16x16x32_bf16 v[56:59], v[160:163], v[184:187], v[56:59]
	v_mfma_f32_16x16x32_bf16 v[44:47], v[152:155], v[194:197], v[44:47]
	v_mfma_f32_16x16x32_bf16 v[40:43], v[160:163], v[194:197], v[40:43]
	v_mfma_f32_16x16x32_bf16 v[28:31], v[152:155], v[202:205], v[28:31]
	v_mfma_f32_16x16x32_bf16 v[24:27], v[160:163], v[202:205], v[24:27]
	v_mfma_f32_16x16x32_bf16 v[12:15], v[152:155], v[210:213], v[12:15]
	v_mfma_f32_16x16x32_bf16 v[8:11], v[160:163], v[210:213], v[8:11]
	s_mov_b32 m0, s44
	s_nop 0
	global_load_lds_dwordx4 v128, s[66:67]
	v_mfma_f32_16x16x32_bf16 v[52:55], v[164:167], v[180:183], v[52:55]
	v_mfma_f32_16x16x32_bf16 v[48:51], v[172:175], v[180:183], v[48:51]
	v_mfma_f32_16x16x32_bf16 v[36:39], v[164:167], v[188:191], v[36:39]
	v_mfma_f32_16x16x32_bf16 v[32:35], v[172:175], v[188:191], v[32:35]
	v_mfma_f32_16x16x32_bf16 v[20:23], v[164:167], v[198:201], v[20:23]
	v_mfma_f32_16x16x32_bf16 v[16:19], v[172:175], v[198:201], v[16:19]
	v_mfma_f32_16x16x32_bf16 v[4:7], v[164:167], v[206:209], v[4:7]
	v_mfma_f32_16x16x32_bf16 v[0:3], v[172:175], v[206:209], v[0:3]
	v_mfma_f32_16x16x32_bf16 v[52:55], v[168:171], v[184:187], v[52:55]
	v_mfma_f32_16x16x32_bf16 v[48:51], v[176:179], v[184:187], v[48:51]
	v_mfma_f32_16x16x32_bf16 v[36:39], v[168:171], v[194:197], v[36:39]
	v_mfma_f32_16x16x32_bf16 v[32:35], v[176:179], v[194:197], v[32:35]
	v_mfma_f32_16x16x32_bf16 v[20:23], v[168:171], v[202:205], v[20:23]
	v_mfma_f32_16x16x32_bf16 v[16:19], v[176:179], v[202:205], v[16:19]
	v_mfma_f32_16x16x32_bf16 v[4:7], v[168:171], v[210:213], v[4:7]
	v_mfma_f32_16x16x32_bf16 v[0:3], v[176:179], v[210:213], v[0:3]
	s_barrier
; #define PG8_STAGE(bufoff, gbase, voff) do { _Pragma("unroll") for (int _i = 0; _i < 2; ++_i) \
;         __builtin_amdgcn_global_load_lds((const unsigned*)((const char*)(gbase) + (voff)[_i]), (LAS unsigned*)(lds + (bufoff) + ldsw + _i * 8192), 16, 0, ((voff) == voffA ? AUXA : 0)); } while (0)
; #define PG8_LDA(dst, b, h) do { _Pragma("unroll") for (int m = 0; m < 4; ++m) _Pragma("unroll") for (int k = 0; k < 2; ++k) dst[m][k] = *(const LAS bf16x8*)(lds + PG8_SA(b, h) + aoff + m * 2048 + k * 1024); } while (0)
; #define PG8_LDB(dst, b, h) do { _Pragma("unroll") for (int n = 0; n < 2; ++n) _Pragma("unroll") for (int k = 0; k < 2; ++k) dst[n][k] = *(const LAS bf16x8*)(lds + PG8_SB(b, h) + boff + n * 2048 + k * 1024); } while (0)
; #define PG8_MMA(ai, bj, At, Bt) do { __builtin_amdgcn_s_setprio(1); _Pragma("unroll") for (int m = 0; m < 4; ++m) _Pragma("unroll") for (int n = 0; n < 2; ++n) _Pragma("unroll") for (int k = 0; k < 2; ++k) \
;         acc[ai][bj][m][n] = __builtin_amdgcn_mfma_f32_16x16x32_bf16(Bt[n][k], At[m][k], acc[ai][bj][m][n], 0, 0, 0); __builtin_amdgcn_s_setprio(0); } while (0)
; #define PG8_WAIT_V(n) asm volatile("s_waitcnt vmcnt(" #n ")" ::: "memory")
; #define PG8_WAIT_L(n) asm volatile("s_waitcnt lgkmcnt(" #n ")" ::: "memory")
; #define PG8_BAR __builtin_amdgcn_s_barrier()
; #define PG8_SCHED __builtin_amdgcn_sched_barrier(0)
;     ...
;             PG8_LDB(B0, 1, 0); PG8_LDB(B1, 1, 1); PG8_SCHED; PG8_LDA(At, 1, 0); PG8_STAGE(PG8_SA(0, 1), a2 + hsA, voffA);
;             PG8_WAIT_V(8); PG8_WAIT_L(0); PG8_BAR; PG8_MMA(0, 0, At, B0); PG8_MMA(0, 1, At, B1); PG8_BAR; PG8_SCHED;
;             PG8_LDA(At, 1, 1); PG8_STAGE(PG8_SB(1, 0), b3, voffB); PG8_STAGE(PG8_SB(1, 1), b3 + hsB, voffB); PG8_STAGE(PG8_SA(1, 0), a3, voffA);
;             PG8_WAIT_V(8); PG8_WAIT_L(0); PG8_BAR; PG8_MMA(1, 0, At, B0); PG8_MMA(1, 1, At, B1); PG8_BAR; PG8_SCHED;
;         }
	s_mov_b32 m0, s3
	s_nop 0
	global_load_lds_dwordx4 v134, s[26:27]
	s_mov_b32 m0, s29
	s_nop 0
	global_load_lds_dwordx4 v130, s[26:27]
	s_setprio 0
	ds_read_b128 v[148:151], v146
	ds_read_b128 v[152:155], v146 offset:1024
	ds_read_b128 v[156:159], v146 offset:2048
	ds_read_b128 v[160:163], v146 offset:3072
	ds_read_b128 v[164:167], v147
	ds_read_b128 v[168:171], v147 offset:1024
	ds_read_b128 v[172:175], v147 offset:2048
	ds_read_b128 v[176:179], v147 offset:3072
	s_add_u32 s26, s26, 0x20000
	s_addc_u32 s27, s27, 0
	s_mov_b32 m0, s30
	ds_read_b128 v[180:183], v145 offset:32768
	ds_read_b128 v[184:187], v145 offset:33792
	ds_read_b128 v[188:191], v145 offset:34816
	ds_read_b128 v[194:197], v145 offset:35840
	ds_read_b128 v[198:201], v145 offset:36864
	ds_read_b128 v[202:205], v145 offset:37888
	ds_read_b128 v[206:209], v145 offset:38912
	ds_read_b128 v[210:213], v145 offset:39936
	global_load_lds_dwordx4 v134, s[26:27]
	s_waitcnt vmcnt(7)
	s_waitcnt lgkmcnt(0)
	s_setprio 1
	s_barrier
	v_mfma_f32_16x16x32_bf16 v[124:127], v[148:151], v[180:183], v[124:127]
	v_mfma_f32_16x16x32_bf16 v[120:123], v[156:159], v[180:183], v[120:123]
	v_mfma_f32_16x16x32_bf16 v[108:111], v[148:151], v[188:191], v[108:111]
	v_mfma_f32_16x16x32_bf16 v[104:107], v[156:159], v[188:191], v[104:107]
	v_mfma_f32_16x16x32_bf16 v[92:95], v[148:151], v[198:201], v[92:95]
	v_mfma_f32_16x16x32_bf16 v[88:91], v[156:159], v[198:201], v[88:91]
	v_mfma_f32_16x16x32_bf16 v[76:79], v[148:151], v[206:209], v[76:79]
	v_mfma_f32_16x16x32_bf16 v[72:75], v[156:159], v[206:209], v[72:75]
	v_mfma_f32_16x16x32_bf16 v[124:127], v[152:155], v[184:187], v[124:127]
	v_mfma_f32_16x16x32_bf16 v[120:123], v[160:163], v[184:187], v[120:123]
	v_mfma_f32_16x16x32_bf16 v[108:111], v[152:155], v[194:197], v[108:111]
	v_mfma_f32_16x16x32_bf16 v[104:107], v[160:163], v[194:197], v[104:107]
	v_mfma_f32_16x16x32_bf16 v[92:95], v[152:155], v[202:205], v[92:95]
	v_mfma_f32_16x16x32_bf16 v[88:91], v[160:163], v[202:205], v[88:91]
	v_mfma_f32_16x16x32_bf16 v[76:79], v[152:155], v[210:213], v[76:79]
	v_mfma_f32_16x16x32_bf16 v[72:75], v[160:163], v[210:213], v[72:75]
	s_mov_b32 m0, s31
	s_nop 0
	global_load_lds_dwordx4 v130, s[26:27]
	v_mfma_f32_16x16x32_bf16 v[116:119], v[164:167], v[180:183], v[116:119]
	v_mfma_f32_16x16x32_bf16 v[112:115], v[172:175], v[180:183], v[112:115]
	v_mfma_f32_16x16x32_bf16 v[100:103], v[164:167], v[188:191], v[100:103]
	v_mfma_f32_16x16x32_bf16 v[96:99], v[172:175], v[188:191], v[96:99]
	v_mfma_f32_16x16x32_bf16 v[84:87], v[164:167], v[198:201], v[84:87]
	v_mfma_f32_16x16x32_bf16 v[80:83], v[172:175], v[198:201], v[80:83]
	v_mfma_f32_16x16x32_bf16 v[68:71], v[164:167], v[206:209], v[68:71]
	v_mfma_f32_16x16x32_bf16 v[64:67], v[172:175], v[206:209], v[64:67]
	v_mfma_f32_16x16x32_bf16 v[116:119], v[168:171], v[184:187], v[116:119]
	v_mfma_f32_16x16x32_bf16 v[112:115], v[176:179], v[184:187], v[112:115]
	v_mfma_f32_16x16x32_bf16 v[100:103], v[168:171], v[194:197], v[100:103]
	v_mfma_f32_16x16x32_bf16 v[96:99], v[176:179], v[194:197], v[96:99]
	v_mfma_f32_16x16x32_bf16 v[84:87], v[168:171], v[202:205], v[84:87]
	v_mfma_f32_16x16x32_bf16 v[80:83], v[176:179], v[202:205], v[80:83]
	v_mfma_f32_16x16x32_bf16 v[68:71], v[168:171], v[210:213], v[68:71]
	v_mfma_f32_16x16x32_bf16 v[64:67], v[176:179], v[210:213], v[64:67]
	s_barrier
	s_setprio 0
	s_add_i32 s26, s45, s28
	s_mov_b32 m0, s26
	ds_read_b128 v[180:183], v145 offset:49152
	ds_read_b128 v[184:187], v145 offset:50176
	ds_read_b128 v[188:191], v145 offset:51200
	ds_read_b128 v[194:197], v145 offset:52224
	ds_read_b128 v[198:201], v145 offset:53248
	ds_read_b128 v[202:205], v145 offset:54272
	ds_read_b128 v[206:209], v145 offset:55296
	ds_read_b128 v[210:213], v145 offset:56320
	global_load_lds_dwordx4 v132, s[98:99]
	s_add_i32 m0, s26, 0x2000
	s_add_u32 s24, s24, 0x10080
	s_addc_u32 s25, s25, 0
	s_add_i32 s26, s46, s28
	global_load_lds_dwordx4 v128, s[98:99]
	s_mov_b32 m0, s26
	s_nop 0
	global_load_lds_dwordx4 v132, s[24:25]
	s_waitcnt vmcnt(5)
	s_waitcnt lgkmcnt(0)
	s_setprio 1
	s_barrier
	v_mfma_f32_16x16x32_bf16 v[60:63], v[148:151], v[180:183], v[60:63]
	v_mfma_f32_16x16x32_bf16 v[56:59], v[156:159], v[180:183], v[56:59]
	v_mfma_f32_16x16x32_bf16 v[44:47], v[148:151], v[188:191], v[44:47]
	v_mfma_f32_16x16x32_bf16 v[40:43], v[156:159], v[188:191], v[40:43]
	v_mfma_f32_16x16x32_bf16 v[28:31], v[148:151], v[198:201], v[28:31]
	v_mfma_f32_16x16x32_bf16 v[24:27], v[156:159], v[198:201], v[24:27]
	v_mfma_f32_16x16x32_bf16 v[12:15], v[148:151], v[206:209], v[12:15]
	v_mfma_f32_16x16x32_bf16 v[8:11], v[156:159], v[206:209], v[8:11]
	v_mfma_f32_16x16x32_bf16 v[60:63], v[152:155], v[184:187], v[60:63]
	v_mfma_f32_16x16x32_bf16 v[56:59], v[160:163], v[184:187], v[56:59]
	v_mfma_f32_16x16x32_bf16 v[44:47], v[152:155], v[194:197], v[44:47]
	v_mfma_f32_16x16x32_bf16 v[40:43], v[160:163], v[194:197], v[40:43]
	v_mfma_f32_16x16x32_bf16 v[28:31], v[152:155], v[202:205], v[28:31]
	v_mfma_f32_16x16x32_bf16 v[24:27], v[160:163], v[202:205], v[24:27]
	v_mfma_f32_16x16x32_bf16 v[12:15], v[152:155], v[210:213], v[12:15]
	v_mfma_f32_16x16x32_bf16 v[8:11], v[160:163], v[210:213], v[8:11]
	s_add_i32 m0, s26, 0x2000
	s_nop 0
	global_load_lds_dwordx4 v128, s[24:25]
	v_mfma_f32_16x16x32_bf16 v[52:55], v[164:167], v[180:183], v[52:55]
	v_mfma_f32_16x16x32_bf16 v[48:51], v[172:175], v[180:183], v[48:51]
	v_mfma_f32_16x16x32_bf16 v[36:39], v[164:167], v[188:191], v[36:39]
	v_mfma_f32_16x16x32_bf16 v[32:35], v[172:175], v[188:191], v[32:35]
	v_mfma_f32_16x16x32_bf16 v[20:23], v[164:167], v[198:201], v[20:23]
	v_mfma_f32_16x16x32_bf16 v[16:19], v[172:175], v[198:201], v[16:19]
	v_mfma_f32_16x16x32_bf16 v[4:7], v[164:167], v[206:209], v[4:7]
	v_mfma_f32_16x16x32_bf16 v[0:3], v[172:175], v[206:209], v[0:3]
	v_mfma_f32_16x16x32_bf16 v[52:55], v[168:171], v[184:187], v[52:55]
	v_mfma_f32_16x16x32_bf16 v[48:51], v[176:179], v[184:187], v[48:51]
	v_mfma_f32_16x16x32_bf16 v[36:39], v[168:171], v[194:197], v[36:39]
	v_mfma_f32_16x16x32_bf16 v[32:35], v[176:179], v[194:197], v[32:35]
	v_mfma_f32_16x16x32_bf16 v[20:23], v[168:171], v[202:205], v[20:23]
	v_mfma_f32_16x16x32_bf16 v[16:19], v[176:179], v[202:205], v[16:19]
	v_mfma_f32_16x16x32_bf16 v[4:7], v[168:171], v[210:213], v[4:7]
	v_mfma_f32_16x16x32_bf16 v[0:3], v[176:179], v[210:213], v[0:3]
	s_barrier
	s_setprio 0
	s_add_u32 s22, s22, 0x100
	s_addc_u32 s23, s23, 0
	s_add_u32 s54, s54, 0x100
	s_addc_u32 s55, s55, 0
	s_cmp_ge_i32 s56, s35
	s_mov_b32 s24, s56
	s_cbranch_scc0 .LBB0_648

; #define PG8_STAGE(bufoff, gbase, voff) do { _Pragma("unroll") for (int _i = 0; _i < 2; ++_i) \
;         __builtin_amdgcn_global_load_lds((const unsigned*)((const char*)(gbase) + (voff)[_i]), (LAS unsigned*)(lds + (bufoff) + ldsw + _i * 8192), 16, 0, ((voff) == voffA ? AUXA : 0)); } while (0)
; #define PG8_LDA(dst, b, h) do { _Pragma("unroll") for (int m = 0; m < 4; ++m) _Pragma("unroll") for (int k = 0; k < 2; ++k) dst[m][k] = *(const LAS bf16x8*)(lds + PG8_SA(b, h) + aoff + m * 2048 + k * 1024); } while (0)
; #define PG8_LDB(dst, b, h) do { _Pragma("unroll") for (int n = 0; n < 2; ++n) _Pragma("unroll") for (int k = 0; k < 2; ++k) dst[n][k] = *(const LAS bf16x8*)(lds + PG8_SB(b, h) + boff + n * 2048 + k * 1024); } while (0)
; #define PG8_MMA(ai, bj, At, Bt) do { __builtin_amdgcn_s_setprio(1); _Pragma("unroll") for (int m = 0; m < 4; ++m) _Pragma("unroll") for (int n = 0; n < 2; ++n) _Pragma("unroll") for (int k = 0; k < 2; ++k) \
;         acc[ai][bj][m][n] = __builtin_amdgcn_mfma_f32_16x16x32_bf16(Bt[n][k], At[m][k], acc[ai][bj][m][n], 0, 0, 0); __builtin_amdgcn_s_setprio(0); } while (0)
; #define PG8_WAIT_V(n) asm volatile("s_waitcnt vmcnt(" #n ")" ::: "memory")
; #define PG8_WAIT_L(n) asm volatile("s_waitcnt lgkmcnt(" #n ")" ::: "memory")
; #define PG8_BAR __builtin_amdgcn_s_barrier()
; #define PG8_SCHED __builtin_amdgcn_sched_barrier(0)
;     ...
;             const bool last = (t == nt - 2);
;             const char* a1 = cA + (size_t)(t + 1) * kstep;
;             const char* a2 = last ? nA : cA + (size_t)(t + 2) * kstep; const char* b2 = last ? nB : cB + (size_t)(t + 2) * kstep;
;             const char* a3 = a2 + kstep; const char* b3 = b2 + kstep;
;             PG8_LDB(B0, 0, 0); PG8_LDB(B1, 0, 1); PG8_SCHED; PG8_LDA(At, 0, 0); PG8_STAGE(PG8_SA(1, 1), a1 + hsA, voffA);
;             if (Epi::NPRE != 0 && last) { E.pre(sv, cur, wr, fr); PG8_WAIT_V(16); } else { PG8_WAIT_V(8); }
;             PG8_WAIT_L(0); PG8_BAR; PG8_MMA(0, 0, At, B0); PG8_MMA(0, 1, At, B1); PG8_BAR; PG8_SCHED;
;             PG8_LDA(At, 0, 1); PG8_STAGE(PG8_SB(0, 0), b2, voffB); PG8_STAGE(PG8_SB(0, 1), b2 + hsB, voffB); PG8_STAGE(PG8_SA(0, 0), a2, voffA);
;             if (Epi::NPRE != 0 && last) { PG8_WAIT_V(16); } else { PG8_WAIT_V(8); }
;             PG8_WAIT_L(0); PG8_BAR; PG8_MMA(1, 0, At, B0); PG8_MMA(1, 1, At, B1); PG8_BAR; PG8_SCHED;
.LBB0_887:
	s_add_u32 s98, s24, 0xfffe0000
	s_addc_u32 s99, s25, -1
	s_mov_b32 m0, s40
	s_nop 0
	global_load_lds_dwordx4 v134, s[98:99]
	s_mov_b32 m0, s41
	s_nop 0
	global_load_lds_dwordx4 v130, s[98:99]
	ds_read_b128 v[150:153], v146
	ds_read_b128 v[154:157], v146 offset:1024
	ds_read_b128 v[158:161], v146 offset:2048
	ds_read_b128 v[162:165], v146 offset:3072
	ds_read_b128 v[166:169], v147
	ds_read_b128 v[170:173], v147 offset:1024
	ds_read_b128 v[174:177], v147 offset:2048
	ds_read_b128 v[178:181], v147 offset:3072
	s_add_i32 s53, s26, 2
	s_add_u32 s27, s24, 0xfffe0080
	s_addc_u32 s28, s25, -1
	s_cmp_eq_u32 s42, s26
	s_cselect_b32 s26, s50, s51
	s_cselect_b32 s29, s23, s28
	s_cselect_b32 s28, s48, s27
	s_cselect_b32 s27, s49, s52
	s_add_i32 m0, s3, 0xc000
	ds_read_b128 v[182:185], v148
	ds_read_b128 v[186:189], v148 offset:1024
	ds_read_b128 v[194:197], v148 offset:2048
	ds_read_b128 v[198:201], v148 offset:3072
	ds_read_b128 v[202:205], v148 offset:4096
	ds_read_b128 v[206:209], v148 offset:5120
	ds_read_b128 v[210:213], v148 offset:6144
	ds_read_b128 v[214:217], v148 offset:7168
	global_load_lds_dwordx4 v138, s[24:25]
	s_waitcnt vmcnt(7)
	s_waitcnt lgkmcnt(0)
	s_setprio 1
	s_barrier
	v_mfma_f32_16x16x32_bf16 v[124:127], v[150:153], v[182:185], v[124:127]
	v_mfma_f32_16x16x32_bf16 v[120:123], v[158:161], v[182:185], v[120:123]
	v_mfma_f32_16x16x32_bf16 v[108:111], v[150:153], v[194:197], v[108:111]
	v_mfma_f32_16x16x32_bf16 v[104:107], v[158:161], v[194:197], v[104:107]
	v_mfma_f32_16x16x32_bf16 v[92:95], v[150:153], v[202:205], v[92:95]
	v_mfma_f32_16x16x32_bf16 v[88:91], v[158:161], v[202:205], v[88:91]
	v_mfma_f32_16x16x32_bf16 v[76:79], v[150:153], v[210:213], v[76:79]
	v_mfma_f32_16x16x32_bf16 v[72:75], v[158:161], v[210:213], v[72:75]
	v_mfma_f32_16x16x32_bf16 v[124:127], v[154:157], v[186:189], v[124:127]
	v_mfma_f32_16x16x32_bf16 v[120:123], v[162:165], v[186:189], v[120:123]
	v_mfma_f32_16x16x32_bf16 v[108:111], v[154:157], v[198:201], v[108:111]
	v_mfma_f32_16x16x32_bf16 v[104:107], v[162:165], v[198:201], v[104:107]
	v_mfma_f32_16x16x32_bf16 v[92:95], v[154:157], v[206:209], v[92:95]
	v_mfma_f32_16x16x32_bf16 v[88:91], v[162:165], v[206:209], v[88:91]
	v_mfma_f32_16x16x32_bf16 v[76:79], v[154:157], v[214:217], v[76:79]
	v_mfma_f32_16x16x32_bf16 v[72:75], v[162:165], v[214:217], v[72:75]
	s_add_i32 m0, s3, 0xe000
	s_nop 0
	global_load_lds_dwordx4 v140, s[24:25]
	v_mfma_f32_16x16x32_bf16 v[116:119], v[166:169], v[182:185], v[116:119]
	v_mfma_f32_16x16x32_bf16 v[112:115], v[174:177], v[182:185], v[112:115]
	v_mfma_f32_16x16x32_bf16 v[100:103], v[166:169], v[194:197], v[100:103]
	v_mfma_f32_16x16x32_bf16 v[96:99], v[174:177], v[194:197], v[96:99]
	v_mfma_f32_16x16x32_bf16 v[84:87], v[166:169], v[202:205], v[84:87]
	v_mfma_f32_16x16x32_bf16 v[80:83], v[174:177], v[202:205], v[80:83]
	v_mfma_f32_16x16x32_bf16 v[68:71], v[166:169], v[210:213], v[68:71]
	v_mfma_f32_16x16x32_bf16 v[64:67], v[174:177], v[210:213], v[64:67]
	v_mfma_f32_16x16x32_bf16 v[116:119], v[170:173], v[186:189], v[116:119]
	v_mfma_f32_16x16x32_bf16 v[112:115], v[178:181], v[186:189], v[112:115]
	v_mfma_f32_16x16x32_bf16 v[100:103], v[170:173], v[198:201], v[100:103]
	v_mfma_f32_16x16x32_bf16 v[96:99], v[178:181], v[198:201], v[96:99]
	v_mfma_f32_16x16x32_bf16 v[84:87], v[170:173], v[206:209], v[84:87]
	v_mfma_f32_16x16x32_bf16 v[80:83], v[178:181], v[206:209], v[80:83]
	v_mfma_f32_16x16x32_bf16 v[68:71], v[170:173], v[214:217], v[68:71]
	v_mfma_f32_16x16x32_bf16 v[64:67], v[178:181], v[214:217], v[64:67]
	s_barrier
	s_setprio 0
	s_add_u32 s98, s26, s12
	s_addc_u32 s99, s27, s13
	s_add_u32 s100, s28, s12
	s_addc_u32 s101, s29, s13
	s_add_i32 s54, s43, s34
	s_mov_b32 m0, s54
	ds_read_b128 v[182:185], v148 offset:16384
	ds_read_b128 v[186:189], v148 offset:17408
	ds_read_b128 v[194:197], v148 offset:18432
	ds_read_b128 v[198:201], v148 offset:19456
	ds_read_b128 v[202:205], v148 offset:20480
	ds_read_b128 v[206:209], v148 offset:21504
	ds_read_b128 v[210:213], v148 offset:22528
	ds_read_b128 v[214:217], v148 offset:23552
	global_load_lds_dwordx4 v132, s[26:27]
	s_add_i32 m0, s54, 0x2000
	s_add_u32 s54, s26, 0x20000
	s_addc_u32 s55, s27, 0
	s_add_i32 s56, s44, s34
	global_load_lds_dwordx4 v128, s[26:27]
	s_mov_b32 m0, s56
	s_nop 0
	global_load_lds_dwordx4 v132, s[54:55]
	s_waitcnt vmcnt(5)
	s_waitcnt lgkmcnt(0)
	s_setprio 1
	s_barrier
	v_mfma_f32_16x16x32_bf16 v[60:63], v[150:153], v[182:185], v[60:63]
	v_mfma_f32_16x16x32_bf16 v[56:59], v[158:161], v[182:185], v[56:59]
	v_mfma_f32_16x16x32_bf16 v[44:47], v[150:153], v[194:197], v[44:47]
	v_mfma_f32_16x16x32_bf16 v[40:43], v[158:161], v[194:197], v[40:43]
	v_mfma_f32_16x16x32_bf16 v[28:31], v[150:153], v[202:205], v[28:31]
	v_mfma_f32_16x16x32_bf16 v[24:27], v[158:161], v[202:205], v[24:27]
	v_mfma_f32_16x16x32_bf16 v[12:15], v[150:153], v[210:213], v[12:15]
	v_mfma_f32_16x16x32_bf16 v[8:11], v[158:161], v[210:213], v[8:11]
	v_mfma_f32_16x16x32_bf16 v[60:63], v[154:157], v[186:189], v[60:63]
	v_mfma_f32_16x16x32_bf16 v[56:59], v[162:165], v[186:189], v[56:59]
	v_mfma_f32_16x16x32_bf16 v[44:47], v[154:157], v[198:201], v[44:47]
	v_mfma_f32_16x16x32_bf16 v[40:43], v[162:165], v[198:201], v[40:43]
	v_mfma_f32_16x16x32_bf16 v[28:31], v[154:157], v[206:209], v[28:31]
	v_mfma_f32_16x16x32_bf16 v[24:27], v[162:165], v[206:209], v[24:27]
	v_mfma_f32_16x16x32_bf16 v[12:15], v[154:157], v[214:217], v[12:15]
	v_mfma_f32_16x16x32_bf16 v[8:11], v[162:165], v[214:217], v[8:11]
	s_add_i32 m0, s56, 0x2000
	s_nop 0
	global_load_lds_dwordx4 v128, s[54:55]
	v_mfma_f32_16x16x32_bf16 v[52:55], v[166:169], v[182:185], v[52:55]
	v_mfma_f32_16x16x32_bf16 v[48:51], v[174:177], v[182:185], v[48:51]
	v_mfma_f32_16x16x32_bf16 v[36:39], v[166:169], v[194:197], v[36:39]
	v_mfma_f32_16x16x32_bf16 v[32:35], v[174:177], v[194:197], v[32:35]
	v_mfma_f32_16x16x32_bf16 v[20:23], v[166:169], v[202:205], v[20:23]
	v_mfma_f32_16x16x32_bf16 v[16:19], v[174:177], v[202:205], v[16:19]
	v_mfma_f32_16x16x32_bf16 v[4:7], v[166:169], v[210:213], v[4:7]
	v_mfma_f32_16x16x32_bf16 v[0:3], v[174:177], v[210:213], v[0:3]
	v_mfma_f32_16x16x32_bf16 v[52:55], v[170:173], v[186:189], v[52:55]
	v_mfma_f32_16x16x32_bf16 v[48:51], v[178:181], v[186:189], v[48:51]
	v_mfma_f32_16x16x32_bf16 v[36:39], v[170:173], v[198:201], v[36:39]
	v_mfma_f32_16x16x32_bf16 v[32:35], v[178:181], v[198:201], v[32:35]
	v_mfma_f32_16x16x32_bf16 v[20:23], v[170:173], v[206:209], v[20:23]
	v_mfma_f32_16x16x32_bf16 v[16:19], v[178:181], v[206:209], v[16:19]
	v_mfma_f32_16x16x32_bf16 v[4:7], v[170:173], v[214:217], v[4:7]
	v_mfma_f32_16x16x32_bf16 v[0:3], v[178:181], v[214:217], v[0:3]
	s_barrier
; #define PG8_STAGE(bufoff, gbase, voff) do { _Pragma("unroll") for (int _i = 0; _i < 2; ++_i) \
;         __builtin_amdgcn_global_load_lds((const unsigned*)((const char*)(gbase) + (voff)[_i]), (LAS unsigned*)(lds + (bufoff) + ldsw + _i * 8192), 16, 0, ((voff) == voffA ? AUXA : 0)); } while (0)
; #define PG8_LDA(dst, b, h) do { _Pragma("unroll") for (int m = 0; m < 4; ++m) _Pragma("unroll") for (int k = 0; k < 2; ++k) dst[m][k] = *(const LAS bf16x8*)(lds + PG8_SA(b, h) + aoff + m * 2048 + k * 1024); } while (0)
; #define PG8_LDB(dst, b, h) do { _Pragma("unroll") for (int n = 0; n < 2; ++n) _Pragma("unroll") for (int k = 0; k < 2; ++k) dst[n][k] = *(const LAS bf16x8*)(lds + PG8_SB(b, h) + boff + n * 2048 + k * 1024); } while (0)
; #define PG8_MMA(ai, bj, At, Bt) do { __builtin_amdgcn_s_setprio(1); _Pragma("unroll") for (int m = 0; m < 4; ++m) _Pragma("unroll") for (int n = 0; n < 2; ++n) _Pragma("unroll") for (int k = 0; k < 2; ++k) \
;         acc[ai][bj][m][n] = __builtin_amdgcn_mfma_f32_16x16x32_bf16(Bt[n][k], At[m][k], acc[ai][bj][m][n], 0, 0, 0); __builtin_amdgcn_s_setprio(0); } while (0)
; #define PG8_WAIT_V(n) asm volatile("s_waitcnt vmcnt(" #n ")" ::: "memory")
; #define PG8_WAIT_L(n) asm volatile("s_waitcnt lgkmcnt(" #n ")" ::: "memory")
; #define PG8_BAR __builtin_amdgcn_s_barrier()
; #define PG8_SCHED __builtin_amdgcn_sched_barrier(0)
;     ...
;             PG8_LDB(B0, 1, 0); PG8_LDB(B1, 1, 1); PG8_SCHED; PG8_LDA(At, 1, 0); PG8_STAGE(PG8_SA(0, 1), a2 + hsA, voffA);
;             PG8_WAIT_V(8); PG8_WAIT_L(0); PG8_BAR; PG8_MMA(0, 0, At, B0); PG8_MMA(0, 1, At, B1); PG8_BAR; PG8_SCHED;
;             PG8_LDA(At, 1, 1); PG8_STAGE(PG8_SB(1, 0), b3, voffB); PG8_STAGE(PG8_SB(1, 1), b3 + hsB, voffB); PG8_STAGE(PG8_SA(1, 0), a3, voffA);
;             PG8_WAIT_V(8); PG8_WAIT_L(0); PG8_BAR; PG8_MMA(1, 0, At, B0); PG8_MMA(1, 1, At, B1); PG8_BAR; PG8_SCHED;
;         }
	s_mov_b32 m0, s3
	s_nop 0
	global_load_lds_dwordx4 v134, s[28:29]
	s_mov_b32 m0, s35
	s_nop 0
	global_load_lds_dwordx4 v130, s[28:29]
	s_setprio 0
	s_add_i32 s54, 0, 0x18000
	v_add_u32_e32 v149, s54, v143
	s_add_i32 s55, 0, 0x1c000
	ds_read_b128 v[150:153], v149
	ds_read_b128 v[154:157], v149 offset:1024
	ds_read_b128 v[158:161], v149 offset:2048
	ds_read_b128 v[162:165], v149 offset:3072
	v_add_u32_e32 v149, s55, v143
	ds_read_b128 v[166:169], v149
	ds_read_b128 v[170:173], v149 offset:1024
	ds_read_b128 v[174:177], v149 offset:2048
	ds_read_b128 v[178:181], v149 offset:3072
	s_add_u32 s28, s28, 0x20000
	s_addc_u32 s29, s29, 0
	s_mov_b32 m0, s36
	ds_read_b128 v[182:185], v148 offset:32768
	ds_read_b128 v[186:189], v148 offset:33792
	ds_read_b128 v[194:197], v148 offset:34816
	ds_read_b128 v[198:201], v148 offset:35840
	ds_read_b128 v[202:205], v148 offset:36864
	ds_read_b128 v[206:209], v148 offset:37888
	ds_read_b128 v[210:213], v148 offset:38912
	ds_read_b128 v[214:217], v148 offset:39936
	global_load_lds_dwordx4 v134, s[28:29]
	s_waitcnt vmcnt(7)
	s_waitcnt lgkmcnt(0)
	s_setprio 1
	s_barrier
	v_mfma_f32_16x16x32_bf16 v[124:127], v[150:153], v[182:185], v[124:127]
	v_mfma_f32_16x16x32_bf16 v[120:123], v[158:161], v[182:185], v[120:123]
	v_mfma_f32_16x16x32_bf16 v[108:111], v[150:153], v[194:197], v[108:111]
	v_mfma_f32_16x16x32_bf16 v[104:107], v[158:161], v[194:197], v[104:107]
	v_mfma_f32_16x16x32_bf16 v[92:95], v[150:153], v[202:205], v[92:95]
	v_mfma_f32_16x16x32_bf16 v[88:91], v[158:161], v[202:205], v[88:91]
	v_mfma_f32_16x16x32_bf16 v[76:79], v[150:153], v[210:213], v[76:79]
	v_mfma_f32_16x16x32_bf16 v[72:75], v[158:161], v[210:213], v[72:75]
	v_mfma_f32_16x16x32_bf16 v[124:127], v[154:157], v[186:189], v[124:127]
	v_mfma_f32_16x16x32_bf16 v[120:123], v[162:165], v[186:189], v[120:123]
	v_mfma_f32_16x16x32_bf16 v[108:111], v[154:157], v[198:201], v[108:111]
	v_mfma_f32_16x16x32_bf16 v[104:107], v[162:165], v[198:201], v[104:107]
	v_mfma_f32_16x16x32_bf16 v[92:95], v[154:157], v[206:209], v[92:95]
	v_mfma_f32_16x16x32_bf16 v[88:91], v[162:165], v[206:209], v[88:91]
	v_mfma_f32_16x16x32_bf16 v[76:79], v[154:157], v[214:217], v[76:79]
	v_mfma_f32_16x16x32_bf16 v[72:75], v[162:165], v[214:217], v[72:75]
	s_mov_b32 m0, s37
	s_nop 0
	global_load_lds_dwordx4 v130, s[28:29]
	v_mfma_f32_16x16x32_bf16 v[116:119], v[166:169], v[182:185], v[116:119]
	v_mfma_f32_16x16x32_bf16 v[112:115], v[174:177], v[182:185], v[112:115]
	v_mfma_f32_16x16x32_bf16 v[100:103], v[166:169], v[194:197], v[100:103]
	v_mfma_f32_16x16x32_bf16 v[96:99], v[174:177], v[194:197], v[96:99]
	v_mfma_f32_16x16x32_bf16 v[84:87], v[166:169], v[202:205], v[84:87]
	v_mfma_f32_16x16x32_bf16 v[80:83], v[174:177], v[202:205], v[80:83]
	v_mfma_f32_16x16x32_bf16 v[68:71], v[166:169], v[210:213], v[68:71]
	v_mfma_f32_16x16x32_bf16 v[64:67], v[174:177], v[210:213], v[64:67]
	v_mfma_f32_16x16x32_bf16 v[116:119], v[170:173], v[186:189], v[116:119]
	v_mfma_f32_16x16x32_bf16 v[112:115], v[178:181], v[186:189], v[112:115]
	v_mfma_f32_16x16x32_bf16 v[100:103], v[170:173], v[198:201], v[100:103]
	v_mfma_f32_16x16x32_bf16 v[96:99], v[178:181], v[198:201], v[96:99]
	v_mfma_f32_16x16x32_bf16 v[84:87], v[170:173], v[206:209], v[84:87]
	v_mfma_f32_16x16x32_bf16 v[80:83], v[178:181], v[206:209], v[80:83]
	v_mfma_f32_16x16x32_bf16 v[68:71], v[170:173], v[214:217], v[68:71]
	v_mfma_f32_16x16x32_bf16 v[64:67], v[178:181], v[214:217], v[64:67]
	s_barrier
	s_setprio 0
	s_add_i32 s28, s54, s34
	s_mov_b32 m0, s28
	ds_read_b128 v[182:185], v148 offset:49152
	ds_read_b128 v[186:189], v148 offset:50176
	ds_read_b128 v[194:197], v148 offset:51200
	ds_read_b128 v[198:201], v148 offset:52224
	ds_read_b128 v[202:205], v148 offset:53248
	ds_read_b128 v[206:209], v148 offset:54272
	ds_read_b128 v[210:213], v148 offset:55296
	ds_read_b128 v[214:217], v148 offset:56320
	global_load_lds_dwordx4 v132, s[98:99]
	s_add_i32 m0, s28, 0x2000
	s_add_u32 s26, s26, 0x20080
	s_addc_u32 s27, s27, 0
	s_add_i32 s28, s55, s34
	global_load_lds_dwordx4 v128, s[98:99]
	s_mov_b32 m0, s28
	s_nop 0
	global_load_lds_dwordx4 v132, s[26:27]
	s_waitcnt vmcnt(5)
	s_waitcnt lgkmcnt(0)
	s_setprio 1
	s_barrier
	v_mfma_f32_16x16x32_bf16 v[60:63], v[150:153], v[182:185], v[60:63]
	v_mfma_f32_16x16x32_bf16 v[56:59], v[158:161], v[182:185], v[56:59]
	v_mfma_f32_16x16x32_bf16 v[44:47], v[150:153], v[194:197], v[44:47]
	v_mfma_f32_16x16x32_bf16 v[40:43], v[158:161], v[194:197], v[40:43]
	v_mfma_f32_16x16x32_bf16 v[28:31], v[150:153], v[202:205], v[28:31]
	v_mfma_f32_16x16x32_bf16 v[24:27], v[158:161], v[202:205], v[24:27]
	v_mfma_f32_16x16x32_bf16 v[12:15], v[150:153], v[210:213], v[12:15]
	v_mfma_f32_16x16x32_bf16 v[8:11], v[158:161], v[210:213], v[8:11]
	v_mfma_f32_16x16x32_bf16 v[60:63], v[154:157], v[186:189], v[60:63]
	v_mfma_f32_16x16x32_bf16 v[56:59], v[162:165], v[186:189], v[56:59]
	v_mfma_f32_16x16x32_bf16 v[44:47], v[154:157], v[198:201], v[44:47]
	v_mfma_f32_16x16x32_bf16 v[40:43], v[162:165], v[198:201], v[40:43]
	v_mfma_f32_16x16x32_bf16 v[28:31], v[154:157], v[206:209], v[28:31]
	v_mfma_f32_16x16x32_bf16 v[24:27], v[162:165], v[206:209], v[24:27]
	v_mfma_f32_16x16x32_bf16 v[12:15], v[154:157], v[214:217], v[12:15]
	v_mfma_f32_16x16x32_bf16 v[8:11], v[162:165], v[214:217], v[8:11]
	s_add_i32 m0, s28, 0x2000
	s_nop 0
	global_load_lds_dwordx4 v128, s[26:27]
	v_mfma_f32_16x16x32_bf16 v[52:55], v[166:169], v[182:185], v[52:55]
	v_mfma_f32_16x16x32_bf16 v[48:51], v[174:177], v[182:185], v[48:51]
	v_mfma_f32_16x16x32_bf16 v[36:39], v[166:169], v[194:197], v[36:39]
	v_mfma_f32_16x16x32_bf16 v[32:35], v[174:177], v[194:197], v[32:35]
	v_mfma_f32_16x16x32_bf16 v[20:23], v[166:169], v[202:205], v[20:23]
	v_mfma_f32_16x16x32_bf16 v[16:19], v[174:177], v[202:205], v[16:19]
	v_mfma_f32_16x16x32_bf16 v[4:7], v[166:169], v[210:213], v[4:7]
	v_mfma_f32_16x16x32_bf16 v[0:3], v[174:177], v[210:213], v[0:3]
	v_mfma_f32_16x16x32_bf16 v[52:55], v[170:173], v[186:189], v[52:55]
	v_mfma_f32_16x16x32_bf16 v[48:51], v[178:181], v[186:189], v[48:51]
	v_mfma_f32_16x16x32_bf16 v[36:39], v[170:173], v[198:201], v[36:39]
	v_mfma_f32_16x16x32_bf16 v[32:35], v[178:181], v[198:201], v[32:35]
	v_mfma_f32_16x16x32_bf16 v[20:23], v[170:173], v[206:209], v[20:23]
	v_mfma_f32_16x16x32_bf16 v[16:19], v[178:181], v[206:209], v[16:19]
	v_mfma_f32_16x16x32_bf16 v[4:7], v[170:173], v[214:217], v[4:7]
	v_mfma_f32_16x16x32_bf16 v[0:3], v[178:181], v[214:217], v[0:3]
	s_barrier
	s_setprio 0
	s_add_u32 s24, s24, 0x100
	s_addc_u32 s25, s25, 0
	s_add_u32 s51, s51, 0x100
	s_addc_u32 s52, s52, 0
	s_cmp_ge_i32 s53, s39
	s_mov_b32 s26, s53
	s_cbranch_scc0 .LBB0_887

; #define PG8_STAGE(bufoff, gbase, voff) do { _Pragma("unroll") for (int _i = 0; _i < 2; ++_i) \
;         __builtin_amdgcn_global_load_lds((const unsigned*)((const char*)(gbase) + (voff)[_i]), (LAS unsigned*)(lds + (bufoff) + ldsw + _i * 8192), 16, 0, ((voff) == voffA ? AUXA : 0)); } while (0)
; #define PG8_LDA(dst, b, h) do { _Pragma("unroll") for (int m = 0; m < 4; ++m) _Pragma("unroll") for (int k = 0; k < 2; ++k) dst[m][k] = *(const LAS bf16x8*)(lds + PG8_SA(b, h) + aoff + m * 2048 + k * 1024); } while (0)
; #define PG8_LDB(dst, b, h) do { _Pragma("unroll") for (int n = 0; n < 2; ++n) _Pragma("unroll") for (int k = 0; k < 2; ++k) dst[n][k] = *(const LAS bf16x8*)(lds + PG8_SB(b, h) + boff + n * 2048 + k * 1024); } while (0)
; #define PG8_MMA(ai, bj, At, Bt) do { __builtin_amdgcn_s_setprio(1); _Pragma("unroll") for (int m = 0; m < 4; ++m) _Pragma("unroll") for (int n = 0; n < 2; ++n) _Pragma("unroll") for (int k = 0; k < 2; ++k) \
;         acc[ai][bj][m][n] = __builtin_amdgcn_mfma_f32_16x16x32_bf16(Bt[n][k], At[m][k], acc[ai][bj][m][n], 0, 0, 0); __builtin_amdgcn_s_setprio(0); } while (0)
; #define PG8_WAIT_V(n) asm volatile("s_waitcnt vmcnt(" #n ")" ::: "memory")
; #define PG8_WAIT_L(n) asm volatile("s_waitcnt lgkmcnt(" #n ")" ::: "memory")
; #define PG8_BAR __builtin_amdgcn_s_barrier()
; #define PG8_SCHED __builtin_amdgcn_sched_barrier(0)
;     ...
;             const bool last = (t == nt - 2);
;             const char* a1 = cA + (size_t)(t + 1) * kstep;
;             const char* a2 = last ? nA : cA + (size_t)(t + 2) * kstep; const char* b2 = last ? nB : cB + (size_t)(t + 2) * kstep;
;             const char* a3 = a2 + kstep; const char* b3 = b2 + kstep;
;             PG8_LDB(B0, 0, 0); PG8_LDB(B1, 0, 1); PG8_SCHED; PG8_LDA(At, 0, 0); PG8_STAGE(PG8_SA(1, 1), a1 + hsA, voffA);
;             if (Epi::NPRE != 0 && last) { E.pre(sv, cur, wr, fr); PG8_WAIT_V(16); } else { PG8_WAIT_V(8); }
;             PG8_WAIT_L(0); PG8_BAR; PG8_MMA(0, 0, At, B0); PG8_MMA(0, 1, At, B1); PG8_BAR; PG8_SCHED;
;             PG8_LDA(At, 0, 1); PG8_STAGE(PG8_SB(0, 0), b2, voffB); PG8_STAGE(PG8_SB(0, 1), b2 + hsB, voffB); PG8_STAGE(PG8_SA(0, 0), a2, voffA);
;             if (Epi::NPRE != 0 && last) { PG8_WAIT_V(16); } else { PG8_WAIT_V(8); }
;             PG8_WAIT_L(0); PG8_BAR; PG8_MMA(1, 0, At, B0); PG8_MMA(1, 1, At, B1); PG8_BAR; PG8_SCHED;
.LBB0_959:
	s_add_u32 s98, s28, 0xfffc0000
	s_addc_u32 s99, s29, -1
	s_mov_b32 m0, s40
	s_nop 0
	global_load_lds_dwordx4 v170, s[98:99]
	s_mov_b32 m0, s41
	s_nop 0
	global_load_lds_dwordx4 v166, s[98:99]
	ds_read_b128 v[88:91], v196
	ds_read_b128 v[92:95], v196 offset:1024
	ds_read_b128 v[104:107], v196 offset:2048
	ds_read_b128 v[108:111], v196 offset:3072
	ds_read_b128 v[144:147], v197
	ds_read_b128 v[148:151], v197 offset:1024
	ds_read_b128 v[152:155], v197 offset:2048
	ds_read_b128 v[156:159], v197 offset:3072
	s_add_i32 s51, s30, 2
	s_add_u32 s31, s28, 0xfffc0080
	s_addc_u32 s34, s29, -1
	s_cmp_eq_u32 s42, s30
	s_cselect_b32 s30, s48, s49
	s_cselect_b32 s35, s19, s34
	s_cselect_b32 s34, s21, s31
	s_cselect_b32 s31, s47, s50
	s_add_i32 m0, s5, 0xc000
	ds_read_b128 v[160:163], v198
	ds_read_b128 v[180:183], v198 offset:1024
	ds_read_b128 v[184:187], v198 offset:2048
	ds_read_b128 v[188:191], v198 offset:3072
	ds_read_b128 v[200:203], v198 offset:4096
	ds_read_b128 v[204:207], v198 offset:5120
	ds_read_b128 v[208:211], v198 offset:6144
	ds_read_b128 v[212:215], v198 offset:7168
	global_load_lds_dwordx4 v172, s[28:29]
	s_waitcnt vmcnt(7)
	s_waitcnt lgkmcnt(0)
	s_setprio 1
	s_barrier
	v_mfma_f32_16x16x32_bf16 v[136:139], v[88:91], v[160:163], v[136:139]
	v_mfma_f32_16x16x32_bf16 v[140:143], v[104:107], v[160:163], v[140:143]
	v_mfma_f32_16x16x32_bf16 v[124:127], v[88:91], v[184:187], v[124:127]
	v_mfma_f32_16x16x32_bf16 v[120:123], v[104:107], v[184:187], v[120:123]
	v_mfma_f32_16x16x32_bf16 v[100:103], v[88:91], v[200:203], v[100:103]
	v_mfma_f32_16x16x32_bf16 v[96:99], v[104:107], v[200:203], v[96:99]
	v_mfma_f32_16x16x32_bf16 v[76:79], v[88:91], v[208:211], v[76:79]
	v_mfma_f32_16x16x32_bf16 v[72:75], v[104:107], v[208:211], v[72:75]
	v_mfma_f32_16x16x32_bf16 v[136:139], v[92:95], v[180:183], v[136:139]
	v_mfma_f32_16x16x32_bf16 v[140:143], v[108:111], v[180:183], v[140:143]
	v_mfma_f32_16x16x32_bf16 v[124:127], v[92:95], v[188:191], v[124:127]
	v_mfma_f32_16x16x32_bf16 v[120:123], v[108:111], v[188:191], v[120:123]
	v_mfma_f32_16x16x32_bf16 v[100:103], v[92:95], v[204:207], v[100:103]
	v_mfma_f32_16x16x32_bf16 v[96:99], v[108:111], v[204:207], v[96:99]
	v_mfma_f32_16x16x32_bf16 v[76:79], v[92:95], v[212:215], v[76:79]
	v_mfma_f32_16x16x32_bf16 v[72:75], v[108:111], v[212:215], v[72:75]
	s_add_i32 m0, s5, 0xe000
	s_nop 0
	global_load_lds_dwordx4 v174, s[28:29]
	v_mfma_f32_16x16x32_bf16 v[132:135], v[144:147], v[160:163], v[132:135]
	v_mfma_f32_16x16x32_bf16 v[128:131], v[152:155], v[160:163], v[128:131]
	v_mfma_f32_16x16x32_bf16 v[116:119], v[144:147], v[184:187], v[116:119]
	v_mfma_f32_16x16x32_bf16 v[112:115], v[152:155], v[184:187], v[112:115]
	v_mfma_f32_16x16x32_bf16 v[84:87], v[144:147], v[200:203], v[84:87]
	v_mfma_f32_16x16x32_bf16 v[80:83], v[152:155], v[200:203], v[80:83]
	v_mfma_f32_16x16x32_bf16 v[68:71], v[144:147], v[208:211], v[68:71]
	v_mfma_f32_16x16x32_bf16 v[64:67], v[152:155], v[208:211], v[64:67]
	v_mfma_f32_16x16x32_bf16 v[132:135], v[148:151], v[180:183], v[132:135]
	v_mfma_f32_16x16x32_bf16 v[128:131], v[156:159], v[180:183], v[128:131]
	v_mfma_f32_16x16x32_bf16 v[116:119], v[148:151], v[188:191], v[116:119]
	v_mfma_f32_16x16x32_bf16 v[112:115], v[156:159], v[188:191], v[112:115]
	v_mfma_f32_16x16x32_bf16 v[84:87], v[148:151], v[204:207], v[84:87]
	v_mfma_f32_16x16x32_bf16 v[80:83], v[156:159], v[204:207], v[80:83]
	v_mfma_f32_16x16x32_bf16 v[68:71], v[148:151], v[212:215], v[68:71]
	v_mfma_f32_16x16x32_bf16 v[64:67], v[156:159], v[212:215], v[64:67]
	s_barrier
	s_setprio 0
	s_add_u32 s98, s30, s12
	s_addc_u32 s99, s31, s13
	s_add_u32 s100, s34, s12
	s_addc_u32 s101, s35, s13
	s_add_i32 s52, s44, s3
	s_mov_b32 m0, s52
	ds_read_b128 v[160:163], v198 offset:16384
	ds_read_b128 v[180:183], v198 offset:17408
	ds_read_b128 v[184:187], v198 offset:18432
	ds_read_b128 v[188:191], v198 offset:19456
	ds_read_b128 v[200:203], v198 offset:20480
	ds_read_b128 v[204:207], v198 offset:21504
	ds_read_b128 v[208:211], v198 offset:22528
	ds_read_b128 v[212:215], v198 offset:23552
	global_load_lds_dwordx4 v168, s[30:31]
	s_add_i32 m0, s52, 0x2000
	s_add_u32 s52, s30, 0x40000
	s_addc_u32 s53, s31, 0
	s_add_i32 s54, s45, s3
	global_load_lds_dwordx4 v164, s[30:31]
	s_mov_b32 m0, s54
	s_nop 0
	global_load_lds_dwordx4 v168, s[52:53]
	s_waitcnt vmcnt(5)
	s_waitcnt lgkmcnt(0)
	s_setprio 1
	s_barrier
	v_mfma_f32_16x16x32_bf16 v[60:63], v[88:91], v[160:163], v[60:63]
	v_mfma_f32_16x16x32_bf16 v[56:59], v[104:107], v[160:163], v[56:59]
	v_mfma_f32_16x16x32_bf16 v[44:47], v[88:91], v[184:187], v[44:47]
	v_mfma_f32_16x16x32_bf16 v[40:43], v[104:107], v[184:187], v[40:43]
	v_mfma_f32_16x16x32_bf16 v[28:31], v[88:91], v[200:203], v[28:31]
	v_mfma_f32_16x16x32_bf16 v[24:27], v[104:107], v[200:203], v[24:27]
	v_mfma_f32_16x16x32_bf16 v[12:15], v[88:91], v[208:211], v[12:15]
	v_mfma_f32_16x16x32_bf16 v[8:11], v[104:107], v[208:211], v[8:11]
	v_mfma_f32_16x16x32_bf16 v[60:63], v[92:95], v[180:183], v[60:63]
	v_mfma_f32_16x16x32_bf16 v[56:59], v[108:111], v[180:183], v[56:59]
	v_mfma_f32_16x16x32_bf16 v[44:47], v[92:95], v[188:191], v[44:47]
	v_mfma_f32_16x16x32_bf16 v[40:43], v[108:111], v[188:191], v[40:43]
	v_mfma_f32_16x16x32_bf16 v[28:31], v[92:95], v[204:207], v[28:31]
	v_mfma_f32_16x16x32_bf16 v[24:27], v[108:111], v[204:207], v[24:27]
	v_mfma_f32_16x16x32_bf16 v[12:15], v[92:95], v[212:215], v[12:15]
	v_mfma_f32_16x16x32_bf16 v[8:11], v[108:111], v[212:215], v[8:11]
	s_add_i32 m0, s54, 0x2000
	s_nop 0
	global_load_lds_dwordx4 v164, s[52:53]
	v_mfma_f32_16x16x32_bf16 v[52:55], v[144:147], v[160:163], v[52:55]
	v_mfma_f32_16x16x32_bf16 v[48:51], v[152:155], v[160:163], v[48:51]
	v_mfma_f32_16x16x32_bf16 v[36:39], v[144:147], v[184:187], v[36:39]
	v_mfma_f32_16x16x32_bf16 v[32:35], v[152:155], v[184:187], v[32:35]
	v_mfma_f32_16x16x32_bf16 v[20:23], v[144:147], v[200:203], v[20:23]
	v_mfma_f32_16x16x32_bf16 v[16:19], v[152:155], v[200:203], v[16:19]
	v_mfma_f32_16x16x32_bf16 v[4:7], v[144:147], v[208:211], v[4:7]
	v_mfma_f32_16x16x32_bf16 v[0:3], v[152:155], v[208:211], v[0:3]
	v_mfma_f32_16x16x32_bf16 v[52:55], v[148:151], v[180:183], v[52:55]
	v_mfma_f32_16x16x32_bf16 v[48:51], v[156:159], v[180:183], v[48:51]
	v_mfma_f32_16x16x32_bf16 v[36:39], v[148:151], v[188:191], v[36:39]
	v_mfma_f32_16x16x32_bf16 v[32:35], v[156:159], v[188:191], v[32:35]
	v_mfma_f32_16x16x32_bf16 v[20:23], v[148:151], v[204:207], v[20:23]
	v_mfma_f32_16x16x32_bf16 v[16:19], v[156:159], v[204:207], v[16:19]
	v_mfma_f32_16x16x32_bf16 v[4:7], v[148:151], v[212:215], v[4:7]
	v_mfma_f32_16x16x32_bf16 v[0:3], v[156:159], v[212:215], v[0:3]
	s_barrier
; #define PG8_STAGE(bufoff, gbase, voff) do { _Pragma("unroll") for (int _i = 0; _i < 2; ++_i) \
;         __builtin_amdgcn_global_load_lds((const unsigned*)((const char*)(gbase) + (voff)[_i]), (LAS unsigned*)(lds + (bufoff) + ldsw + _i * 8192), 16, 0, ((voff) == voffA ? AUXA : 0)); } while (0)
; #define PG8_LDA(dst, b, h) do { _Pragma("unroll") for (int m = 0; m < 4; ++m) _Pragma("unroll") for (int k = 0; k < 2; ++k) dst[m][k] = *(const LAS bf16x8*)(lds + PG8_SA(b, h) + aoff + m * 2048 + k * 1024); } while (0)
; #define PG8_LDB(dst, b, h) do { _Pragma("unroll") for (int n = 0; n < 2; ++n) _Pragma("unroll") for (int k = 0; k < 2; ++k) dst[n][k] = *(const LAS bf16x8*)(lds + PG8_SB(b, h) + boff + n * 2048 + k * 1024); } while (0)
; #define PG8_MMA(ai, bj, At, Bt) do { __builtin_amdgcn_s_setprio(1); _Pragma("unroll") for (int m = 0; m < 4; ++m) _Pragma("unroll") for (int n = 0; n < 2; ++n) _Pragma("unroll") for (int k = 0; k < 2; ++k) \
;         acc[ai][bj][m][n] = __builtin_amdgcn_mfma_f32_16x16x32_bf16(Bt[n][k], At[m][k], acc[ai][bj][m][n], 0, 0, 0); __builtin_amdgcn_s_setprio(0); } while (0)
; #define PG8_WAIT_V(n) asm volatile("s_waitcnt vmcnt(" #n ")" ::: "memory")
; #define PG8_WAIT_L(n) asm volatile("s_waitcnt lgkmcnt(" #n ")" ::: "memory")
; #define PG8_BAR __builtin_amdgcn_s_barrier()
; #define PG8_SCHED __builtin_amdgcn_sched_barrier(0)
;     ...
;             PG8_LDB(B0, 1, 0); PG8_LDB(B1, 1, 1); PG8_SCHED; PG8_LDA(At, 1, 0); PG8_STAGE(PG8_SA(0, 1), a2 + hsA, voffA);
;             PG8_WAIT_V(8); PG8_WAIT_L(0); PG8_BAR; PG8_MMA(0, 0, At, B0); PG8_MMA(0, 1, At, B1); PG8_BAR; PG8_SCHED;
;             PG8_LDA(At, 1, 1); PG8_STAGE(PG8_SB(1, 0), b3, voffB); PG8_STAGE(PG8_SB(1, 1), b3 + hsB, voffB); PG8_STAGE(PG8_SA(1, 0), a3, voffA);
;             PG8_WAIT_V(8); PG8_WAIT_L(0); PG8_BAR; PG8_MMA(1, 0, At, B0); PG8_MMA(1, 1, At, B1); PG8_BAR; PG8_SCHED;
;         }
	s_mov_b32 m0, s5
	s_nop 0
	global_load_lds_dwordx4 v170, s[34:35]
	s_mov_b32 m0, s27
	s_nop 0
	global_load_lds_dwordx4 v166, s[34:35]
	s_setprio 0
	s_add_i32 s52, 0, 0x18000
	s_add_i32 s53, 0, 0x1c000
	v_add_u32_e32 v108, s52, v194
	v_add_u32_e32 v156, s53, v194
	ds_read_b128 v[88:91], v108
	ds_read_b128 v[92:95], v108 offset:1024
	ds_read_b128 v[104:107], v108 offset:2048
	ds_read_b128 v[108:111], v108 offset:3072
	ds_read_b128 v[144:147], v156
	ds_read_b128 v[148:151], v156 offset:1024
	ds_read_b128 v[152:155], v156 offset:2048
	ds_read_b128 v[156:159], v156 offset:3072
	s_add_u32 s34, s34, 0x40000
	s_addc_u32 s35, s35, 0
	s_mov_b32 m0, s36
	ds_read_b128 v[160:163], v198 offset:32768
	ds_read_b128 v[180:183], v198 offset:33792
	ds_read_b128 v[184:187], v198 offset:34816
	ds_read_b128 v[188:191], v198 offset:35840
	ds_read_b128 v[200:203], v198 offset:36864
	ds_read_b128 v[204:207], v198 offset:37888
	ds_read_b128 v[208:211], v198 offset:38912
	ds_read_b128 v[212:215], v198 offset:39936
	global_load_lds_dwordx4 v170, s[34:35]
	s_waitcnt vmcnt(7)
	s_waitcnt lgkmcnt(0)
	s_setprio 1
	s_barrier
	v_mfma_f32_16x16x32_bf16 v[136:139], v[88:91], v[160:163], v[136:139]
	v_mfma_f32_16x16x32_bf16 v[140:143], v[104:107], v[160:163], v[140:143]
	v_mfma_f32_16x16x32_bf16 v[124:127], v[88:91], v[184:187], v[124:127]
	v_mfma_f32_16x16x32_bf16 v[120:123], v[104:107], v[184:187], v[120:123]
	v_mfma_f32_16x16x32_bf16 v[100:103], v[88:91], v[200:203], v[100:103]
	v_mfma_f32_16x16x32_bf16 v[96:99], v[104:107], v[200:203], v[96:99]
	v_mfma_f32_16x16x32_bf16 v[76:79], v[88:91], v[208:211], v[76:79]
	v_mfma_f32_16x16x32_bf16 v[72:75], v[104:107], v[208:211], v[72:75]
	v_mfma_f32_16x16x32_bf16 v[136:139], v[92:95], v[180:183], v[136:139]
	v_mfma_f32_16x16x32_bf16 v[140:143], v[108:111], v[180:183], v[140:143]
	v_mfma_f32_16x16x32_bf16 v[124:127], v[92:95], v[188:191], v[124:127]
	v_mfma_f32_16x16x32_bf16 v[120:123], v[108:111], v[188:191], v[120:123]
	v_mfma_f32_16x16x32_bf16 v[100:103], v[92:95], v[204:207], v[100:103]
	v_mfma_f32_16x16x32_bf16 v[96:99], v[108:111], v[204:207], v[96:99]
	v_mfma_f32_16x16x32_bf16 v[76:79], v[92:95], v[212:215], v[76:79]
	v_mfma_f32_16x16x32_bf16 v[72:75], v[108:111], v[212:215], v[72:75]
	s_mov_b32 m0, s37
	s_nop 0
	global_load_lds_dwordx4 v166, s[34:35]
	v_mfma_f32_16x16x32_bf16 v[132:135], v[144:147], v[160:163], v[132:135]
	v_mfma_f32_16x16x32_bf16 v[128:131], v[152:155], v[160:163], v[128:131]
	v_mfma_f32_16x16x32_bf16 v[116:119], v[144:147], v[184:187], v[116:119]
	v_mfma_f32_16x16x32_bf16 v[112:115], v[152:155], v[184:187], v[112:115]
	v_mfma_f32_16x16x32_bf16 v[84:87], v[144:147], v[200:203], v[84:87]
	v_mfma_f32_16x16x32_bf16 v[80:83], v[152:155], v[200:203], v[80:83]
	v_mfma_f32_16x16x32_bf16 v[68:71], v[144:147], v[208:211], v[68:71]
	v_mfma_f32_16x16x32_bf16 v[64:67], v[152:155], v[208:211], v[64:67]
	v_mfma_f32_16x16x32_bf16 v[132:135], v[148:151], v[180:183], v[132:135]
	v_mfma_f32_16x16x32_bf16 v[128:131], v[156:159], v[180:183], v[128:131]
	v_mfma_f32_16x16x32_bf16 v[116:119], v[148:151], v[188:191], v[116:119]
	v_mfma_f32_16x16x32_bf16 v[112:115], v[156:159], v[188:191], v[112:115]
	v_mfma_f32_16x16x32_bf16 v[84:87], v[148:151], v[204:207], v[84:87]
	v_mfma_f32_16x16x32_bf16 v[80:83], v[156:159], v[204:207], v[80:83]
	v_mfma_f32_16x16x32_bf16 v[68:71], v[148:151], v[212:215], v[68:71]
	v_mfma_f32_16x16x32_bf16 v[64:67], v[156:159], v[212:215], v[64:67]
	s_barrier
	s_setprio 0
	s_add_i32 s34, s52, s3
	s_mov_b32 m0, s34
	ds_read_b128 v[160:163], v198 offset:49152
	ds_read_b128 v[180:183], v198 offset:50176
	ds_read_b128 v[184:187], v198 offset:51200
	ds_read_b128 v[188:191], v198 offset:52224
	ds_read_b128 v[200:203], v198 offset:53248
	ds_read_b128 v[204:207], v198 offset:54272
	ds_read_b128 v[208:211], v198 offset:55296
	ds_read_b128 v[212:215], v198 offset:56320
	global_load_lds_dwordx4 v168, s[98:99]
	s_add_i32 m0, s34, 0x2000
	s_add_u32 s30, s30, 0x40080
	s_addc_u32 s31, s31, 0
	s_add_i32 s34, s53, s3
	global_load_lds_dwordx4 v164, s[98:99]
	s_mov_b32 m0, s34
	s_nop 0
	global_load_lds_dwordx4 v168, s[30:31]
	s_waitcnt vmcnt(5)
	s_waitcnt lgkmcnt(0)
	s_setprio 1
	s_barrier
	v_mfma_f32_16x16x32_bf16 v[60:63], v[88:91], v[160:163], v[60:63]
	v_mfma_f32_16x16x32_bf16 v[56:59], v[104:107], v[160:163], v[56:59]
	v_mfma_f32_16x16x32_bf16 v[44:47], v[88:91], v[184:187], v[44:47]
	v_mfma_f32_16x16x32_bf16 v[40:43], v[104:107], v[184:187], v[40:43]
	v_mfma_f32_16x16x32_bf16 v[28:31], v[88:91], v[200:203], v[28:31]
	v_mfma_f32_16x16x32_bf16 v[24:27], v[104:107], v[200:203], v[24:27]
	v_mfma_f32_16x16x32_bf16 v[12:15], v[88:91], v[208:211], v[12:15]
	v_mfma_f32_16x16x32_bf16 v[8:11], v[104:107], v[208:211], v[8:11]
	v_mfma_f32_16x16x32_bf16 v[60:63], v[92:95], v[180:183], v[60:63]
	v_mfma_f32_16x16x32_bf16 v[56:59], v[108:111], v[180:183], v[56:59]
	v_mfma_f32_16x16x32_bf16 v[44:47], v[92:95], v[188:191], v[44:47]
	v_mfma_f32_16x16x32_bf16 v[40:43], v[108:111], v[188:191], v[40:43]
	v_mfma_f32_16x16x32_bf16 v[28:31], v[92:95], v[204:207], v[28:31]
	v_mfma_f32_16x16x32_bf16 v[24:27], v[108:111], v[204:207], v[24:27]
	v_mfma_f32_16x16x32_bf16 v[12:15], v[92:95], v[212:215], v[12:15]
	v_mfma_f32_16x16x32_bf16 v[8:11], v[108:111], v[212:215], v[8:11]
	s_add_i32 m0, s34, 0x2000
	s_nop 0
	global_load_lds_dwordx4 v164, s[30:31]
	v_mfma_f32_16x16x32_bf16 v[52:55], v[144:147], v[160:163], v[52:55]
	v_mfma_f32_16x16x32_bf16 v[48:51], v[152:155], v[160:163], v[48:51]
	v_mfma_f32_16x16x32_bf16 v[36:39], v[144:147], v[184:187], v[36:39]
	v_mfma_f32_16x16x32_bf16 v[32:35], v[152:155], v[184:187], v[32:35]
	v_mfma_f32_16x16x32_bf16 v[20:23], v[144:147], v[200:203], v[20:23]
	v_mfma_f32_16x16x32_bf16 v[16:19], v[152:155], v[200:203], v[16:19]
	v_mfma_f32_16x16x32_bf16 v[4:7], v[144:147], v[208:211], v[4:7]
	v_mfma_f32_16x16x32_bf16 v[0:3], v[152:155], v[208:211], v[0:3]
	v_mfma_f32_16x16x32_bf16 v[52:55], v[148:151], v[180:183], v[52:55]
	v_mfma_f32_16x16x32_bf16 v[48:51], v[156:159], v[180:183], v[48:51]
	v_mfma_f32_16x16x32_bf16 v[36:39], v[148:151], v[188:191], v[36:39]
	v_mfma_f32_16x16x32_bf16 v[32:35], v[156:159], v[188:191], v[32:35]
	v_mfma_f32_16x16x32_bf16 v[20:23], v[148:151], v[204:207], v[20:23]
	v_mfma_f32_16x16x32_bf16 v[16:19], v[156:159], v[204:207], v[16:19]
	v_mfma_f32_16x16x32_bf16 v[4:7], v[148:151], v[212:215], v[4:7]
	v_mfma_f32_16x16x32_bf16 v[0:3], v[156:159], v[212:215], v[0:3]
	s_barrier
	s_setprio 0
	s_add_u32 s28, s28, 0x100
	s_addc_u32 s29, s29, 0
	s_add_u32 s49, s49, 0x100
	s_addc_u32 s50, s50, 0
	s_cmp_ge_i32 s51, s39
	s_mov_b32 s30, s51
	s_cbranch_scc0 .LBB0_959

; #define PG8_STAGE(bufoff, gbase, voff) do { _Pragma("unroll") for (int _i = 0; _i < 2; ++_i) \
;         __builtin_amdgcn_global_load_lds((const unsigned*)((const char*)(gbase) + (voff)[_i]), (LAS unsigned*)(lds + (bufoff) + ldsw + _i * 8192), 16, 0, ((voff) == voffA ? AUXA : 0)); } while (0)
; #define PG8_LDA(dst, b, h) do { _Pragma("unroll") for (int m = 0; m < 4; ++m) _Pragma("unroll") for (int k = 0; k < 2; ++k) dst[m][k] = *(const LAS bf16x8*)(lds + PG8_SA(b, h) + aoff + m * 2048 + k * 1024); } while (0)
; #define PG8_LDB(dst, b, h) do { _Pragma("unroll") for (int n = 0; n < 2; ++n) _Pragma("unroll") for (int k = 0; k < 2; ++k) dst[n][k] = *(const LAS bf16x8*)(lds + PG8_SB(b, h) + boff + n * 2048 + k * 1024); } while (0)
; #define PG8_MMA(ai, bj, At, Bt) do { __builtin_amdgcn_s_setprio(1); _Pragma("unroll") for (int m = 0; m < 4; ++m) _Pragma("unroll") for (int n = 0; n < 2; ++n) _Pragma("unroll") for (int k = 0; k < 2; ++k) \
;         acc[ai][bj][m][n] = __builtin_amdgcn_mfma_f32_16x16x32_bf16(Bt[n][k], At[m][k], acc[ai][bj][m][n], 0, 0, 0); __builtin_amdgcn_s_setprio(0); } while (0)
; #define PG8_WAIT_V(n) asm volatile("s_waitcnt vmcnt(" #n ")" ::: "memory")
; #define PG8_WAIT_L(n) asm volatile("s_waitcnt lgkmcnt(" #n ")" ::: "memory")
; #define PG8_BAR __builtin_amdgcn_s_barrier()
; #define PG8_SCHED __builtin_amdgcn_sched_barrier(0)
;     ...
;             const bool last = (t == nt - 2);
;             const char* a1 = cA + (size_t)(t + 1) * kstep;
;             const char* a2 = last ? nA : cA + (size_t)(t + 2) * kstep; const char* b2 = last ? nB : cB + (size_t)(t + 2) * kstep;
;             const char* a3 = a2 + kstep; const char* b3 = b2 + kstep;
;             PG8_LDB(B0, 0, 0); PG8_LDB(B1, 0, 1); PG8_SCHED; PG8_LDA(At, 0, 0); PG8_STAGE(PG8_SA(1, 1), a1 + hsA, voffA);
;             if (Epi::NPRE != 0 && last) { E.pre(sv, cur, wr, fr); PG8_WAIT_V(16); } else { PG8_WAIT_V(8); }
;             PG8_WAIT_L(0); PG8_BAR; PG8_MMA(0, 0, At, B0); PG8_MMA(0, 1, At, B1); PG8_BAR; PG8_SCHED;
;             PG8_LDA(At, 0, 1); PG8_STAGE(PG8_SB(0, 0), b2, voffB); PG8_STAGE(PG8_SB(0, 1), b2 + hsB, voffB); PG8_STAGE(PG8_SA(0, 0), a2, voffA);
;             if (Epi::NPRE != 0 && last) { PG8_WAIT_V(16); } else { PG8_WAIT_V(8); }
;             PG8_WAIT_L(0); PG8_BAR; PG8_MMA(1, 0, At, B0); PG8_MMA(1, 1, At, B1); PG8_BAR; PG8_SCHED;
.LBB0_1040:
	s_add_u32 s98, s28, 0xfffc0000
	s_addc_u32 s99, s29, -1
	s_mov_b32 m0, s45
	s_nop 0
	global_load_lds_dwordx4 v134, s[98:99]
	s_mov_b32 m0, s46
	s_nop 0
	global_load_lds_dwordx4 v130, s[98:99]
	ds_read_b128 v[150:153], v147
	ds_read_b128 v[154:157], v147 offset:1024
	ds_read_b128 v[158:161], v147 offset:2048
	ds_read_b128 v[162:165], v147 offset:3072
	ds_read_b128 v[166:169], v148
	ds_read_b128 v[170:173], v148 offset:1024
	ds_read_b128 v[174:177], v148 offset:2048
	ds_read_b128 v[178:181], v148 offset:3072
	s_add_i32 s56, s30, 2
	s_add_u32 s31, s28, 0xfffc0080
	s_addc_u32 s34, s29, -1
	s_cmp_eq_u32 s47, s30
	s_cselect_b32 s30, s53, s54
	s_cselect_b32 s35, s21, s34
	s_cselect_b32 s34, s23, s31
	s_cselect_b32 s31, s52, s55
	s_add_i32 m0, s19, 0xc000
	ds_read_b128 v[182:185], v149
	ds_read_b128 v[186:189], v149 offset:1024
	ds_read_b128 v[190:193], v149 offset:2048
	ds_read_b128 v[194:197], v149 offset:3072
	ds_read_b128 v[198:201], v149 offset:4096
	ds_read_b128 v[202:205], v149 offset:5120
	ds_read_b128 v[206:209], v149 offset:6144
	ds_read_b128 v[210:213], v149 offset:7168
	global_load_lds_dwordx4 v136, s[28:29]
	s_waitcnt vmcnt(7)
	s_waitcnt lgkmcnt(0)
	s_setprio 1
	s_barrier
	v_mfma_f32_16x16x32_bf16 v[124:127], v[150:153], v[182:185], v[124:127]
	v_mfma_f32_16x16x32_bf16 v[120:123], v[158:161], v[182:185], v[120:123]
	v_mfma_f32_16x16x32_bf16 v[108:111], v[150:153], v[190:193], v[108:111]
	v_mfma_f32_16x16x32_bf16 v[104:107], v[158:161], v[190:193], v[104:107]
	v_mfma_f32_16x16x32_bf16 v[92:95], v[150:153], v[198:201], v[92:95]
	v_mfma_f32_16x16x32_bf16 v[88:91], v[158:161], v[198:201], v[88:91]
	v_mfma_f32_16x16x32_bf16 v[76:79], v[150:153], v[206:209], v[76:79]
	v_mfma_f32_16x16x32_bf16 v[72:75], v[158:161], v[206:209], v[72:75]
	v_mfma_f32_16x16x32_bf16 v[124:127], v[154:157], v[186:189], v[124:127]
	v_mfma_f32_16x16x32_bf16 v[120:123], v[162:165], v[186:189], v[120:123]
	v_mfma_f32_16x16x32_bf16 v[108:111], v[154:157], v[194:197], v[108:111]
	v_mfma_f32_16x16x32_bf16 v[104:107], v[162:165], v[194:197], v[104:107]
	v_mfma_f32_16x16x32_bf16 v[92:95], v[154:157], v[202:205], v[92:95]
	v_mfma_f32_16x16x32_bf16 v[88:91], v[162:165], v[202:205], v[88:91]
	v_mfma_f32_16x16x32_bf16 v[76:79], v[154:157], v[210:213], v[76:79]
	v_mfma_f32_16x16x32_bf16 v[72:75], v[162:165], v[210:213], v[72:75]
	s_add_i32 m0, s19, 0xe000
	s_nop 0
	global_load_lds_dwordx4 v138, s[28:29]
	v_mfma_f32_16x16x32_bf16 v[116:119], v[166:169], v[182:185], v[116:119]
	v_mfma_f32_16x16x32_bf16 v[112:115], v[174:177], v[182:185], v[112:115]
	v_mfma_f32_16x16x32_bf16 v[100:103], v[166:169], v[190:193], v[100:103]
	v_mfma_f32_16x16x32_bf16 v[96:99], v[174:177], v[190:193], v[96:99]
	v_mfma_f32_16x16x32_bf16 v[84:87], v[166:169], v[198:201], v[84:87]
	v_mfma_f32_16x16x32_bf16 v[80:83], v[174:177], v[198:201], v[80:83]
	v_mfma_f32_16x16x32_bf16 v[68:71], v[166:169], v[206:209], v[68:71]
	v_mfma_f32_16x16x32_bf16 v[64:67], v[174:177], v[206:209], v[64:67]
	v_mfma_f32_16x16x32_bf16 v[116:119], v[170:173], v[186:189], v[116:119]
	v_mfma_f32_16x16x32_bf16 v[112:115], v[178:181], v[186:189], v[112:115]
	v_mfma_f32_16x16x32_bf16 v[100:103], v[170:173], v[194:197], v[100:103]
	v_mfma_f32_16x16x32_bf16 v[96:99], v[178:181], v[194:197], v[96:99]
	v_mfma_f32_16x16x32_bf16 v[84:87], v[170:173], v[202:205], v[84:87]
	v_mfma_f32_16x16x32_bf16 v[80:83], v[178:181], v[202:205], v[80:83]
	v_mfma_f32_16x16x32_bf16 v[68:71], v[170:173], v[210:213], v[68:71]
	v_mfma_f32_16x16x32_bf16 v[64:67], v[178:181], v[210:213], v[64:67]
	s_barrier
	s_setprio 0
	s_add_u32 s98, s30, s14
	s_addc_u32 s99, s31, s15
	s_add_u32 s100, s34, s14
	s_addc_u32 s101, s35, s15
	s_add_i32 s57, s49, s37
	s_mov_b32 m0, s57
	ds_read_b128 v[182:185], v149 offset:16384
	ds_read_b128 v[186:189], v149 offset:17408
	ds_read_b128 v[190:193], v149 offset:18432
	ds_read_b128 v[194:197], v149 offset:19456
	ds_read_b128 v[198:201], v149 offset:20480
	ds_read_b128 v[202:205], v149 offset:21504
	ds_read_b128 v[206:209], v149 offset:22528
	ds_read_b128 v[210:213], v149 offset:23552
	global_load_lds_dwordx4 v132, s[30:31]
	s_add_i32 m0, s57, 0x2000
	s_add_u32 s58, s30, 0x40000
	s_addc_u32 s59, s31, 0
	s_add_i32 s57, s50, s37
	global_load_lds_dwordx4 v128, s[30:31]
	s_mov_b32 m0, s57
	s_nop 0
	global_load_lds_dwordx4 v132, s[58:59]
	s_waitcnt vmcnt(5)
	s_waitcnt lgkmcnt(0)
	s_setprio 1
	s_barrier
	v_mfma_f32_16x16x32_bf16 v[60:63], v[150:153], v[182:185], v[60:63]
	v_mfma_f32_16x16x32_bf16 v[56:59], v[158:161], v[182:185], v[56:59]
	v_mfma_f32_16x16x32_bf16 v[44:47], v[150:153], v[190:193], v[44:47]
	v_mfma_f32_16x16x32_bf16 v[40:43], v[158:161], v[190:193], v[40:43]
	v_mfma_f32_16x16x32_bf16 v[28:31], v[150:153], v[198:201], v[28:31]
	v_mfma_f32_16x16x32_bf16 v[24:27], v[158:161], v[198:201], v[24:27]
	v_mfma_f32_16x16x32_bf16 v[12:15], v[150:153], v[206:209], v[12:15]
	v_mfma_f32_16x16x32_bf16 v[8:11], v[158:161], v[206:209], v[8:11]
	v_mfma_f32_16x16x32_bf16 v[60:63], v[154:157], v[186:189], v[60:63]
	v_mfma_f32_16x16x32_bf16 v[56:59], v[162:165], v[186:189], v[56:59]
	v_mfma_f32_16x16x32_bf16 v[44:47], v[154:157], v[194:197], v[44:47]
	v_mfma_f32_16x16x32_bf16 v[40:43], v[162:165], v[194:197], v[40:43]
	v_mfma_f32_16x16x32_bf16 v[28:31], v[154:157], v[202:205], v[28:31]
	v_mfma_f32_16x16x32_bf16 v[24:27], v[162:165], v[202:205], v[24:27]
	v_mfma_f32_16x16x32_bf16 v[12:15], v[154:157], v[210:213], v[12:15]
	v_mfma_f32_16x16x32_bf16 v[8:11], v[162:165], v[210:213], v[8:11]
	s_add_i32 m0, s57, 0x2000
	s_nop 0
	global_load_lds_dwordx4 v128, s[58:59]
	v_mfma_f32_16x16x32_bf16 v[52:55], v[166:169], v[182:185], v[52:55]
	v_mfma_f32_16x16x32_bf16 v[48:51], v[174:177], v[182:185], v[48:51]
	v_mfma_f32_16x16x32_bf16 v[36:39], v[166:169], v[190:193], v[36:39]
	v_mfma_f32_16x16x32_bf16 v[32:35], v[174:177], v[190:193], v[32:35]
	v_mfma_f32_16x16x32_bf16 v[20:23], v[166:169], v[198:201], v[20:23]
	v_mfma_f32_16x16x32_bf16 v[16:19], v[174:177], v[198:201], v[16:19]
	v_mfma_f32_16x16x32_bf16 v[4:7], v[166:169], v[206:209], v[4:7]
	v_mfma_f32_16x16x32_bf16 v[0:3], v[174:177], v[206:209], v[0:3]
	v_mfma_f32_16x16x32_bf16 v[52:55], v[170:173], v[186:189], v[52:55]
	v_mfma_f32_16x16x32_bf16 v[48:51], v[178:181], v[186:189], v[48:51]
	v_mfma_f32_16x16x32_bf16 v[36:39], v[170:173], v[194:197], v[36:39]
	v_mfma_f32_16x16x32_bf16 v[32:35], v[178:181], v[194:197], v[32:35]
	v_mfma_f32_16x16x32_bf16 v[20:23], v[170:173], v[202:205], v[20:23]
	v_mfma_f32_16x16x32_bf16 v[16:19], v[178:181], v[202:205], v[16:19]
	v_mfma_f32_16x16x32_bf16 v[4:7], v[170:173], v[210:213], v[4:7]
	v_mfma_f32_16x16x32_bf16 v[0:3], v[178:181], v[210:213], v[0:3]
	s_barrier
; #define PG8_STAGE(bufoff, gbase, voff) do { _Pragma("unroll") for (int _i = 0; _i < 2; ++_i) \
;         __builtin_amdgcn_global_load_lds((const unsigned*)((const char*)(gbase) + (voff)[_i]), (LAS unsigned*)(lds + (bufoff) + ldsw + _i * 8192), 16, 0, ((voff) == voffA ? AUXA : 0)); } while (0)
; #define PG8_LDA(dst, b, h) do { _Pragma("unroll") for (int m = 0; m < 4; ++m) _Pragma("unroll") for (int k = 0; k < 2; ++k) dst[m][k] = *(const LAS bf16x8*)(lds + PG8_SA(b, h) + aoff + m * 2048 + k * 1024); } while (0)
; #define PG8_LDB(dst, b, h) do { _Pragma("unroll") for (int n = 0; n < 2; ++n) _Pragma("unroll") for (int k = 0; k < 2; ++k) dst[n][k] = *(const LAS bf16x8*)(lds + PG8_SB(b, h) + boff + n * 2048 + k * 1024); } while (0)
; #define PG8_MMA(ai, bj, At, Bt) do { __builtin_amdgcn_s_setprio(1); _Pragma("unroll") for (int m = 0; m < 4; ++m) _Pragma("unroll") for (int n = 0; n < 2; ++n) _Pragma("unroll") for (int k = 0; k < 2; ++k) \
;         acc[ai][bj][m][n] = __builtin_amdgcn_mfma_f32_16x16x32_bf16(Bt[n][k], At[m][k], acc[ai][bj][m][n], 0, 0, 0); __builtin_amdgcn_s_setprio(0); } while (0)
; #define PG8_WAIT_V(n) asm volatile("s_waitcnt vmcnt(" #n ")" ::: "memory")
; #define PG8_WAIT_L(n) asm volatile("s_waitcnt lgkmcnt(" #n ")" ::: "memory")
; #define PG8_BAR __builtin_amdgcn_s_barrier()
; #define PG8_SCHED __builtin_amdgcn_sched_barrier(0)
;     ...
;             PG8_LDB(B0, 1, 0); PG8_LDB(B1, 1, 1); PG8_SCHED; PG8_LDA(At, 1, 0); PG8_STAGE(PG8_SA(0, 1), a2 + hsA, voffA);
;             PG8_WAIT_V(8); PG8_WAIT_L(0); PG8_BAR; PG8_MMA(0, 0, At, B0); PG8_MMA(0, 1, At, B1); PG8_BAR; PG8_SCHED;
;             PG8_LDA(At, 1, 1); PG8_STAGE(PG8_SB(1, 0), b3, voffB); PG8_STAGE(PG8_SB(1, 1), b3 + hsB, voffB); PG8_STAGE(PG8_SA(1, 0), a3, voffA);
;             PG8_WAIT_V(8); PG8_WAIT_L(0); PG8_BAR; PG8_MMA(1, 0, At, B0); PG8_MMA(1, 1, At, B1); PG8_BAR; PG8_SCHED;
;         }
	s_mov_b32 m0, s19
	s_nop 0
	global_load_lds_dwordx4 v134, s[34:35]
	s_mov_b32 m0, s40
	s_nop 0
	global_load_lds_dwordx4 v130, s[34:35]
	s_setprio 0
	s_add_i32 s57, 0, 0x18000
	s_add_i32 s58, 0, 0x1c000
	v_add_u32_e32 v162, s57, v145
	v_add_u32_e32 v178, s58, v145
	ds_read_b128 v[150:153], v162
	ds_read_b128 v[154:157], v162 offset:1024
	ds_read_b128 v[158:161], v162 offset:2048
	ds_read_b128 v[162:165], v162 offset:3072
	ds_read_b128 v[166:169], v178
	ds_read_b128 v[170:173], v178 offset:1024
	ds_read_b128 v[174:177], v178 offset:2048
	ds_read_b128 v[178:181], v178 offset:3072
	s_add_u32 s34, s34, 0x40000
	s_addc_u32 s35, s35, 0
	s_mov_b32 m0, s41
	ds_read_b128 v[182:185], v149 offset:32768
	ds_read_b128 v[186:189], v149 offset:33792
	ds_read_b128 v[190:193], v149 offset:34816
	ds_read_b128 v[194:197], v149 offset:35840
	ds_read_b128 v[198:201], v149 offset:36864
	ds_read_b128 v[202:205], v149 offset:37888
	ds_read_b128 v[206:209], v149 offset:38912
	ds_read_b128 v[210:213], v149 offset:39936
	global_load_lds_dwordx4 v134, s[34:35]
	s_waitcnt vmcnt(7)
	s_waitcnt lgkmcnt(0)
	s_setprio 1
	s_barrier
	v_mfma_f32_16x16x32_bf16 v[124:127], v[150:153], v[182:185], v[124:127]
	v_mfma_f32_16x16x32_bf16 v[120:123], v[158:161], v[182:185], v[120:123]
	v_mfma_f32_16x16x32_bf16 v[108:111], v[150:153], v[190:193], v[108:111]
	v_mfma_f32_16x16x32_bf16 v[104:107], v[158:161], v[190:193], v[104:107]
	v_mfma_f32_16x16x32_bf16 v[92:95], v[150:153], v[198:201], v[92:95]
	v_mfma_f32_16x16x32_bf16 v[88:91], v[158:161], v[198:201], v[88:91]
	v_mfma_f32_16x16x32_bf16 v[76:79], v[150:153], v[206:209], v[76:79]
	v_mfma_f32_16x16x32_bf16 v[72:75], v[158:161], v[206:209], v[72:75]
	v_mfma_f32_16x16x32_bf16 v[124:127], v[154:157], v[186:189], v[124:127]
	v_mfma_f32_16x16x32_bf16 v[120:123], v[162:165], v[186:189], v[120:123]
	v_mfma_f32_16x16x32_bf16 v[108:111], v[154:157], v[194:197], v[108:111]
	v_mfma_f32_16x16x32_bf16 v[104:107], v[162:165], v[194:197], v[104:107]
	v_mfma_f32_16x16x32_bf16 v[92:95], v[154:157], v[202:205], v[92:95]
	v_mfma_f32_16x16x32_bf16 v[88:91], v[162:165], v[202:205], v[88:91]
	v_mfma_f32_16x16x32_bf16 v[76:79], v[154:157], v[210:213], v[76:79]
	v_mfma_f32_16x16x32_bf16 v[72:75], v[162:165], v[210:213], v[72:75]
	s_mov_b32 m0, s42
	s_nop 0
	global_load_lds_dwordx4 v130, s[34:35]
	v_mfma_f32_16x16x32_bf16 v[116:119], v[166:169], v[182:185], v[116:119]
	v_mfma_f32_16x16x32_bf16 v[112:115], v[174:177], v[182:185], v[112:115]
	v_mfma_f32_16x16x32_bf16 v[100:103], v[166:169], v[190:193], v[100:103]
	v_mfma_f32_16x16x32_bf16 v[96:99], v[174:177], v[190:193], v[96:99]
	v_mfma_f32_16x16x32_bf16 v[84:87], v[166:169], v[198:201], v[84:87]
	v_mfma_f32_16x16x32_bf16 v[80:83], v[174:177], v[198:201], v[80:83]
	v_mfma_f32_16x16x32_bf16 v[68:71], v[166:169], v[206:209], v[68:71]
	v_mfma_f32_16x16x32_bf16 v[64:67], v[174:177], v[206:209], v[64:67]
	v_mfma_f32_16x16x32_bf16 v[116:119], v[170:173], v[186:189], v[116:119]
	v_mfma_f32_16x16x32_bf16 v[112:115], v[178:181], v[186:189], v[112:115]
	v_mfma_f32_16x16x32_bf16 v[100:103], v[170:173], v[194:197], v[100:103]
	v_mfma_f32_16x16x32_bf16 v[96:99], v[178:181], v[194:197], v[96:99]
	v_mfma_f32_16x16x32_bf16 v[84:87], v[170:173], v[202:205], v[84:87]
	v_mfma_f32_16x16x32_bf16 v[80:83], v[178:181], v[202:205], v[80:83]
	v_mfma_f32_16x16x32_bf16 v[68:71], v[170:173], v[210:213], v[68:71]
	v_mfma_f32_16x16x32_bf16 v[64:67], v[178:181], v[210:213], v[64:67]
	s_barrier
	s_setprio 0
	s_add_i32 s34, s57, s37
	s_mov_b32 m0, s34
	ds_read_b128 v[182:185], v149 offset:49152
	ds_read_b128 v[186:189], v149 offset:50176
	ds_read_b128 v[190:193], v149 offset:51200
	ds_read_b128 v[194:197], v149 offset:52224
	ds_read_b128 v[198:201], v149 offset:53248
	ds_read_b128 v[202:205], v149 offset:54272
	ds_read_b128 v[206:209], v149 offset:55296
	ds_read_b128 v[210:213], v149 offset:56320
	global_load_lds_dwordx4 v132, s[98:99]
	s_add_i32 m0, s34, 0x2000
	s_add_u32 s30, s30, 0x40080
	s_addc_u32 s31, s31, 0
	s_add_i32 s34, s58, s37
	global_load_lds_dwordx4 v128, s[98:99]
	s_mov_b32 m0, s34
	s_nop 0
	global_load_lds_dwordx4 v132, s[30:31]
	s_waitcnt vmcnt(5)
	s_waitcnt lgkmcnt(0)
	s_setprio 1
	s_barrier
	v_mfma_f32_16x16x32_bf16 v[60:63], v[150:153], v[182:185], v[60:63]
	v_mfma_f32_16x16x32_bf16 v[56:59], v[158:161], v[182:185], v[56:59]
	v_mfma_f32_16x16x32_bf16 v[44:47], v[150:153], v[190:193], v[44:47]
	v_mfma_f32_16x16x32_bf16 v[40:43], v[158:161], v[190:193], v[40:43]
	v_mfma_f32_16x16x32_bf16 v[28:31], v[150:153], v[198:201], v[28:31]
	v_mfma_f32_16x16x32_bf16 v[24:27], v[158:161], v[198:201], v[24:27]
	v_mfma_f32_16x16x32_bf16 v[12:15], v[150:153], v[206:209], v[12:15]
	v_mfma_f32_16x16x32_bf16 v[8:11], v[158:161], v[206:209], v[8:11]
	v_mfma_f32_16x16x32_bf16 v[60:63], v[154:157], v[186:189], v[60:63]
	v_mfma_f32_16x16x32_bf16 v[56:59], v[162:165], v[186:189], v[56:59]
	v_mfma_f32_16x16x32_bf16 v[44:47], v[154:157], v[194:197], v[44:47]
	v_mfma_f32_16x16x32_bf16 v[40:43], v[162:165], v[194:197], v[40:43]
	v_mfma_f32_16x16x32_bf16 v[28:31], v[154:157], v[202:205], v[28:31]
	v_mfma_f32_16x16x32_bf16 v[24:27], v[162:165], v[202:205], v[24:27]
	v_mfma_f32_16x16x32_bf16 v[12:15], v[154:157], v[210:213], v[12:15]
	v_mfma_f32_16x16x32_bf16 v[8:11], v[162:165], v[210:213], v[8:11]
	s_add_i32 m0, s34, 0x2000
	s_nop 0
	global_load_lds_dwordx4 v128, s[30:31]
	v_mfma_f32_16x16x32_bf16 v[52:55], v[166:169], v[182:185], v[52:55]
	v_mfma_f32_16x16x32_bf16 v[48:51], v[174:177], v[182:185], v[48:51]
	v_mfma_f32_16x16x32_bf16 v[36:39], v[166:169], v[190:193], v[36:39]
	v_mfma_f32_16x16x32_bf16 v[32:35], v[174:177], v[190:193], v[32:35]
	v_mfma_f32_16x16x32_bf16 v[20:23], v[166:169], v[198:201], v[20:23]
	v_mfma_f32_16x16x32_bf16 v[16:19], v[174:177], v[198:201], v[16:19]
	v_mfma_f32_16x16x32_bf16 v[4:7], v[166:169], v[206:209], v[4:7]
	v_mfma_f32_16x16x32_bf16 v[0:3], v[174:177], v[206:209], v[0:3]
	v_mfma_f32_16x16x32_bf16 v[52:55], v[170:173], v[186:189], v[52:55]
	v_mfma_f32_16x16x32_bf16 v[48:51], v[178:181], v[186:189], v[48:51]
	v_mfma_f32_16x16x32_bf16 v[36:39], v[170:173], v[194:197], v[36:39]
	v_mfma_f32_16x16x32_bf16 v[32:35], v[178:181], v[194:197], v[32:35]
	v_mfma_f32_16x16x32_bf16 v[20:23], v[170:173], v[202:205], v[20:23]
	v_mfma_f32_16x16x32_bf16 v[16:19], v[178:181], v[202:205], v[16:19]
	v_mfma_f32_16x16x32_bf16 v[4:7], v[170:173], v[210:213], v[4:7]
	v_mfma_f32_16x16x32_bf16 v[0:3], v[178:181], v[210:213], v[0:3]
	s_barrier
	s_setprio 0
	s_add_u32 s28, s28, 0x100
	s_addc_u32 s29, s29, 0
	s_add_u32 s54, s54, 0x100
	s_addc_u32 s55, s55, 0
	s_cmp_ge_i32 s56, s44
	s_mov_b32 s30, s56
	s_cbranch_scc0 .LBB0_1040

; #define PG8_STAGE(bufoff, gbase, voff) do { _Pragma("unroll") for (int _i = 0; _i < 2; ++_i) \
;         __builtin_amdgcn_global_load_lds((const unsigned*)((const char*)(gbase) + (voff)[_i]), (LAS unsigned*)(lds + (bufoff) + ldsw + _i * 8192), 16, 0, ((voff) == voffA ? AUXA : 0)); } while (0)
; #define PG8_LDA(dst, b, h) do { _Pragma("unroll") for (int m = 0; m < 4; ++m) _Pragma("unroll") for (int k = 0; k < 2; ++k) dst[m][k] = *(const LAS bf16x8*)(lds + PG8_SA(b, h) + aoff + m * 2048 + k * 1024); } while (0)
; #define PG8_LDB(dst, b, h) do { _Pragma("unroll") for (int n = 0; n < 2; ++n) _Pragma("unroll") for (int k = 0; k < 2; ++k) dst[n][k] = *(const LAS bf16x8*)(lds + PG8_SB(b, h) + boff + n * 2048 + k * 1024); } while (0)
; #define PG8_MMA(ai, bj, At, Bt) do { __builtin_amdgcn_s_setprio(1); _Pragma("unroll") for (int m = 0; m < 4; ++m) _Pragma("unroll") for (int n = 0; n < 2; ++n) _Pragma("unroll") for (int k = 0; k < 2; ++k) \
;         acc[ai][bj][m][n] = __builtin_amdgcn_mfma_f32_16x16x32_bf16(Bt[n][k], At[m][k], acc[ai][bj][m][n], 0, 0, 0); __builtin_amdgcn_s_setprio(0); } while (0)
; #define PG8_WAIT_V(n) asm volatile("s_waitcnt vmcnt(" #n ")" ::: "memory")
; #define PG8_WAIT_L(n) asm volatile("s_waitcnt lgkmcnt(" #n ")" ::: "memory")
; #define PG8_BAR __builtin_amdgcn_s_barrier()
; #define PG8_SCHED __builtin_amdgcn_sched_barrier(0)
;     ...
;         for (int t = 0; t < nt; t += 2) {
;             const bool last = (t == nt - 2);
;             const char* a1 = cA + (size_t)(t + 1) * kstep;
;             const char* a2 = last ? nA : cA + (size_t)(t + 2) * kstep; const char* b2 = last ? nB : cB + (size_t)(t + 2) * kstep;
;             const char* a3 = a2 + kstep; const char* b3 = b2 + kstep;
;             PG8_LDB(B0, 0, 0); PG8_LDB(B1, 0, 1); PG8_SCHED; PG8_LDA(At, 0, 0); PG8_STAGE(PG8_SA(1, 1), a1 + hsA, voffA);
;             if (Epi::NPRE != 0 && last) { E.pre(sv, cur, wr, fr); PG8_WAIT_V(16); } else { PG8_WAIT_V(8); }
;             PG8_WAIT_L(0); PG8_BAR; PG8_MMA(0, 0, At, B0); PG8_MMA(0, 1, At, B1); PG8_BAR; PG8_SCHED;
;             PG8_LDA(At, 0, 1); PG8_STAGE(PG8_SB(0, 0), b2, voffB); PG8_STAGE(PG8_SB(0, 1), b2 + hsB, voffB); PG8_STAGE(PG8_SA(0, 0), a2, voffA);
;             if (Epi::NPRE != 0 && last) { PG8_WAIT_V(16); } else { PG8_WAIT_V(8); }
;             PG8_WAIT_L(0); PG8_BAR; PG8_MMA(1, 0, At, B0); PG8_MMA(1, 1, At, B1); PG8_BAR; PG8_SCHED;
.LBB0_1112:
	s_add_u32 s98, s28, 0xfffc0000
	s_addc_u32 s99, s29, -1
	s_mov_b32 m0, s43
	s_nop 0
	global_load_lds_dwordx4 v134, s[98:99]
	s_mov_b32 m0, s44
	s_nop 0
	global_load_lds_dwordx4 v130, s[98:99]
	ds_read_b128 v[150:153], v147
	ds_read_b128 v[154:157], v147 offset:1024
	ds_read_b128 v[158:161], v147 offset:2048
	ds_read_b128 v[162:165], v147 offset:3072
	ds_read_b128 v[166:169], v148
	ds_read_b128 v[170:173], v148 offset:1024
	ds_read_b128 v[174:177], v148 offset:2048
	ds_read_b128 v[178:181], v148 offset:3072
	s_add_i32 s54, s30, 2
	s_add_u32 s31, s28, 0xfffc0080
	s_addc_u32 s34, s29, -1
	s_cmp_eq_u32 s45, s30
	s_cselect_b32 s30, s51, s52
	s_cselect_b32 s35, s21, s34
	s_cselect_b32 s34, s23, s31
	s_cselect_b32 s31, s50, s53
	s_add_i32 m0, s19, 0xc000
	ds_read_b128 v[182:185], v149
	ds_read_b128 v[186:189], v149 offset:1024
	ds_read_b128 v[190:193], v149 offset:2048
	ds_read_b128 v[194:197], v149 offset:3072
	ds_read_b128 v[198:201], v149 offset:4096
	ds_read_b128 v[202:205], v149 offset:5120
	ds_read_b128 v[206:209], v149 offset:6144
	ds_read_b128 v[210:213], v149 offset:7168
	global_load_lds_dwordx4 v136, s[28:29]
	s_waitcnt vmcnt(7)
	s_waitcnt lgkmcnt(0)
	s_setprio 1
	s_barrier
	v_mfma_f32_16x16x32_bf16 v[124:127], v[150:153], v[182:185], v[124:127]
	v_mfma_f32_16x16x32_bf16 v[120:123], v[158:161], v[182:185], v[120:123]
	v_mfma_f32_16x16x32_bf16 v[108:111], v[150:153], v[190:193], v[108:111]
	v_mfma_f32_16x16x32_bf16 v[104:107], v[158:161], v[190:193], v[104:107]
	v_mfma_f32_16x16x32_bf16 v[92:95], v[150:153], v[198:201], v[92:95]
	v_mfma_f32_16x16x32_bf16 v[88:91], v[158:161], v[198:201], v[88:91]
	v_mfma_f32_16x16x32_bf16 v[76:79], v[150:153], v[206:209], v[76:79]
	v_mfma_f32_16x16x32_bf16 v[72:75], v[158:161], v[206:209], v[72:75]
	v_mfma_f32_16x16x32_bf16 v[124:127], v[154:157], v[186:189], v[124:127]
	v_mfma_f32_16x16x32_bf16 v[120:123], v[162:165], v[186:189], v[120:123]
	v_mfma_f32_16x16x32_bf16 v[108:111], v[154:157], v[194:197], v[108:111]
	v_mfma_f32_16x16x32_bf16 v[104:107], v[162:165], v[194:197], v[104:107]
	v_mfma_f32_16x16x32_bf16 v[92:95], v[154:157], v[202:205], v[92:95]
	v_mfma_f32_16x16x32_bf16 v[88:91], v[162:165], v[202:205], v[88:91]
	v_mfma_f32_16x16x32_bf16 v[76:79], v[154:157], v[210:213], v[76:79]
	v_mfma_f32_16x16x32_bf16 v[72:75], v[162:165], v[210:213], v[72:75]
	s_add_i32 m0, s19, 0xe000
	s_nop 0
	global_load_lds_dwordx4 v138, s[28:29]
	v_mfma_f32_16x16x32_bf16 v[116:119], v[166:169], v[182:185], v[116:119]
	v_mfma_f32_16x16x32_bf16 v[112:115], v[174:177], v[182:185], v[112:115]
	v_mfma_f32_16x16x32_bf16 v[100:103], v[166:169], v[190:193], v[100:103]
	v_mfma_f32_16x16x32_bf16 v[96:99], v[174:177], v[190:193], v[96:99]
	v_mfma_f32_16x16x32_bf16 v[84:87], v[166:169], v[198:201], v[84:87]
	v_mfma_f32_16x16x32_bf16 v[80:83], v[174:177], v[198:201], v[80:83]
	v_mfma_f32_16x16x32_bf16 v[68:71], v[166:169], v[206:209], v[68:71]
	v_mfma_f32_16x16x32_bf16 v[64:67], v[174:177], v[206:209], v[64:67]
	v_mfma_f32_16x16x32_bf16 v[116:119], v[170:173], v[186:189], v[116:119]
	v_mfma_f32_16x16x32_bf16 v[112:115], v[178:181], v[186:189], v[112:115]
	v_mfma_f32_16x16x32_bf16 v[100:103], v[170:173], v[194:197], v[100:103]
	v_mfma_f32_16x16x32_bf16 v[96:99], v[178:181], v[194:197], v[96:99]
	v_mfma_f32_16x16x32_bf16 v[84:87], v[170:173], v[202:205], v[84:87]
	v_mfma_f32_16x16x32_bf16 v[80:83], v[178:181], v[202:205], v[80:83]
	v_mfma_f32_16x16x32_bf16 v[68:71], v[170:173], v[210:213], v[68:71]
	v_mfma_f32_16x16x32_bf16 v[64:67], v[178:181], v[210:213], v[64:67]
	s_barrier
	s_setprio 0
	s_add_u32 s98, s30, s14
	s_addc_u32 s99, s31, s15
	s_add_u32 s100, s34, s14
	s_addc_u32 s101, s35, s15
	s_add_i32 s55, s47, s5
	s_mov_b32 m0, s55
	ds_read_b128 v[182:185], v149 offset:16384
	ds_read_b128 v[186:189], v149 offset:17408
	ds_read_b128 v[190:193], v149 offset:18432
	ds_read_b128 v[194:197], v149 offset:19456
	ds_read_b128 v[198:201], v149 offset:20480
	ds_read_b128 v[202:205], v149 offset:21504
	ds_read_b128 v[206:209], v149 offset:22528
	ds_read_b128 v[210:213], v149 offset:23552
	global_load_lds_dwordx4 v132, s[30:31]
	s_add_i32 m0, s55, 0x2000
	s_add_u32 s56, s30, 0x40000
	s_addc_u32 s57, s31, 0
	s_add_i32 s55, s48, s5
	global_load_lds_dwordx4 v128, s[30:31]
	s_mov_b32 m0, s55
	s_nop 0
	global_load_lds_dwordx4 v132, s[56:57]
	s_waitcnt vmcnt(5)
	s_waitcnt lgkmcnt(0)
	s_setprio 1
	s_barrier
	v_mfma_f32_16x16x32_bf16 v[60:63], v[150:153], v[182:185], v[60:63]
	v_mfma_f32_16x16x32_bf16 v[56:59], v[158:161], v[182:185], v[56:59]
	v_mfma_f32_16x16x32_bf16 v[44:47], v[150:153], v[190:193], v[44:47]
	v_mfma_f32_16x16x32_bf16 v[40:43], v[158:161], v[190:193], v[40:43]
	v_mfma_f32_16x16x32_bf16 v[28:31], v[150:153], v[198:201], v[28:31]
	v_mfma_f32_16x16x32_bf16 v[24:27], v[158:161], v[198:201], v[24:27]
	v_mfma_f32_16x16x32_bf16 v[12:15], v[150:153], v[206:209], v[12:15]
	v_mfma_f32_16x16x32_bf16 v[8:11], v[158:161], v[206:209], v[8:11]
	v_mfma_f32_16x16x32_bf16 v[60:63], v[154:157], v[186:189], v[60:63]
	v_mfma_f32_16x16x32_bf16 v[56:59], v[162:165], v[186:189], v[56:59]
	v_mfma_f32_16x16x32_bf16 v[44:47], v[154:157], v[194:197], v[44:47]
	v_mfma_f32_16x16x32_bf16 v[40:43], v[162:165], v[194:197], v[40:43]
	v_mfma_f32_16x16x32_bf16 v[28:31], v[154:157], v[202:205], v[28:31]
	v_mfma_f32_16x16x32_bf16 v[24:27], v[162:165], v[202:205], v[24:27]
	v_mfma_f32_16x16x32_bf16 v[12:15], v[154:157], v[210:213], v[12:15]
	v_mfma_f32_16x16x32_bf16 v[8:11], v[162:165], v[210:213], v[8:11]
	s_add_i32 m0, s55, 0x2000
	s_nop 0
	global_load_lds_dwordx4 v128, s[56:57]
	v_mfma_f32_16x16x32_bf16 v[52:55], v[166:169], v[182:185], v[52:55]
	v_mfma_f32_16x16x32_bf16 v[48:51], v[174:177], v[182:185], v[48:51]
	v_mfma_f32_16x16x32_bf16 v[36:39], v[166:169], v[190:193], v[36:39]
	v_mfma_f32_16x16x32_bf16 v[32:35], v[174:177], v[190:193], v[32:35]
	v_mfma_f32_16x16x32_bf16 v[20:23], v[166:169], v[198:201], v[20:23]
	v_mfma_f32_16x16x32_bf16 v[16:19], v[174:177], v[198:201], v[16:19]
	v_mfma_f32_16x16x32_bf16 v[4:7], v[166:169], v[206:209], v[4:7]
	v_mfma_f32_16x16x32_bf16 v[0:3], v[174:177], v[206:209], v[0:3]
	v_mfma_f32_16x16x32_bf16 v[52:55], v[170:173], v[186:189], v[52:55]
	v_mfma_f32_16x16x32_bf16 v[48:51], v[178:181], v[186:189], v[48:51]
	v_mfma_f32_16x16x32_bf16 v[36:39], v[170:173], v[194:197], v[36:39]
	v_mfma_f32_16x16x32_bf16 v[32:35], v[178:181], v[194:197], v[32:35]
	v_mfma_f32_16x16x32_bf16 v[20:23], v[170:173], v[202:205], v[20:23]
	v_mfma_f32_16x16x32_bf16 v[16:19], v[178:181], v[202:205], v[16:19]
	v_mfma_f32_16x16x32_bf16 v[4:7], v[170:173], v[210:213], v[4:7]
	v_mfma_f32_16x16x32_bf16 v[0:3], v[178:181], v[210:213], v[0:3]
	s_barrier
; #define PG8_STAGE(bufoff, gbase, voff) do { _Pragma("unroll") for (int _i = 0; _i < 2; ++_i) \
;         __builtin_amdgcn_global_load_lds((const unsigned*)((const char*)(gbase) + (voff)[_i]), (LAS unsigned*)(lds + (bufoff) + ldsw + _i * 8192), 16, 0, ((voff) == voffA ? AUXA : 0)); } while (0)
; #define PG8_LDA(dst, b, h) do { _Pragma("unroll") for (int m = 0; m < 4; ++m) _Pragma("unroll") for (int k = 0; k < 2; ++k) dst[m][k] = *(const LAS bf16x8*)(lds + PG8_SA(b, h) + aoff + m * 2048 + k * 1024); } while (0)
; #define PG8_LDB(dst, b, h) do { _Pragma("unroll") for (int n = 0; n < 2; ++n) _Pragma("unroll") for (int k = 0; k < 2; ++k) dst[n][k] = *(const LAS bf16x8*)(lds + PG8_SB(b, h) + boff + n * 2048 + k * 1024); } while (0)
; #define PG8_MMA(ai, bj, At, Bt) do { __builtin_amdgcn_s_setprio(1); _Pragma("unroll") for (int m = 0; m < 4; ++m) _Pragma("unroll") for (int n = 0; n < 2; ++n) _Pragma("unroll") for (int k = 0; k < 2; ++k) \
;         acc[ai][bj][m][n] = __builtin_amdgcn_mfma_f32_16x16x32_bf16(Bt[n][k], At[m][k], acc[ai][bj][m][n], 0, 0, 0); __builtin_amdgcn_s_setprio(0); } while (0)
; #define PG8_WAIT_V(n) asm volatile("s_waitcnt vmcnt(" #n ")" ::: "memory")
; #define PG8_WAIT_L(n) asm volatile("s_waitcnt lgkmcnt(" #n ")" ::: "memory")
; #define PG8_BAR __builtin_amdgcn_s_barrier()
; #define PG8_SCHED __builtin_amdgcn_sched_barrier(0)
;     ...
;             PG8_LDB(B0, 1, 0); PG8_LDB(B1, 1, 1); PG8_SCHED; PG8_LDA(At, 1, 0); PG8_STAGE(PG8_SA(0, 1), a2 + hsA, voffA);
;             PG8_WAIT_V(8); PG8_WAIT_L(0); PG8_BAR; PG8_MMA(0, 0, At, B0); PG8_MMA(0, 1, At, B1); PG8_BAR; PG8_SCHED;
;             PG8_LDA(At, 1, 1); PG8_STAGE(PG8_SB(1, 0), b3, voffB); PG8_STAGE(PG8_SB(1, 1), b3 + hsB, voffB); PG8_STAGE(PG8_SA(1, 0), a3, voffA);
;             PG8_WAIT_V(8); PG8_WAIT_L(0); PG8_BAR; PG8_MMA(1, 0, At, B0); PG8_MMA(1, 1, At, B1); PG8_BAR; PG8_SCHED;
;         }
	s_mov_b32 m0, s19
	s_nop 0
	global_load_lds_dwordx4 v134, s[34:35]
	s_mov_b32 m0, s38
	s_nop 0
	global_load_lds_dwordx4 v130, s[34:35]
	s_setprio 0
	s_add_i32 s55, 0, 0x18000
	s_add_i32 s56, 0, 0x1c000
	v_add_u32_e32 v162, s55, v145
	v_add_u32_e32 v178, s56, v145
	ds_read_b128 v[150:153], v162
	ds_read_b128 v[154:157], v162 offset:1024
	ds_read_b128 v[158:161], v162 offset:2048
	ds_read_b128 v[162:165], v162 offset:3072
	ds_read_b128 v[166:169], v178
	ds_read_b128 v[170:173], v178 offset:1024
	ds_read_b128 v[174:177], v178 offset:2048
	ds_read_b128 v[178:181], v178 offset:3072
	s_add_u32 s34, s34, 0x40000
	s_addc_u32 s35, s35, 0
	s_mov_b32 m0, s39
	ds_read_b128 v[182:185], v149 offset:32768
	ds_read_b128 v[186:189], v149 offset:33792
	ds_read_b128 v[190:193], v149 offset:34816
	ds_read_b128 v[194:197], v149 offset:35840
	ds_read_b128 v[198:201], v149 offset:36864
	ds_read_b128 v[202:205], v149 offset:37888
	ds_read_b128 v[206:209], v149 offset:38912
	ds_read_b128 v[210:213], v149 offset:39936
	global_load_lds_dwordx4 v134, s[34:35]
	s_waitcnt vmcnt(7)
	s_waitcnt lgkmcnt(0)
	s_setprio 1
	s_barrier
	v_mfma_f32_16x16x32_bf16 v[124:127], v[150:153], v[182:185], v[124:127]
	v_mfma_f32_16x16x32_bf16 v[120:123], v[158:161], v[182:185], v[120:123]
	v_mfma_f32_16x16x32_bf16 v[108:111], v[150:153], v[190:193], v[108:111]
	v_mfma_f32_16x16x32_bf16 v[104:107], v[158:161], v[190:193], v[104:107]
	v_mfma_f32_16x16x32_bf16 v[92:95], v[150:153], v[198:201], v[92:95]
	v_mfma_f32_16x16x32_bf16 v[88:91], v[158:161], v[198:201], v[88:91]
	v_mfma_f32_16x16x32_bf16 v[76:79], v[150:153], v[206:209], v[76:79]
	v_mfma_f32_16x16x32_bf16 v[72:75], v[158:161], v[206:209], v[72:75]
	v_mfma_f32_16x16x32_bf16 v[124:127], v[154:157], v[186:189], v[124:127]
	v_mfma_f32_16x16x32_bf16 v[120:123], v[162:165], v[186:189], v[120:123]
	v_mfma_f32_16x16x32_bf16 v[108:111], v[154:157], v[194:197], v[108:111]
	v_mfma_f32_16x16x32_bf16 v[104:107], v[162:165], v[194:197], v[104:107]
	v_mfma_f32_16x16x32_bf16 v[92:95], v[154:157], v[202:205], v[92:95]
	v_mfma_f32_16x16x32_bf16 v[88:91], v[162:165], v[202:205], v[88:91]
	v_mfma_f32_16x16x32_bf16 v[76:79], v[154:157], v[210:213], v[76:79]
	v_mfma_f32_16x16x32_bf16 v[72:75], v[162:165], v[210:213], v[72:75]
	s_mov_b32 m0, s40
	s_nop 0
	global_load_lds_dwordx4 v130, s[34:35]
	v_mfma_f32_16x16x32_bf16 v[116:119], v[166:169], v[182:185], v[116:119]
	v_mfma_f32_16x16x32_bf16 v[112:115], v[174:177], v[182:185], v[112:115]
	v_mfma_f32_16x16x32_bf16 v[100:103], v[166:169], v[190:193], v[100:103]
	v_mfma_f32_16x16x32_bf16 v[96:99], v[174:177], v[190:193], v[96:99]
	v_mfma_f32_16x16x32_bf16 v[84:87], v[166:169], v[198:201], v[84:87]
	v_mfma_f32_16x16x32_bf16 v[80:83], v[174:177], v[198:201], v[80:83]
	v_mfma_f32_16x16x32_bf16 v[68:71], v[166:169], v[206:209], v[68:71]
	v_mfma_f32_16x16x32_bf16 v[64:67], v[174:177], v[206:209], v[64:67]
	v_mfma_f32_16x16x32_bf16 v[116:119], v[170:173], v[186:189], v[116:119]
	v_mfma_f32_16x16x32_bf16 v[112:115], v[178:181], v[186:189], v[112:115]
	v_mfma_f32_16x16x32_bf16 v[100:103], v[170:173], v[194:197], v[100:103]
	v_mfma_f32_16x16x32_bf16 v[96:99], v[178:181], v[194:197], v[96:99]
	v_mfma_f32_16x16x32_bf16 v[84:87], v[170:173], v[202:205], v[84:87]
	v_mfma_f32_16x16x32_bf16 v[80:83], v[178:181], v[202:205], v[80:83]
	v_mfma_f32_16x16x32_bf16 v[68:71], v[170:173], v[210:213], v[68:71]
	v_mfma_f32_16x16x32_bf16 v[64:67], v[178:181], v[210:213], v[64:67]
	s_barrier
	s_setprio 0
	s_add_i32 s34, s55, s5
	s_mov_b32 m0, s34
	ds_read_b128 v[182:185], v149 offset:49152
	ds_read_b128 v[186:189], v149 offset:50176
	ds_read_b128 v[190:193], v149 offset:51200
	ds_read_b128 v[194:197], v149 offset:52224
	ds_read_b128 v[198:201], v149 offset:53248
	ds_read_b128 v[202:205], v149 offset:54272
	ds_read_b128 v[206:209], v149 offset:55296
	ds_read_b128 v[210:213], v149 offset:56320
	global_load_lds_dwordx4 v132, s[98:99]
	s_add_i32 m0, s34, 0x2000
	s_add_u32 s30, s30, 0x40080
	s_addc_u32 s31, s31, 0
	s_add_i32 s34, s56, s5
	global_load_lds_dwordx4 v128, s[98:99]
	s_mov_b32 m0, s34
	s_nop 0
	global_load_lds_dwordx4 v132, s[30:31]
	s_waitcnt vmcnt(5)
	s_waitcnt lgkmcnt(0)
	s_setprio 1
	s_barrier
	v_mfma_f32_16x16x32_bf16 v[60:63], v[150:153], v[182:185], v[60:63]
	v_mfma_f32_16x16x32_bf16 v[56:59], v[158:161], v[182:185], v[56:59]
	v_mfma_f32_16x16x32_bf16 v[44:47], v[150:153], v[190:193], v[44:47]
	v_mfma_f32_16x16x32_bf16 v[40:43], v[158:161], v[190:193], v[40:43]
	v_mfma_f32_16x16x32_bf16 v[28:31], v[150:153], v[198:201], v[28:31]
	v_mfma_f32_16x16x32_bf16 v[24:27], v[158:161], v[198:201], v[24:27]
	v_mfma_f32_16x16x32_bf16 v[12:15], v[150:153], v[206:209], v[12:15]
	v_mfma_f32_16x16x32_bf16 v[8:11], v[158:161], v[206:209], v[8:11]
	v_mfma_f32_16x16x32_bf16 v[60:63], v[154:157], v[186:189], v[60:63]
	v_mfma_f32_16x16x32_bf16 v[56:59], v[162:165], v[186:189], v[56:59]
	v_mfma_f32_16x16x32_bf16 v[44:47], v[154:157], v[194:197], v[44:47]
	v_mfma_f32_16x16x32_bf16 v[40:43], v[162:165], v[194:197], v[40:43]
	v_mfma_f32_16x16x32_bf16 v[28:31], v[154:157], v[202:205], v[28:31]
	v_mfma_f32_16x16x32_bf16 v[24:27], v[162:165], v[202:205], v[24:27]
	v_mfma_f32_16x16x32_bf16 v[12:15], v[154:157], v[210:213], v[12:15]
	v_mfma_f32_16x16x32_bf16 v[8:11], v[162:165], v[210:213], v[8:11]
	s_add_i32 m0, s34, 0x2000
	s_nop 0
	global_load_lds_dwordx4 v128, s[30:31]
	v_mfma_f32_16x16x32_bf16 v[52:55], v[166:169], v[182:185], v[52:55]
	v_mfma_f32_16x16x32_bf16 v[48:51], v[174:177], v[182:185], v[48:51]
	v_mfma_f32_16x16x32_bf16 v[36:39], v[166:169], v[190:193], v[36:39]
	v_mfma_f32_16x16x32_bf16 v[32:35], v[174:177], v[190:193], v[32:35]
	v_mfma_f32_16x16x32_bf16 v[20:23], v[166:169], v[198:201], v[20:23]
	v_mfma_f32_16x16x32_bf16 v[16:19], v[174:177], v[198:201], v[16:19]
	v_mfma_f32_16x16x32_bf16 v[4:7], v[166:169], v[206:209], v[4:7]
	v_mfma_f32_16x16x32_bf16 v[0:3], v[174:177], v[206:209], v[0:3]
	v_mfma_f32_16x16x32_bf16 v[52:55], v[170:173], v[186:189], v[52:55]
	v_mfma_f32_16x16x32_bf16 v[48:51], v[178:181], v[186:189], v[48:51]
	v_mfma_f32_16x16x32_bf16 v[36:39], v[170:173], v[194:197], v[36:39]
	v_mfma_f32_16x16x32_bf16 v[32:35], v[178:181], v[194:197], v[32:35]
	v_mfma_f32_16x16x32_bf16 v[20:23], v[170:173], v[202:205], v[20:23]
	v_mfma_f32_16x16x32_bf16 v[16:19], v[178:181], v[202:205], v[16:19]
	v_mfma_f32_16x16x32_bf16 v[4:7], v[170:173], v[210:213], v[4:7]
	v_mfma_f32_16x16x32_bf16 v[0:3], v[178:181], v[210:213], v[0:3]
	s_barrier
	s_setprio 0
	s_add_u32 s28, s28, 0x100
	s_addc_u32 s29, s29, 0
	s_add_u32 s52, s52, 0x100
	s_addc_u32 s53, s53, 0
	s_cmp_ge_i32 s54, s42
	s_mov_b32 s30, s54
	s_cbranch_scc0 .LBB0_1112

; #define PG8_STAGE(bufoff, gbase, voff) do { _Pragma("unroll") for (int _i = 0; _i < 2; ++_i) \
;         __builtin_amdgcn_global_load_lds((const unsigned*)((const char*)(gbase) + (voff)[_i]), (LAS unsigned*)(lds + (bufoff) + ldsw + _i * 8192), 16, 0, ((voff) == voffA ? AUXA : 0)); } while (0)
; #define PG8_LDA(dst, b, h) do { _Pragma("unroll") for (int m = 0; m < 4; ++m) _Pragma("unroll") for (int k = 0; k < 2; ++k) dst[m][k] = *(const LAS bf16x8*)(lds + PG8_SA(b, h) + aoff + m * 2048 + k * 1024); } while (0)
; #define PG8_LDB(dst, b, h) do { _Pragma("unroll") for (int n = 0; n < 2; ++n) _Pragma("unroll") for (int k = 0; k < 2; ++k) dst[n][k] = *(const LAS bf16x8*)(lds + PG8_SB(b, h) + boff + n * 2048 + k * 1024); } while (0)
; #define PG8_MMA(ai, bj, At, Bt) do { __builtin_amdgcn_s_setprio(1); _Pragma("unroll") for (int m = 0; m < 4; ++m) _Pragma("unroll") for (int n = 0; n < 2; ++n) _Pragma("unroll") for (int k = 0; k < 2; ++k) \
;         acc[ai][bj][m][n] = __builtin_amdgcn_mfma_f32_16x16x32_bf16(Bt[n][k], At[m][k], acc[ai][bj][m][n], 0, 0, 0); __builtin_amdgcn_s_setprio(0); } while (0)
; #define PG8_WAIT_V(n) asm volatile("s_waitcnt vmcnt(" #n ")" ::: "memory")
; #define PG8_WAIT_L(n) asm volatile("s_waitcnt lgkmcnt(" #n ")" ::: "memory")
; #define PG8_BAR __builtin_amdgcn_s_barrier()
; #define PG8_SCHED __builtin_amdgcn_sched_barrier(0)
;     ...
;             PG8_WAIT_L(0); PG8_BAR; PG8_MMA(1, 0, At, B0); PG8_MMA(1, 1, At, B1); PG8_BAR; PG8_SCHED;
;             PG8_LDB(B0, 1, 0); PG8_LDB(B1, 1, 1); PG8_SCHED; PG8_LDA(At, 1, 0); PG8_STAGE(PG8_SA(0, 1), a2 + hsA, voffA);
;             PG8_WAIT_V(8); PG8_WAIT_L(0); PG8_BAR; PG8_MMA(0, 0, At, B0); PG8_MMA(0, 1, At, B1); PG8_BAR; PG8_SCHED;
.LBB0_1184:
	s_waitcnt lgkmcnt(0)
	s_add_i32 s62, s62, 2
	s_setprio 1
	s_barrier
	v_mfma_f32_16x16x32_bf16 v[60:63], v[144:147], v[184:187], v[60:63]
	v_mfma_f32_16x16x32_bf16 v[52:55], v[152:155], v[184:187], v[52:55]
	v_mfma_f32_16x16x32_bf16 v[44:47], v[144:147], v[176:179], v[44:47]
	v_mfma_f32_16x16x32_bf16 v[36:39], v[152:155], v[176:179], v[36:39]
	v_mfma_f32_16x16x32_bf16 v[28:31], v[144:147], v[168:171], v[28:31]
	v_mfma_f32_16x16x32_bf16 v[20:23], v[152:155], v[168:171], v[20:23]
	v_mfma_f32_16x16x32_bf16 v[12:15], v[144:147], v[160:163], v[12:15]
	v_mfma_f32_16x16x32_bf16 v[4:7], v[152:155], v[160:163], v[4:7]
	v_mfma_f32_16x16x32_bf16 v[60:63], v[148:151], v[188:191], v[60:63]
	v_mfma_f32_16x16x32_bf16 v[52:55], v[156:159], v[188:191], v[52:55]
	v_mfma_f32_16x16x32_bf16 v[44:47], v[148:151], v[180:183], v[44:47]
	v_mfma_f32_16x16x32_bf16 v[36:39], v[156:159], v[180:183], v[36:39]
	v_mfma_f32_16x16x32_bf16 v[28:31], v[148:151], v[172:175], v[28:31]
	v_mfma_f32_16x16x32_bf16 v[20:23], v[156:159], v[172:175], v[20:23]
	v_mfma_f32_16x16x32_bf16 v[12:15], v[148:151], v[164:167], v[12:15]
	v_mfma_f32_16x16x32_bf16 v[4:7], v[156:159], v[164:167], v[4:7]
	s_mov_b32 m0, s46
	s_nop 0
	global_load_lds_dwordx4 v192, s[100:101]
	v_mfma_f32_16x16x32_bf16 v[56:59], v[128:131], v[184:187], v[56:59]
	v_mfma_f32_16x16x32_bf16 v[48:51], v[136:139], v[184:187], v[48:51]
	v_mfma_f32_16x16x32_bf16 v[40:43], v[128:131], v[176:179], v[40:43]
	v_mfma_f32_16x16x32_bf16 v[32:35], v[136:139], v[176:179], v[32:35]
	v_mfma_f32_16x16x32_bf16 v[24:27], v[128:131], v[168:171], v[24:27]
	v_mfma_f32_16x16x32_bf16 v[16:19], v[136:139], v[168:171], v[16:19]
	v_mfma_f32_16x16x32_bf16 v[8:11], v[128:131], v[160:163], v[8:11]
	v_mfma_f32_16x16x32_bf16 v[0:3], v[136:139], v[160:163], v[0:3]
	v_mfma_f32_16x16x32_bf16 v[56:59], v[132:135], v[188:191], v[56:59]
	v_mfma_f32_16x16x32_bf16 v[48:51], v[140:143], v[188:191], v[48:51]
	v_mfma_f32_16x16x32_bf16 v[40:43], v[132:135], v[180:183], v[40:43]
	v_mfma_f32_16x16x32_bf16 v[32:35], v[140:143], v[180:183], v[32:35]
	v_mfma_f32_16x16x32_bf16 v[24:27], v[132:135], v[172:175], v[24:27]
	v_mfma_f32_16x16x32_bf16 v[16:19], v[140:143], v[172:175], v[16:19]
	v_mfma_f32_16x16x32_bf16 v[8:11], v[132:135], v[164:167], v[8:11]
	v_mfma_f32_16x16x32_bf16 v[0:3], v[140:143], v[164:167], v[0:3]
	s_barrier
	s_mov_b32 m0, s42
	s_nop 0
	global_load_lds_dwordx4 v198, s[34:35]
	s_mov_b32 m0, s47
	s_nop 0
	global_load_lds_dwordx4 v194, s[34:35]
	s_setprio 0
	s_add_i32 s36, 0, 0x18000
	s_add_i32 s37, 0, 0x1c000
	v_add_u32_e32 v140, s36, v221
	v_add_u32_e32 v156, s37, v221
	ds_read_b128 v[128:131], v140
	ds_read_b128 v[132:135], v140 offset:1024
	ds_read_b128 v[136:139], v140 offset:2048
	ds_read_b128 v[140:143], v140 offset:3072
	ds_read_b128 v[144:147], v156
	ds_read_b128 v[148:151], v156 offset:1024
	ds_read_b128 v[152:155], v156 offset:2048
	ds_read_b128 v[156:159], v156 offset:3072
	s_add_u32 s34, s34, 0x80000
	s_addc_u32 s35, s35, 0
	s_mov_b32 m0, s48
	ds_read_b128 v[160:163], v225 offset:32768
	ds_read_b128 v[164:167], v225 offset:33792
	ds_read_b128 v[168:171], v225 offset:34816
	ds_read_b128 v[172:175], v225 offset:35840
	ds_read_b128 v[176:179], v225 offset:36864
	ds_read_b128 v[180:183], v225 offset:37888
	ds_read_b128 v[184:187], v225 offset:38912
	ds_read_b128 v[188:191], v225 offset:39936
	global_load_lds_dwordx4 v198, s[34:35]
	s_waitcnt vmcnt(7)
	s_waitcnt lgkmcnt(0)
	s_setprio 1
	s_barrier
	v_mfma_f32_16x16x32_bf16 v[124:127], v[128:131], v[160:163], v[124:127]
	v_mfma_f32_16x16x32_bf16 v[116:119], v[136:139], v[160:163], v[116:119]
	v_mfma_f32_16x16x32_bf16 v[108:111], v[128:131], v[168:171], v[108:111]
	v_mfma_f32_16x16x32_bf16 v[100:103], v[136:139], v[168:171], v[100:103]
	v_mfma_f32_16x16x32_bf16 v[92:95], v[128:131], v[176:179], v[92:95]
	v_mfma_f32_16x16x32_bf16 v[84:87], v[136:139], v[176:179], v[84:87]
	v_mfma_f32_16x16x32_bf16 v[76:79], v[128:131], v[184:187], v[76:79]
	v_mfma_f32_16x16x32_bf16 v[68:71], v[136:139], v[184:187], v[68:71]
	v_mfma_f32_16x16x32_bf16 v[124:127], v[132:135], v[164:167], v[124:127]
	v_mfma_f32_16x16x32_bf16 v[116:119], v[140:143], v[164:167], v[116:119]
	v_mfma_f32_16x16x32_bf16 v[108:111], v[132:135], v[172:175], v[108:111]
	v_mfma_f32_16x16x32_bf16 v[100:103], v[140:143], v[172:175], v[100:103]
	v_mfma_f32_16x16x32_bf16 v[92:95], v[132:135], v[180:183], v[92:95]
	v_mfma_f32_16x16x32_bf16 v[84:87], v[140:143], v[180:183], v[84:87]
	v_mfma_f32_16x16x32_bf16 v[76:79], v[132:135], v[188:191], v[76:79]
	v_mfma_f32_16x16x32_bf16 v[68:71], v[140:143], v[188:191], v[68:71]
	s_mov_b32 m0, s49
	s_nop 0
	global_load_lds_dwordx4 v194, s[34:35]
	v_mfma_f32_16x16x32_bf16 v[120:123], v[144:147], v[160:163], v[120:123]
	v_mfma_f32_16x16x32_bf16 v[112:115], v[152:155], v[160:163], v[112:115]
	v_mfma_f32_16x16x32_bf16 v[104:107], v[144:147], v[168:171], v[104:107]
	v_mfma_f32_16x16x32_bf16 v[96:99], v[152:155], v[168:171], v[96:99]
	v_mfma_f32_16x16x32_bf16 v[88:91], v[144:147], v[176:179], v[88:91]
	v_mfma_f32_16x16x32_bf16 v[80:83], v[152:155], v[176:179], v[80:83]
	v_mfma_f32_16x16x32_bf16 v[72:75], v[144:147], v[184:187], v[72:75]
	v_mfma_f32_16x16x32_bf16 v[64:67], v[152:155], v[184:187], v[64:67]
	v_mfma_f32_16x16x32_bf16 v[120:123], v[148:151], v[164:167], v[120:123]
	v_mfma_f32_16x16x32_bf16 v[112:115], v[156:159], v[164:167], v[112:115]
	v_mfma_f32_16x16x32_bf16 v[104:107], v[148:151], v[172:175], v[104:107]
	v_mfma_f32_16x16x32_bf16 v[96:99], v[156:159], v[172:175], v[96:99]
	v_mfma_f32_16x16x32_bf16 v[88:91], v[148:151], v[180:183], v[88:91]
	v_mfma_f32_16x16x32_bf16 v[80:83], v[156:159], v[180:183], v[80:83]
	v_mfma_f32_16x16x32_bf16 v[72:75], v[148:151], v[188:191], v[72:75]
	v_mfma_f32_16x16x32_bf16 v[64:67], v[156:159], v[188:191], v[64:67]
	s_barrier
; #define PG8_STAGE(bufoff, gbase, voff) do { _Pragma("unroll") for (int _i = 0; _i < 2; ++_i) \
;         __builtin_amdgcn_global_load_lds((const unsigned*)((const char*)(gbase) + (voff)[_i]), (LAS unsigned*)(lds + (bufoff) + ldsw + _i * 8192), 16, 0, ((voff) == voffA ? AUXA : 0)); } while (0)
; #define PG8_LDA(dst, b, h) do { _Pragma("unroll") for (int m = 0; m < 4; ++m) _Pragma("unroll") for (int k = 0; k < 2; ++k) dst[m][k] = *(const LAS bf16x8*)(lds + PG8_SA(b, h) + aoff + m * 2048 + k * 1024); } while (0)
; #define PG8_LDB(dst, b, h) do { _Pragma("unroll") for (int n = 0; n < 2; ++n) _Pragma("unroll") for (int k = 0; k < 2; ++k) dst[n][k] = *(const LAS bf16x8*)(lds + PG8_SB(b, h) + boff + n * 2048 + k * 1024); } while (0)
; #define PG8_MMA(ai, bj, At, Bt) do { __builtin_amdgcn_s_setprio(1); _Pragma("unroll") for (int m = 0; m < 4; ++m) _Pragma("unroll") for (int n = 0; n < 2; ++n) _Pragma("unroll") for (int k = 0; k < 2; ++k) \
;         acc[ai][bj][m][n] = __builtin_amdgcn_mfma_f32_16x16x32_bf16(Bt[n][k], At[m][k], acc[ai][bj][m][n], 0, 0, 0); __builtin_amdgcn_s_setprio(0); } while (0)
; #define PG8_WAIT_V(n) asm volatile("s_waitcnt vmcnt(" #n ")" ::: "memory")
; #define PG8_WAIT_L(n) asm volatile("s_waitcnt lgkmcnt(" #n ")" ::: "memory")
; #define PG8_BAR __builtin_amdgcn_s_barrier()
; #define PG8_SCHED __builtin_amdgcn_sched_barrier(0)
;     ...
;             const bool last = (t == nt - 2);
;             const char* a1 = cA + (size_t)(t + 1) * kstep;
;             const char* a2 = last ? nA : cA + (size_t)(t + 2) * kstep; const char* b2 = last ? nB : cB + (size_t)(t + 2) * kstep;
;             const char* a3 = a2 + kstep; const char* b3 = b2 + kstep;
;             PG8_LDB(B0, 0, 0); PG8_LDB(B1, 0, 1); PG8_SCHED; PG8_LDA(At, 0, 0); PG8_STAGE(PG8_SA(1, 1), a1 + hsA, voffA);
;             if (Epi::NPRE != 0 && last) { E.pre(sv, cur, wr, fr); PG8_WAIT_V(16); } else { PG8_WAIT_V(8); }
;     ...
;             PG8_LDA(At, 1, 1); PG8_STAGE(PG8_SB(1, 0), b3, voffB); PG8_STAGE(PG8_SB(1, 1), b3 + hsB, voffB); PG8_STAGE(PG8_SA(1, 0), a3, voffA);
;             PG8_WAIT_V(8); PG8_WAIT_L(0); PG8_BAR; PG8_MMA(1, 0, At, B0); PG8_MMA(1, 1, At, B1); PG8_BAR; PG8_SCHED;
;         }
	s_setprio 0
	s_add_i32 s34, s36, s5
	s_mov_b32 m0, s34
	ds_read_b128 v[160:163], v225 offset:49152
	ds_read_b128 v[164:167], v225 offset:50176
	ds_read_b128 v[168:171], v225 offset:51200
	ds_read_b128 v[172:175], v225 offset:52224
	ds_read_b128 v[176:179], v225 offset:53248
	ds_read_b128 v[180:183], v225 offset:54272
	ds_read_b128 v[184:187], v225 offset:55296
	ds_read_b128 v[188:191], v225 offset:56320
	global_load_lds_dwordx4 v196, s[98:99]
	s_add_i32 m0, s34, 0x2000
	s_add_u32 s30, s30, 0x80080
	s_addc_u32 s31, s31, 0
	s_add_i32 s34, s37, s5
	global_load_lds_dwordx4 v192, s[98:99]
	s_mov_b32 m0, s34
	s_nop 0
	global_load_lds_dwordx4 v196, s[30:31]
	s_waitcnt vmcnt(5)
	s_waitcnt lgkmcnt(0)
	s_setprio 1
	s_barrier
	v_mfma_f32_16x16x32_bf16 v[60:63], v[128:131], v[160:163], v[60:63]
	v_mfma_f32_16x16x32_bf16 v[52:55], v[136:139], v[160:163], v[52:55]
	v_mfma_f32_16x16x32_bf16 v[44:47], v[128:131], v[168:171], v[44:47]
	v_mfma_f32_16x16x32_bf16 v[36:39], v[136:139], v[168:171], v[36:39]
	v_mfma_f32_16x16x32_bf16 v[28:31], v[128:131], v[176:179], v[28:31]
	v_mfma_f32_16x16x32_bf16 v[20:23], v[136:139], v[176:179], v[20:23]
	v_mfma_f32_16x16x32_bf16 v[12:15], v[128:131], v[184:187], v[12:15]
	v_mfma_f32_16x16x32_bf16 v[4:7], v[136:139], v[184:187], v[4:7]
	v_mfma_f32_16x16x32_bf16 v[60:63], v[132:135], v[164:167], v[60:63]
	v_mfma_f32_16x16x32_bf16 v[52:55], v[140:143], v[164:167], v[52:55]
	v_mfma_f32_16x16x32_bf16 v[44:47], v[132:135], v[172:175], v[44:47]
	v_mfma_f32_16x16x32_bf16 v[36:39], v[140:143], v[172:175], v[36:39]
	v_mfma_f32_16x16x32_bf16 v[28:31], v[132:135], v[180:183], v[28:31]
	v_mfma_f32_16x16x32_bf16 v[20:23], v[140:143], v[180:183], v[20:23]
	v_mfma_f32_16x16x32_bf16 v[12:15], v[132:135], v[188:191], v[12:15]
	v_mfma_f32_16x16x32_bf16 v[4:7], v[140:143], v[188:191], v[4:7]
	s_add_i32 m0, s34, 0x2000
	s_nop 0
	global_load_lds_dwordx4 v192, s[30:31]
	v_mfma_f32_16x16x32_bf16 v[56:59], v[144:147], v[160:163], v[56:59]
	v_mfma_f32_16x16x32_bf16 v[48:51], v[152:155], v[160:163], v[48:51]
	v_mfma_f32_16x16x32_bf16 v[40:43], v[144:147], v[168:171], v[40:43]
	v_mfma_f32_16x16x32_bf16 v[32:35], v[152:155], v[168:171], v[32:35]
	v_mfma_f32_16x16x32_bf16 v[24:27], v[144:147], v[176:179], v[24:27]
	v_mfma_f32_16x16x32_bf16 v[16:19], v[152:155], v[176:179], v[16:19]
	v_mfma_f32_16x16x32_bf16 v[8:11], v[144:147], v[184:187], v[8:11]
	v_mfma_f32_16x16x32_bf16 v[0:3], v[152:155], v[184:187], v[0:3]
	v_mfma_f32_16x16x32_bf16 v[56:59], v[148:151], v[164:167], v[56:59]
	v_mfma_f32_16x16x32_bf16 v[48:51], v[156:159], v[164:167], v[48:51]
	v_mfma_f32_16x16x32_bf16 v[40:43], v[148:151], v[172:175], v[40:43]
	v_mfma_f32_16x16x32_bf16 v[32:35], v[156:159], v[172:175], v[32:35]
	v_mfma_f32_16x16x32_bf16 v[24:27], v[148:151], v[180:183], v[24:27]
	v_mfma_f32_16x16x32_bf16 v[16:19], v[156:159], v[180:183], v[16:19]
	v_mfma_f32_16x16x32_bf16 v[8:11], v[148:151], v[188:191], v[8:11]
	v_mfma_f32_16x16x32_bf16 v[0:3], v[156:159], v[188:191], v[0:3]
	s_barrier
	s_setprio 0
	s_add_u32 s28, s28, 0x100
	s_addc_u32 s29, s29, 0
	s_add_u32 s60, s60, 0x100
	s_addc_u32 s61, s61, 0
	s_cmp_ge_i32 s62, s51
	s_cbranch_scc1 .LBB0_1194
.LBB0_1185:
	s_add_u32 s98, s28, 0xfff80000
	s_addc_u32 s99, s29, -1
	s_mov_b32 m0, s52
	s_nop 0
	global_load_lds_dwordx4 v198, s[98:99]
	s_mov_b32 m0, s53
	s_nop 0
	global_load_lds_dwordx4 v194, s[98:99]
	ds_read_b128 v[144:147], v223
	ds_read_b128 v[148:151], v223 offset:1024
	ds_read_b128 v[152:155], v223 offset:2048
	ds_read_b128 v[156:159], v223 offset:3072
	ds_read_b128 v[128:131], v224
	ds_read_b128 v[132:135], v224 offset:1024
	ds_read_b128 v[136:139], v224 offset:2048
	ds_read_b128 v[140:143], v224 offset:3072
	s_cmp_eq_u32 s54, s62
	s_cselect_b64 s[30:31], -1, 0
	s_cmp_lg_u32 s54, s62
	s_cselect_b64 s[36:37], -1, 0
	s_add_i32 m0, s42, 0xc000
	ds_read_b128 v[184:187], v225
	ds_read_b128 v[188:191], v225 offset:1024
	ds_read_b128 v[176:179], v225 offset:2048
	ds_read_b128 v[180:183], v225 offset:3072
	ds_read_b128 v[168:171], v225 offset:4096
	ds_read_b128 v[172:175], v225 offset:5120
	ds_read_b128 v[160:163], v225 offset:6144
	ds_read_b128 v[164:167], v225 offset:7168
	global_load_lds_dwordx4 v200, s[28:29]
	s_mov_b64 s[34:35], -1
	s_and_b64 vcc, exec, s[36:37]
	s_cbranch_vccz .LBB0_1187
	s_waitcnt vmcnt(7)
	s_mov_b64 s[34:35], 0
; #define PG8_STAGE(bufoff, gbase, voff) do { _Pragma("unroll") for (int _i = 0; _i < 2; ++_i) \
;         __builtin_amdgcn_global_load_lds((const unsigned*)((const char*)(gbase) + (voff)[_i]), (LAS unsigned*)(lds + (bufoff) + ldsw + _i * 8192), 16, 0, ((voff) == voffA ? AUXA : 0)); } while (0)
; #define PG8_LDA(dst, b, h) do { _Pragma("unroll") for (int m = 0; m < 4; ++m) _Pragma("unroll") for (int k = 0; k < 2; ++k) dst[m][k] = *(const LAS bf16x8*)(lds + PG8_SA(b, h) + aoff + m * 2048 + k * 1024); } while (0)
; #define PG8_MMA(ai, bj, At, Bt) do { __builtin_amdgcn_s_setprio(1); _Pragma("unroll") for (int m = 0; m < 4; ++m) _Pragma("unroll") for (int n = 0; n < 2; ++n) _Pragma("unroll") for (int k = 0; k < 2; ++k) \
;         acc[ai][bj][m][n] = __builtin_amdgcn_mfma_f32_16x16x32_bf16(Bt[n][k], At[m][k], acc[ai][bj][m][n], 0, 0, 0); __builtin_amdgcn_s_setprio(0); } while (0)
; #define PG8_WAIT_V(n) asm volatile("s_waitcnt vmcnt(" #n ")" ::: "memory")
; #define PG8_WAIT_L(n) asm volatile("s_waitcnt lgkmcnt(" #n ")" ::: "memory")
; #define PG8_BAR __builtin_amdgcn_s_barrier()
; #define PG8_SCHED __builtin_amdgcn_sched_barrier(0)
;     ...
;             if (Epi::NPRE != 0 && last) { E.pre(sv, cur, wr, fr); PG8_WAIT_V(16); } else { PG8_WAIT_V(8); }
;             PG8_WAIT_L(0); PG8_BAR; PG8_MMA(0, 0, At, B0); PG8_MMA(0, 1, At, B1); PG8_BAR; PG8_SCHED;
;             PG8_LDA(At, 0, 1); PG8_STAGE(PG8_SB(0, 0), b2, voffB); PG8_STAGE(PG8_SB(0, 1), b2 + hsB, voffB); PG8_STAGE(PG8_SA(0, 0), a2, voffA);
;             if (Epi::NPRE != 0 && last) { PG8_WAIT_V(16); } else { PG8_WAIT_V(8); }
;             PG8_WAIT_L(0); PG8_BAR; PG8_MMA(1, 0, At, B0); PG8_MMA(1, 1, At, B1); PG8_BAR; PG8_SCHED;
;     __device__ __forceinline__ void pre(float (&sv)[8], const Unit& u, int wr, int fr) const {
; #pragma unroll
;         for (int i = 0; i < 8; ++i) sv[i] = ss[u.pm * 256 + wr * 64 + fr + (i >> 2) * 128 + (i & 3) * 16]; }
.LBB0_1187:
	s_andn2_b64 vcc, exec, s[34:35]
	s_cbranch_vccnz .LBB0_1189
	global_load_dword v235, v[210:211], off
	global_load_dword v233, v[210:211], off offset:64
	global_load_dword v232, v[210:211], off offset:128
	global_load_dword v231, v[210:211], off offset:192
	global_load_dword v230, v[210:211], off offset:512
	global_load_dword v229, v[210:211], off offset:576
	global_load_dword v228, v[210:211], off offset:640
	global_load_dword v227, v[210:211], off offset:704
	s_waitcnt vmcnt(15)
.LBB0_1189:
	s_add_u32 s34, s28, 0xfff80080
	s_addc_u32 s35, s29, -1
	s_waitcnt lgkmcnt(0)
	s_and_b64 s[30:31], s[30:31], exec
	s_cselect_b32 s35, s21, s35
	s_cselect_b32 s34, s23, s34
	s_cselect_b32 s31, s58, s61
	s_cselect_b32 s30, s59, s60
	s_setprio 1
	s_barrier
	v_mfma_f32_16x16x32_bf16 v[124:127], v[144:147], v[184:187], v[124:127]
	v_mfma_f32_16x16x32_bf16 v[116:119], v[152:155], v[184:187], v[116:119]
	v_mfma_f32_16x16x32_bf16 v[108:111], v[144:147], v[176:179], v[108:111]
	v_mfma_f32_16x16x32_bf16 v[100:103], v[152:155], v[176:179], v[100:103]
	v_mfma_f32_16x16x32_bf16 v[92:95], v[144:147], v[168:171], v[92:95]
	v_mfma_f32_16x16x32_bf16 v[84:87], v[152:155], v[168:171], v[84:87]
	v_mfma_f32_16x16x32_bf16 v[76:79], v[144:147], v[160:163], v[76:79]
	v_mfma_f32_16x16x32_bf16 v[68:71], v[152:155], v[160:163], v[68:71]
	v_mfma_f32_16x16x32_bf16 v[124:127], v[148:151], v[188:191], v[124:127]
	v_mfma_f32_16x16x32_bf16 v[116:119], v[156:159], v[188:191], v[116:119]
	v_mfma_f32_16x16x32_bf16 v[108:111], v[148:151], v[180:183], v[108:111]
	v_mfma_f32_16x16x32_bf16 v[100:103], v[156:159], v[180:183], v[100:103]
	v_mfma_f32_16x16x32_bf16 v[92:95], v[148:151], v[172:175], v[92:95]
	v_mfma_f32_16x16x32_bf16 v[84:87], v[156:159], v[172:175], v[84:87]
	v_mfma_f32_16x16x32_bf16 v[76:79], v[148:151], v[164:167], v[76:79]
	v_mfma_f32_16x16x32_bf16 v[68:71], v[156:159], v[164:167], v[68:71]
	s_add_i32 m0, s42, 0xe000
	s_nop 0
	global_load_lds_dwordx4 v202, s[28:29]
	v_mfma_f32_16x16x32_bf16 v[120:123], v[128:131], v[184:187], v[120:123]
	v_mfma_f32_16x16x32_bf16 v[112:115], v[136:139], v[184:187], v[112:115]
	v_mfma_f32_16x16x32_bf16 v[104:107], v[128:131], v[176:179], v[104:107]
	v_mfma_f32_16x16x32_bf16 v[96:99], v[136:139], v[176:179], v[96:99]
	v_mfma_f32_16x16x32_bf16 v[88:91], v[128:131], v[168:171], v[88:91]
	v_mfma_f32_16x16x32_bf16 v[80:83], v[136:139], v[168:171], v[80:83]
	v_mfma_f32_16x16x32_bf16 v[72:75], v[128:131], v[160:163], v[72:75]
	v_mfma_f32_16x16x32_bf16 v[64:67], v[136:139], v[160:163], v[64:67]
	v_mfma_f32_16x16x32_bf16 v[120:123], v[132:135], v[188:191], v[120:123]
	v_mfma_f32_16x16x32_bf16 v[112:115], v[140:143], v[188:191], v[112:115]
	v_mfma_f32_16x16x32_bf16 v[104:107], v[132:135], v[180:183], v[104:107]
	v_mfma_f32_16x16x32_bf16 v[96:99], v[140:143], v[180:183], v[96:99]
	v_mfma_f32_16x16x32_bf16 v[88:91], v[132:135], v[172:175], v[88:91]
	v_mfma_f32_16x16x32_bf16 v[80:83], v[140:143], v[172:175], v[80:83]
	v_mfma_f32_16x16x32_bf16 v[72:75], v[132:135], v[164:167], v[72:75]
	v_mfma_f32_16x16x32_bf16 v[64:67], v[140:143], v[164:167], v[64:67]
	s_barrier
	s_setprio 0
	s_add_u32 s98, s30, s16
	s_addc_u32 s99, s31, s17
	s_add_u32 s100, s34, s16
	s_addc_u32 s101, s35, s17
	s_mov_b32 m0, s43
	s_add_u32 s38, s30, 0x80000
	ds_read_b128 v[184:187], v225 offset:16384
	ds_read_b128 v[188:191], v225 offset:17408
	ds_read_b128 v[176:179], v225 offset:18432
	ds_read_b128 v[180:183], v225 offset:19456
	ds_read_b128 v[168:171], v225 offset:20480
	ds_read_b128 v[172:175], v225 offset:21504
	ds_read_b128 v[160:163], v225 offset:22528
	ds_read_b128 v[164:167], v225 offset:23552
	global_load_lds_dwordx4 v196, s[30:31]
	s_mov_b32 m0, s44
	s_addc_u32 s39, s31, 0
	global_load_lds_dwordx4 v192, s[30:31]
	s_mov_b32 m0, s45
	s_nop 0
	global_load_lds_dwordx4 v196, s[38:39]
	s_mov_b64 s[100:101], s[38:39]
	s_mov_b64 s[38:39], -1
	s_and_b64 vcc, exec, s[36:37]
	s_cbranch_vccz .LBB0_1191
	s_waitcnt vmcnt(5)
	s_mov_b64 s[38:39], 0

; #define PG8_STAGE(bufoff, gbase, voff) do { _Pragma("unroll") for (int _i = 0; _i < 2; ++_i) \
;         __builtin_amdgcn_global_load_lds((const unsigned*)((const char*)(gbase) + (voff)[_i]), (LAS unsigned*)(lds + (bufoff) + ldsw + _i * 8192), 16, 0, ((voff) == voffA ? AUXA : 0)); } while (0)
; #define PG8_LDA(dst, b, h) do { _Pragma("unroll") for (int m = 0; m < 4; ++m) _Pragma("unroll") for (int k = 0; k < 2; ++k) dst[m][k] = *(const LAS bf16x8*)(lds + PG8_SA(b, h) + aoff + m * 2048 + k * 1024); } while (0)
; #define PG8_LDB(dst, b, h) do { _Pragma("unroll") for (int n = 0; n < 2; ++n) _Pragma("unroll") for (int k = 0; k < 2; ++k) dst[n][k] = *(const LAS bf16x8*)(lds + PG8_SB(b, h) + boff + n * 2048 + k * 1024); } while (0)
; #define PG8_MMA(ai, bj, At, Bt) do { __builtin_amdgcn_s_setprio(1); _Pragma("unroll") for (int m = 0; m < 4; ++m) _Pragma("unroll") for (int n = 0; n < 2; ++n) _Pragma("unroll") for (int k = 0; k < 2; ++k) \
;         acc[ai][bj][m][n] = __builtin_amdgcn_mfma_f32_16x16x32_bf16(Bt[n][k], At[m][k], acc[ai][bj][m][n], 0, 0, 0); __builtin_amdgcn_s_setprio(0); } while (0)
; #define PG8_WAIT_V(n) asm volatile("s_waitcnt vmcnt(" #n ")" ::: "memory")
; #define PG8_WAIT_L(n) asm volatile("s_waitcnt lgkmcnt(" #n ")" ::: "memory")
; #define PG8_BAR __builtin_amdgcn_s_barrier()
; #define PG8_SCHED __builtin_amdgcn_sched_barrier(0)
;     ...
;             PG8_LDB(B0, 0, 0); PG8_LDB(B1, 0, 1); PG8_SCHED; PG8_LDA(At, 0, 0); PG8_STAGE(PG8_SA(1, 1), a1 + hsA, voffA);
;             if (Epi::NPRE != 0 && last) { E.pre(sv, cur, wr, fr); PG8_WAIT_V(16); } else { PG8_WAIT_V(8); }
;             PG8_WAIT_L(0); PG8_BAR; PG8_MMA(0, 0, At, B0); PG8_MMA(0, 1, At, B1); PG8_BAR; PG8_SCHED;
;             PG8_LDA(At, 0, 1); PG8_STAGE(PG8_SB(0, 0), b2, voffB); PG8_STAGE(PG8_SB(0, 1), b2 + hsB, voffB); PG8_STAGE(PG8_SA(0, 0), a2, voffA);
;             if (Epi::NPRE != 0 && last) { PG8_WAIT_V(16); } else { PG8_WAIT_V(8); }
;             PG8_WAIT_L(0); PG8_BAR; PG8_MMA(1, 0, At, B0); PG8_MMA(1, 1, At, B1); PG8_BAR; PG8_SCHED;
.LBB0_1267:
	s_add_u32 s98, s34, 0xfff80000
	s_addc_u32 s99, s35, -1
	s_mov_b32 m0, s47
	s_nop 0
	global_load_lds_dwordx4 v152, s[98:99]
	s_mov_b32 m0, s48
	s_nop 0
	global_load_lds_dwordx4 v156, s[98:99]
	ds_read_b128 v[128:131], v189
	ds_read_b128 v[132:135], v189 offset:1024
	ds_read_b128 v[136:139], v189 offset:2048
	ds_read_b128 v[140:143], v189 offset:3072
	ds_read_b128 v[144:147], v190
	ds_read_b128 v[148:151], v190 offset:1024
	ds_read_b128 v[168:171], v190 offset:2048
	ds_read_b128 v[172:175], v190 offset:3072
	s_add_i32 s58, s36, 2
	s_add_u32 s37, s34, 0xfff80080
	s_addc_u32 s38, s35, -1
	s_cmp_eq_u32 s49, s36
	s_cselect_b32 s36, s55, s56
	s_cselect_b32 s39, s21, s38
	s_cselect_b32 s38, s23, s37
	s_cselect_b32 s37, s29, s57
	s_add_i32 m0, s31, 0xc000
	ds_read_b128 v[176:179], v191
	ds_read_b128 v[180:183], v191 offset:1024
	ds_read_b128 v[194:197], v191 offset:2048
	ds_read_b128 v[198:201], v191 offset:3072
	ds_read_b128 v[202:205], v191 offset:4096
	ds_read_b128 v[206:209], v191 offset:5120
	ds_read_b128 v[210:213], v191 offset:6144
	ds_read_b128 v[214:217], v191 offset:7168
	global_load_lds_dwordx4 v160, s[34:35]
	s_waitcnt vmcnt(7)
	s_waitcnt lgkmcnt(0)
	s_setprio 1
	s_barrier
	v_mfma_f32_16x16x32_bf16 v[124:127], v[128:131], v[176:179], v[124:127]
	v_mfma_f32_16x16x32_bf16 v[120:123], v[136:139], v[176:179], v[120:123]
	v_mfma_f32_16x16x32_bf16 v[108:111], v[128:131], v[194:197], v[108:111]
	v_mfma_f32_16x16x32_bf16 v[104:107], v[136:139], v[194:197], v[104:107]
	v_mfma_f32_16x16x32_bf16 v[92:95], v[128:131], v[202:205], v[92:95]
	v_mfma_f32_16x16x32_bf16 v[88:91], v[136:139], v[202:205], v[88:91]
	v_mfma_f32_16x16x32_bf16 v[76:79], v[128:131], v[210:213], v[76:79]
	v_mfma_f32_16x16x32_bf16 v[72:75], v[136:139], v[210:213], v[72:75]
	v_mfma_f32_16x16x32_bf16 v[124:127], v[132:135], v[180:183], v[124:127]
	v_mfma_f32_16x16x32_bf16 v[120:123], v[140:143], v[180:183], v[120:123]
	v_mfma_f32_16x16x32_bf16 v[108:111], v[132:135], v[198:201], v[108:111]
	v_mfma_f32_16x16x32_bf16 v[104:107], v[140:143], v[198:201], v[104:107]
	v_mfma_f32_16x16x32_bf16 v[92:95], v[132:135], v[206:209], v[92:95]
	v_mfma_f32_16x16x32_bf16 v[88:91], v[140:143], v[206:209], v[88:91]
	v_mfma_f32_16x16x32_bf16 v[76:79], v[132:135], v[214:217], v[76:79]
	v_mfma_f32_16x16x32_bf16 v[72:75], v[140:143], v[214:217], v[72:75]
	s_add_i32 m0, s31, 0xe000
	s_nop 0
	global_load_lds_dwordx4 v162, s[34:35]
	v_mfma_f32_16x16x32_bf16 v[116:119], v[144:147], v[176:179], v[116:119]
	v_mfma_f32_16x16x32_bf16 v[112:115], v[168:171], v[176:179], v[112:115]
	v_mfma_f32_16x16x32_bf16 v[100:103], v[144:147], v[194:197], v[100:103]
	v_mfma_f32_16x16x32_bf16 v[96:99], v[168:171], v[194:197], v[96:99]
	v_mfma_f32_16x16x32_bf16 v[84:87], v[144:147], v[202:205], v[84:87]
	v_mfma_f32_16x16x32_bf16 v[80:83], v[168:171], v[202:205], v[80:83]
	v_mfma_f32_16x16x32_bf16 v[68:71], v[144:147], v[210:213], v[68:71]
	v_mfma_f32_16x16x32_bf16 v[64:67], v[168:171], v[210:213], v[64:67]
	v_mfma_f32_16x16x32_bf16 v[116:119], v[148:151], v[180:183], v[116:119]
	v_mfma_f32_16x16x32_bf16 v[112:115], v[172:175], v[180:183], v[112:115]
	v_mfma_f32_16x16x32_bf16 v[100:103], v[148:151], v[198:201], v[100:103]
	v_mfma_f32_16x16x32_bf16 v[96:99], v[172:175], v[198:201], v[96:99]
	v_mfma_f32_16x16x32_bf16 v[84:87], v[148:151], v[206:209], v[84:87]
	v_mfma_f32_16x16x32_bf16 v[80:83], v[172:175], v[206:209], v[80:83]
	v_mfma_f32_16x16x32_bf16 v[68:71], v[148:151], v[214:217], v[68:71]
	v_mfma_f32_16x16x32_bf16 v[64:67], v[172:175], v[214:217], v[64:67]
	s_barrier
	s_setprio 0
	s_add_u32 s98, s36, s16
	s_addc_u32 s99, s37, s17
	s_add_u32 s100, s38, s16
	s_addc_u32 s101, s39, s17
	s_add_i32 s59, s53, s41
	s_mov_b32 m0, s59
	ds_read_b128 v[176:179], v191 offset:16384
	ds_read_b128 v[180:183], v191 offset:17408
	ds_read_b128 v[194:197], v191 offset:18432
	ds_read_b128 v[198:201], v191 offset:19456
	ds_read_b128 v[202:205], v191 offset:20480
	ds_read_b128 v[206:209], v191 offset:21504
	ds_read_b128 v[210:213], v191 offset:22528
	ds_read_b128 v[214:217], v191 offset:23552
	global_load_lds_dwordx4 v154, s[36:37]
	s_add_i32 m0, s59, 0x2000
	s_add_u32 s60, s36, 0x80000
	s_addc_u32 s61, s37, 0
	s_add_i32 s59, s54, s41
	global_load_lds_dwordx4 v158, s[36:37]
	s_mov_b32 m0, s59
	s_nop 0
	global_load_lds_dwordx4 v154, s[60:61]
	s_waitcnt vmcnt(5)
	s_waitcnt lgkmcnt(0)
	s_setprio 1
	s_barrier
	v_mfma_f32_16x16x32_bf16 v[60:63], v[128:131], v[176:179], v[60:63]
	v_mfma_f32_16x16x32_bf16 v[56:59], v[136:139], v[176:179], v[56:59]
	v_mfma_f32_16x16x32_bf16 v[44:47], v[128:131], v[194:197], v[44:47]
	v_mfma_f32_16x16x32_bf16 v[40:43], v[136:139], v[194:197], v[40:43]
	v_mfma_f32_16x16x32_bf16 v[28:31], v[128:131], v[202:205], v[28:31]
	v_mfma_f32_16x16x32_bf16 v[24:27], v[136:139], v[202:205], v[24:27]
	v_mfma_f32_16x16x32_bf16 v[12:15], v[128:131], v[210:213], v[12:15]
	v_mfma_f32_16x16x32_bf16 v[8:11], v[136:139], v[210:213], v[8:11]
	v_mfma_f32_16x16x32_bf16 v[60:63], v[132:135], v[180:183], v[60:63]
	v_mfma_f32_16x16x32_bf16 v[56:59], v[140:143], v[180:183], v[56:59]
	v_mfma_f32_16x16x32_bf16 v[44:47], v[132:135], v[198:201], v[44:47]
	v_mfma_f32_16x16x32_bf16 v[40:43], v[140:143], v[198:201], v[40:43]
	v_mfma_f32_16x16x32_bf16 v[28:31], v[132:135], v[206:209], v[28:31]
	v_mfma_f32_16x16x32_bf16 v[24:27], v[140:143], v[206:209], v[24:27]
	v_mfma_f32_16x16x32_bf16 v[12:15], v[132:135], v[214:217], v[12:15]
	v_mfma_f32_16x16x32_bf16 v[8:11], v[140:143], v[214:217], v[8:11]
	s_add_i32 m0, s59, 0x2000
	s_nop 0
	global_load_lds_dwordx4 v158, s[60:61]
	v_mfma_f32_16x16x32_bf16 v[52:55], v[144:147], v[176:179], v[52:55]
	v_mfma_f32_16x16x32_bf16 v[48:51], v[168:171], v[176:179], v[48:51]
	v_mfma_f32_16x16x32_bf16 v[36:39], v[144:147], v[194:197], v[36:39]
	v_mfma_f32_16x16x32_bf16 v[32:35], v[168:171], v[194:197], v[32:35]
	v_mfma_f32_16x16x32_bf16 v[20:23], v[144:147], v[202:205], v[20:23]
	v_mfma_f32_16x16x32_bf16 v[16:19], v[168:171], v[202:205], v[16:19]
	v_mfma_f32_16x16x32_bf16 v[4:7], v[144:147], v[210:213], v[4:7]
	v_mfma_f32_16x16x32_bf16 v[0:3], v[168:171], v[210:213], v[0:3]
	v_mfma_f32_16x16x32_bf16 v[52:55], v[148:151], v[180:183], v[52:55]
	v_mfma_f32_16x16x32_bf16 v[48:51], v[172:175], v[180:183], v[48:51]
	v_mfma_f32_16x16x32_bf16 v[36:39], v[148:151], v[198:201], v[36:39]
	v_mfma_f32_16x16x32_bf16 v[32:35], v[172:175], v[198:201], v[32:35]
	v_mfma_f32_16x16x32_bf16 v[20:23], v[148:151], v[206:209], v[20:23]
	v_mfma_f32_16x16x32_bf16 v[16:19], v[172:175], v[206:209], v[16:19]
	v_mfma_f32_16x16x32_bf16 v[4:7], v[148:151], v[214:217], v[4:7]
	v_mfma_f32_16x16x32_bf16 v[0:3], v[172:175], v[214:217], v[0:3]
	s_barrier
; #define PG8_STAGE(bufoff, gbase, voff) do { _Pragma("unroll") for (int _i = 0; _i < 2; ++_i) \
;         __builtin_amdgcn_global_load_lds((const unsigned*)((const char*)(gbase) + (voff)[_i]), (LAS unsigned*)(lds + (bufoff) + ldsw + _i * 8192), 16, 0, ((voff) == voffA ? AUXA : 0)); } while (0)
; #define PG8_LDA(dst, b, h) do { _Pragma("unroll") for (int m = 0; m < 4; ++m) _Pragma("unroll") for (int k = 0; k < 2; ++k) dst[m][k] = *(const LAS bf16x8*)(lds + PG8_SA(b, h) + aoff + m * 2048 + k * 1024); } while (0)
; #define PG8_LDB(dst, b, h) do { _Pragma("unroll") for (int n = 0; n < 2; ++n) _Pragma("unroll") for (int k = 0; k < 2; ++k) dst[n][k] = *(const LAS bf16x8*)(lds + PG8_SB(b, h) + boff + n * 2048 + k * 1024); } while (0)
; #define PG8_MMA(ai, bj, At, Bt) do { __builtin_amdgcn_s_setprio(1); _Pragma("unroll") for (int m = 0; m < 4; ++m) _Pragma("unroll") for (int n = 0; n < 2; ++n) _Pragma("unroll") for (int k = 0; k < 2; ++k) \
;         acc[ai][bj][m][n] = __builtin_amdgcn_mfma_f32_16x16x32_bf16(Bt[n][k], At[m][k], acc[ai][bj][m][n], 0, 0, 0); __builtin_amdgcn_s_setprio(0); } while (0)
; #define PG8_WAIT_V(n) asm volatile("s_waitcnt vmcnt(" #n ")" ::: "memory")
; #define PG8_WAIT_L(n) asm volatile("s_waitcnt lgkmcnt(" #n ")" ::: "memory")
; #define PG8_BAR __builtin_amdgcn_s_barrier()
; #define PG8_SCHED __builtin_amdgcn_sched_barrier(0)
;     ...
;             PG8_LDB(B0, 1, 0); PG8_LDB(B1, 1, 1); PG8_SCHED; PG8_LDA(At, 1, 0); PG8_STAGE(PG8_SA(0, 1), a2 + hsA, voffA);
;             PG8_WAIT_V(8); PG8_WAIT_L(0); PG8_BAR; PG8_MMA(0, 0, At, B0); PG8_MMA(0, 1, At, B1); PG8_BAR; PG8_SCHED;
;             PG8_LDA(At, 1, 1); PG8_STAGE(PG8_SB(1, 0), b3, voffB); PG8_STAGE(PG8_SB(1, 1), b3 + hsB, voffB); PG8_STAGE(PG8_SA(1, 0), a3, voffA);
;             PG8_WAIT_V(8); PG8_WAIT_L(0); PG8_BAR; PG8_MMA(1, 0, At, B0); PG8_MMA(1, 1, At, B1); PG8_BAR; PG8_SCHED;
;         }
	s_mov_b32 m0, s31
	s_nop 0
	global_load_lds_dwordx4 v152, s[38:39]
	s_mov_b32 m0, s42
	s_nop 0
	global_load_lds_dwordx4 v156, s[38:39]
	s_setprio 0
	s_add_i32 s59, 0, 0x18000
	s_add_i32 s60, 0, 0x1c000
	v_add_u32_e32 v140, s59, v187
	v_add_u32_e32 v172, s60, v187
	ds_read_b128 v[128:131], v140
	ds_read_b128 v[132:135], v140 offset:1024
	ds_read_b128 v[136:139], v140 offset:2048
	ds_read_b128 v[140:143], v140 offset:3072
	ds_read_b128 v[144:147], v172
	ds_read_b128 v[148:151], v172 offset:1024
	ds_read_b128 v[168:171], v172 offset:2048
	ds_read_b128 v[172:175], v172 offset:3072
	s_add_u32 s38, s38, 0x80000
	s_addc_u32 s39, s39, 0
	s_mov_b32 m0, s43
	ds_read_b128 v[176:179], v191 offset:32768
	ds_read_b128 v[180:183], v191 offset:33792
	ds_read_b128 v[194:197], v191 offset:34816
	ds_read_b128 v[198:201], v191 offset:35840
	ds_read_b128 v[202:205], v191 offset:36864
	ds_read_b128 v[206:209], v191 offset:37888
	ds_read_b128 v[210:213], v191 offset:38912
	ds_read_b128 v[214:217], v191 offset:39936
	global_load_lds_dwordx4 v152, s[38:39]
	s_waitcnt vmcnt(7)
	s_waitcnt lgkmcnt(0)
	s_setprio 1
	s_barrier
	v_mfma_f32_16x16x32_bf16 v[124:127], v[128:131], v[176:179], v[124:127]
	v_mfma_f32_16x16x32_bf16 v[120:123], v[136:139], v[176:179], v[120:123]
	v_mfma_f32_16x16x32_bf16 v[108:111], v[128:131], v[194:197], v[108:111]
	v_mfma_f32_16x16x32_bf16 v[104:107], v[136:139], v[194:197], v[104:107]
	v_mfma_f32_16x16x32_bf16 v[92:95], v[128:131], v[202:205], v[92:95]
	v_mfma_f32_16x16x32_bf16 v[88:91], v[136:139], v[202:205], v[88:91]
	v_mfma_f32_16x16x32_bf16 v[76:79], v[128:131], v[210:213], v[76:79]
	v_mfma_f32_16x16x32_bf16 v[72:75], v[136:139], v[210:213], v[72:75]
	v_mfma_f32_16x16x32_bf16 v[124:127], v[132:135], v[180:183], v[124:127]
	v_mfma_f32_16x16x32_bf16 v[120:123], v[140:143], v[180:183], v[120:123]
	v_mfma_f32_16x16x32_bf16 v[108:111], v[132:135], v[198:201], v[108:111]
	v_mfma_f32_16x16x32_bf16 v[104:107], v[140:143], v[198:201], v[104:107]
	v_mfma_f32_16x16x32_bf16 v[92:95], v[132:135], v[206:209], v[92:95]
	v_mfma_f32_16x16x32_bf16 v[88:91], v[140:143], v[206:209], v[88:91]
	v_mfma_f32_16x16x32_bf16 v[76:79], v[132:135], v[214:217], v[76:79]
	v_mfma_f32_16x16x32_bf16 v[72:75], v[140:143], v[214:217], v[72:75]
	s_mov_b32 m0, s44
	s_nop 0
	global_load_lds_dwordx4 v156, s[38:39]
	v_mfma_f32_16x16x32_bf16 v[116:119], v[144:147], v[176:179], v[116:119]
	v_mfma_f32_16x16x32_bf16 v[112:115], v[168:171], v[176:179], v[112:115]
	v_mfma_f32_16x16x32_bf16 v[100:103], v[144:147], v[194:197], v[100:103]
	v_mfma_f32_16x16x32_bf16 v[96:99], v[168:171], v[194:197], v[96:99]
	v_mfma_f32_16x16x32_bf16 v[84:87], v[144:147], v[202:205], v[84:87]
	v_mfma_f32_16x16x32_bf16 v[80:83], v[168:171], v[202:205], v[80:83]
	v_mfma_f32_16x16x32_bf16 v[68:71], v[144:147], v[210:213], v[68:71]
	v_mfma_f32_16x16x32_bf16 v[64:67], v[168:171], v[210:213], v[64:67]
	v_mfma_f32_16x16x32_bf16 v[116:119], v[148:151], v[180:183], v[116:119]
	v_mfma_f32_16x16x32_bf16 v[112:115], v[172:175], v[180:183], v[112:115]
	v_mfma_f32_16x16x32_bf16 v[100:103], v[148:151], v[198:201], v[100:103]
	v_mfma_f32_16x16x32_bf16 v[96:99], v[172:175], v[198:201], v[96:99]
	v_mfma_f32_16x16x32_bf16 v[84:87], v[148:151], v[206:209], v[84:87]
	v_mfma_f32_16x16x32_bf16 v[80:83], v[172:175], v[206:209], v[80:83]
	v_mfma_f32_16x16x32_bf16 v[68:71], v[148:151], v[214:217], v[68:71]
	v_mfma_f32_16x16x32_bf16 v[64:67], v[172:175], v[214:217], v[64:67]
	s_barrier
	s_setprio 0
	s_add_i32 s38, s59, s41
	s_mov_b32 m0, s38
	ds_read_b128 v[176:179], v191 offset:49152
	ds_read_b128 v[180:183], v191 offset:50176
	ds_read_b128 v[194:197], v191 offset:51200
	ds_read_b128 v[198:201], v191 offset:52224
	ds_read_b128 v[202:205], v191 offset:53248
	ds_read_b128 v[206:209], v191 offset:54272
	ds_read_b128 v[210:213], v191 offset:55296
	ds_read_b128 v[214:217], v191 offset:56320
	global_load_lds_dwordx4 v154, s[98:99]
	s_add_i32 m0, s38, 0x2000
	s_add_u32 s36, s36, 0x80080
	s_addc_u32 s37, s37, 0
	s_add_i32 s38, s60, s41
	global_load_lds_dwordx4 v158, s[98:99]
	s_mov_b32 m0, s38
	s_nop 0
	global_load_lds_dwordx4 v154, s[36:37]
	s_waitcnt vmcnt(5)
	s_waitcnt lgkmcnt(0)
	s_setprio 1
	s_barrier
	v_mfma_f32_16x16x32_bf16 v[60:63], v[128:131], v[176:179], v[60:63]
	v_mfma_f32_16x16x32_bf16 v[56:59], v[136:139], v[176:179], v[56:59]
	v_mfma_f32_16x16x32_bf16 v[44:47], v[128:131], v[194:197], v[44:47]
	v_mfma_f32_16x16x32_bf16 v[40:43], v[136:139], v[194:197], v[40:43]
	v_mfma_f32_16x16x32_bf16 v[28:31], v[128:131], v[202:205], v[28:31]
	v_mfma_f32_16x16x32_bf16 v[24:27], v[136:139], v[202:205], v[24:27]
	v_mfma_f32_16x16x32_bf16 v[12:15], v[128:131], v[210:213], v[12:15]
	v_mfma_f32_16x16x32_bf16 v[8:11], v[136:139], v[210:213], v[8:11]
	v_mfma_f32_16x16x32_bf16 v[60:63], v[132:135], v[180:183], v[60:63]
	v_mfma_f32_16x16x32_bf16 v[56:59], v[140:143], v[180:183], v[56:59]
	v_mfma_f32_16x16x32_bf16 v[44:47], v[132:135], v[198:201], v[44:47]
	v_mfma_f32_16x16x32_bf16 v[40:43], v[140:143], v[198:201], v[40:43]
	v_mfma_f32_16x16x32_bf16 v[28:31], v[132:135], v[206:209], v[28:31]
	v_mfma_f32_16x16x32_bf16 v[24:27], v[140:143], v[206:209], v[24:27]
	v_mfma_f32_16x16x32_bf16 v[12:15], v[132:135], v[214:217], v[12:15]
	v_mfma_f32_16x16x32_bf16 v[8:11], v[140:143], v[214:217], v[8:11]
	s_add_i32 m0, s38, 0x2000
	s_nop 0
	global_load_lds_dwordx4 v158, s[36:37]
	v_mfma_f32_16x16x32_bf16 v[52:55], v[144:147], v[176:179], v[52:55]
	v_mfma_f32_16x16x32_bf16 v[48:51], v[168:171], v[176:179], v[48:51]
	v_mfma_f32_16x16x32_bf16 v[36:39], v[144:147], v[194:197], v[36:39]
	v_mfma_f32_16x16x32_bf16 v[32:35], v[168:171], v[194:197], v[32:35]
	v_mfma_f32_16x16x32_bf16 v[20:23], v[144:147], v[202:205], v[20:23]
	v_mfma_f32_16x16x32_bf16 v[16:19], v[168:171], v[202:205], v[16:19]
	v_mfma_f32_16x16x32_bf16 v[4:7], v[144:147], v[210:213], v[4:7]
	v_mfma_f32_16x16x32_bf16 v[0:3], v[168:171], v[210:213], v[0:3]
	v_mfma_f32_16x16x32_bf16 v[52:55], v[148:151], v[180:183], v[52:55]
	v_mfma_f32_16x16x32_bf16 v[48:51], v[172:175], v[180:183], v[48:51]
	v_mfma_f32_16x16x32_bf16 v[36:39], v[148:151], v[198:201], v[36:39]
	v_mfma_f32_16x16x32_bf16 v[32:35], v[172:175], v[198:201], v[32:35]
	v_mfma_f32_16x16x32_bf16 v[20:23], v[148:151], v[206:209], v[20:23]
	v_mfma_f32_16x16x32_bf16 v[16:19], v[172:175], v[206:209], v[16:19]
	v_mfma_f32_16x16x32_bf16 v[4:7], v[148:151], v[214:217], v[4:7]
	v_mfma_f32_16x16x32_bf16 v[0:3], v[172:175], v[214:217], v[0:3]
	s_barrier
	s_setprio 0
	s_add_u32 s34, s34, 0x100
	s_addc_u32 s35, s35, 0
	s_add_u32 s56, s56, 0x100
	s_addc_u32 s57, s57, 0
	s_cmp_ge_i32 s58, s46
	s_mov_b32 s36, s58
	s_cbranch_scc0 .LBB0_1267

; #define PG8_STAGE(bufoff, gbase, voff) do { _Pragma("unroll") for (int _i = 0; _i < 2; ++_i) \
;         __builtin_amdgcn_global_load_lds((const unsigned*)((const char*)(gbase) + (voff)[_i]), (LAS unsigned*)(lds + (bufoff) + ldsw + _i * 8192), 16, 0, ((voff) == voffA ? AUXA : 0)); } while (0)
; #define PG8_LDA(dst, b, h) do { _Pragma("unroll") for (int m = 0; m < 4; ++m) _Pragma("unroll") for (int k = 0; k < 2; ++k) dst[m][k] = *(const LAS bf16x8*)(lds + PG8_SA(b, h) + aoff + m * 2048 + k * 1024); } while (0)
; #define PG8_LDB(dst, b, h) do { _Pragma("unroll") for (int n = 0; n < 2; ++n) _Pragma("unroll") for (int k = 0; k < 2; ++k) dst[n][k] = *(const LAS bf16x8*)(lds + PG8_SB(b, h) + boff + n * 2048 + k * 1024); } while (0)
; #define PG8_MMA(ai, bj, At, Bt) do { __builtin_amdgcn_s_setprio(1); _Pragma("unroll") for (int m = 0; m < 4; ++m) _Pragma("unroll") for (int n = 0; n < 2; ++n) _Pragma("unroll") for (int k = 0; k < 2; ++k) \
;         acc[ai][bj][m][n] = __builtin_amdgcn_mfma_f32_16x16x32_bf16(Bt[n][k], At[m][k], acc[ai][bj][m][n], 0, 0, 0); __builtin_amdgcn_s_setprio(0); } while (0)
; #define PG8_WAIT_V(n) asm volatile("s_waitcnt vmcnt(" #n ")" ::: "memory")
; #define PG8_WAIT_L(n) asm volatile("s_waitcnt lgkmcnt(" #n ")" ::: "memory")
; #define PG8_BAR __builtin_amdgcn_s_barrier()
; #define PG8_SCHED __builtin_amdgcn_sched_barrier(0)
;     ...
;             PG8_WAIT_L(0); PG8_BAR; PG8_MMA(1, 0, At, B0); PG8_MMA(1, 1, At, B1); PG8_BAR; PG8_SCHED;
;             PG8_LDB(B0, 1, 0); PG8_LDB(B1, 1, 1); PG8_SCHED; PG8_LDA(At, 1, 0); PG8_STAGE(PG8_SA(0, 1), a2 + hsA, voffA);
;             PG8_WAIT_V(8); PG8_WAIT_L(0); PG8_BAR; PG8_MMA(0, 0, At, B0); PG8_MMA(0, 1, At, B1); PG8_BAR; PG8_SCHED;
.LBB0_1355:
	s_waitcnt lgkmcnt(0)
	s_add_i32 s61, s61, 2
	s_setprio 1
	s_barrier
	v_mfma_f32_16x16x32_bf16 v[60:63], v[144:147], v[184:187], v[60:63]
	v_mfma_f32_16x16x32_bf16 v[52:55], v[152:155], v[184:187], v[52:55]
	v_mfma_f32_16x16x32_bf16 v[44:47], v[144:147], v[176:179], v[44:47]
	v_mfma_f32_16x16x32_bf16 v[36:39], v[152:155], v[176:179], v[36:39]
	v_mfma_f32_16x16x32_bf16 v[28:31], v[144:147], v[168:171], v[28:31]
	v_mfma_f32_16x16x32_bf16 v[20:23], v[152:155], v[168:171], v[20:23]
	v_mfma_f32_16x16x32_bf16 v[12:15], v[144:147], v[160:163], v[12:15]
	v_mfma_f32_16x16x32_bf16 v[4:7], v[152:155], v[160:163], v[4:7]
	v_mfma_f32_16x16x32_bf16 v[60:63], v[148:151], v[188:191], v[60:63]
	v_mfma_f32_16x16x32_bf16 v[52:55], v[156:159], v[188:191], v[52:55]
	v_mfma_f32_16x16x32_bf16 v[44:47], v[148:151], v[180:183], v[44:47]
	v_mfma_f32_16x16x32_bf16 v[36:39], v[156:159], v[180:183], v[36:39]
	v_mfma_f32_16x16x32_bf16 v[28:31], v[148:151], v[172:175], v[28:31]
	v_mfma_f32_16x16x32_bf16 v[20:23], v[156:159], v[172:175], v[20:23]
	v_mfma_f32_16x16x32_bf16 v[12:15], v[148:151], v[164:167], v[12:15]
	v_mfma_f32_16x16x32_bf16 v[4:7], v[156:159], v[164:167], v[4:7]
	s_mov_b32 m0, s44
	s_nop 0
	global_load_lds_dwordx4 v192, s[100:101]
	v_mfma_f32_16x16x32_bf16 v[56:59], v[128:131], v[184:187], v[56:59]
	v_mfma_f32_16x16x32_bf16 v[48:51], v[136:139], v[184:187], v[48:51]
	v_mfma_f32_16x16x32_bf16 v[40:43], v[128:131], v[176:179], v[40:43]
	v_mfma_f32_16x16x32_bf16 v[32:35], v[136:139], v[176:179], v[32:35]
	v_mfma_f32_16x16x32_bf16 v[24:27], v[128:131], v[168:171], v[24:27]
	v_mfma_f32_16x16x32_bf16 v[16:19], v[136:139], v[168:171], v[16:19]
	v_mfma_f32_16x16x32_bf16 v[8:11], v[128:131], v[160:163], v[8:11]
	v_mfma_f32_16x16x32_bf16 v[0:3], v[136:139], v[160:163], v[0:3]
	v_mfma_f32_16x16x32_bf16 v[56:59], v[132:135], v[188:191], v[56:59]
	v_mfma_f32_16x16x32_bf16 v[48:51], v[140:143], v[188:191], v[48:51]
	v_mfma_f32_16x16x32_bf16 v[40:43], v[132:135], v[180:183], v[40:43]
	v_mfma_f32_16x16x32_bf16 v[32:35], v[140:143], v[180:183], v[32:35]
	v_mfma_f32_16x16x32_bf16 v[24:27], v[132:135], v[172:175], v[24:27]
	v_mfma_f32_16x16x32_bf16 v[16:19], v[140:143], v[172:175], v[16:19]
	v_mfma_f32_16x16x32_bf16 v[8:11], v[132:135], v[164:167], v[8:11]
	v_mfma_f32_16x16x32_bf16 v[0:3], v[140:143], v[164:167], v[0:3]
	s_barrier
	s_mov_b32 m0, s40
	s_nop 0
	global_load_lds_dwordx4 v198, s[30:31]
	s_mov_b32 m0, s45
	s_nop 0
	global_load_lds_dwordx4 v194, s[30:31]
	s_setprio 0
	s_add_i32 s34, 0, 0x18000
	s_add_i32 s35, 0, 0x1c000
	v_add_u32_e32 v140, s34, v221
	v_add_u32_e32 v156, s35, v221
	ds_read_b128 v[128:131], v140
	ds_read_b128 v[132:135], v140 offset:1024
	ds_read_b128 v[136:139], v140 offset:2048
	ds_read_b128 v[140:143], v140 offset:3072
	ds_read_b128 v[144:147], v156
	ds_read_b128 v[148:151], v156 offset:1024
	ds_read_b128 v[152:155], v156 offset:2048
	ds_read_b128 v[156:159], v156 offset:3072
	s_add_u32 s30, s30, 0x80000
	s_addc_u32 s31, s31, 0
	s_mov_b32 m0, s46
	ds_read_b128 v[160:163], v225 offset:32768
	ds_read_b128 v[164:167], v225 offset:33792
	ds_read_b128 v[168:171], v225 offset:34816
	ds_read_b128 v[172:175], v225 offset:35840
	ds_read_b128 v[176:179], v225 offset:36864
	ds_read_b128 v[180:183], v225 offset:37888
	ds_read_b128 v[184:187], v225 offset:38912
	ds_read_b128 v[188:191], v225 offset:39936
	global_load_lds_dwordx4 v198, s[30:31]
	s_waitcnt vmcnt(7)
	s_waitcnt lgkmcnt(0)
	s_setprio 1
	s_barrier
	v_mfma_f32_16x16x32_bf16 v[124:127], v[128:131], v[160:163], v[124:127]
	v_mfma_f32_16x16x32_bf16 v[116:119], v[136:139], v[160:163], v[116:119]
	v_mfma_f32_16x16x32_bf16 v[108:111], v[128:131], v[168:171], v[108:111]
	v_mfma_f32_16x16x32_bf16 v[100:103], v[136:139], v[168:171], v[100:103]
	v_mfma_f32_16x16x32_bf16 v[92:95], v[128:131], v[176:179], v[92:95]
	v_mfma_f32_16x16x32_bf16 v[84:87], v[136:139], v[176:179], v[84:87]
	v_mfma_f32_16x16x32_bf16 v[76:79], v[128:131], v[184:187], v[76:79]
	v_mfma_f32_16x16x32_bf16 v[68:71], v[136:139], v[184:187], v[68:71]
	v_mfma_f32_16x16x32_bf16 v[124:127], v[132:135], v[164:167], v[124:127]
	v_mfma_f32_16x16x32_bf16 v[116:119], v[140:143], v[164:167], v[116:119]
	v_mfma_f32_16x16x32_bf16 v[108:111], v[132:135], v[172:175], v[108:111]
	v_mfma_f32_16x16x32_bf16 v[100:103], v[140:143], v[172:175], v[100:103]
	v_mfma_f32_16x16x32_bf16 v[92:95], v[132:135], v[180:183], v[92:95]
	v_mfma_f32_16x16x32_bf16 v[84:87], v[140:143], v[180:183], v[84:87]
	v_mfma_f32_16x16x32_bf16 v[76:79], v[132:135], v[188:191], v[76:79]
	v_mfma_f32_16x16x32_bf16 v[68:71], v[140:143], v[188:191], v[68:71]
	s_mov_b32 m0, s47
	s_nop 0
	global_load_lds_dwordx4 v194, s[30:31]
	v_mfma_f32_16x16x32_bf16 v[120:123], v[144:147], v[160:163], v[120:123]
	v_mfma_f32_16x16x32_bf16 v[112:115], v[152:155], v[160:163], v[112:115]
	v_mfma_f32_16x16x32_bf16 v[104:107], v[144:147], v[168:171], v[104:107]
	v_mfma_f32_16x16x32_bf16 v[96:99], v[152:155], v[168:171], v[96:99]
	v_mfma_f32_16x16x32_bf16 v[88:91], v[144:147], v[176:179], v[88:91]
	v_mfma_f32_16x16x32_bf16 v[80:83], v[152:155], v[176:179], v[80:83]
	v_mfma_f32_16x16x32_bf16 v[72:75], v[144:147], v[184:187], v[72:75]
	v_mfma_f32_16x16x32_bf16 v[64:67], v[152:155], v[184:187], v[64:67]
	v_mfma_f32_16x16x32_bf16 v[120:123], v[148:151], v[164:167], v[120:123]
	v_mfma_f32_16x16x32_bf16 v[112:115], v[156:159], v[164:167], v[112:115]
	v_mfma_f32_16x16x32_bf16 v[104:107], v[148:151], v[172:175], v[104:107]
	v_mfma_f32_16x16x32_bf16 v[96:99], v[156:159], v[172:175], v[96:99]
	v_mfma_f32_16x16x32_bf16 v[88:91], v[148:151], v[180:183], v[88:91]
	v_mfma_f32_16x16x32_bf16 v[80:83], v[156:159], v[180:183], v[80:83]
	v_mfma_f32_16x16x32_bf16 v[72:75], v[148:151], v[188:191], v[72:75]
	v_mfma_f32_16x16x32_bf16 v[64:67], v[156:159], v[188:191], v[64:67]
	s_barrier
; #define PG8_STAGE(bufoff, gbase, voff) do { _Pragma("unroll") for (int _i = 0; _i < 2; ++_i) \
;         __builtin_amdgcn_global_load_lds((const unsigned*)((const char*)(gbase) + (voff)[_i]), (LAS unsigned*)(lds + (bufoff) + ldsw + _i * 8192), 16, 0, ((voff) == voffA ? AUXA : 0)); } while (0)
; #define PG8_LDA(dst, b, h) do { _Pragma("unroll") for (int m = 0; m < 4; ++m) _Pragma("unroll") for (int k = 0; k < 2; ++k) dst[m][k] = *(const LAS bf16x8*)(lds + PG8_SA(b, h) + aoff + m * 2048 + k * 1024); } while (0)
; #define PG8_LDB(dst, b, h) do { _Pragma("unroll") for (int n = 0; n < 2; ++n) _Pragma("unroll") for (int k = 0; k < 2; ++k) dst[n][k] = *(const LAS bf16x8*)(lds + PG8_SB(b, h) + boff + n * 2048 + k * 1024); } while (0)
; #define PG8_MMA(ai, bj, At, Bt) do { __builtin_amdgcn_s_setprio(1); _Pragma("unroll") for (int m = 0; m < 4; ++m) _Pragma("unroll") for (int n = 0; n < 2; ++n) _Pragma("unroll") for (int k = 0; k < 2; ++k) \
;         acc[ai][bj][m][n] = __builtin_amdgcn_mfma_f32_16x16x32_bf16(Bt[n][k], At[m][k], acc[ai][bj][m][n], 0, 0, 0); __builtin_amdgcn_s_setprio(0); } while (0)
; #define PG8_WAIT_V(n) asm volatile("s_waitcnt vmcnt(" #n ")" ::: "memory")
; #define PG8_WAIT_L(n) asm volatile("s_waitcnt lgkmcnt(" #n ")" ::: "memory")
; #define PG8_BAR __builtin_amdgcn_s_barrier()
; #define PG8_SCHED __builtin_amdgcn_sched_barrier(0)
;     ...
;             const bool last = (t == nt - 2);
;             const char* a1 = cA + (size_t)(t + 1) * kstep;
;             const char* a2 = last ? nA : cA + (size_t)(t + 2) * kstep; const char* b2 = last ? nB : cB + (size_t)(t + 2) * kstep;
;             const char* a3 = a2 + kstep; const char* b3 = b2 + kstep;
;             PG8_LDB(B0, 0, 0); PG8_LDB(B1, 0, 1); PG8_SCHED; PG8_LDA(At, 0, 0); PG8_STAGE(PG8_SA(1, 1), a1 + hsA, voffA);
;             if (Epi::NPRE != 0 && last) { E.pre(sv, cur, wr, fr); PG8_WAIT_V(16); } else { PG8_WAIT_V(8); }
;     ...
;             PG8_LDA(At, 1, 1); PG8_STAGE(PG8_SB(1, 0), b3, voffB); PG8_STAGE(PG8_SB(1, 1), b3 + hsB, voffB); PG8_STAGE(PG8_SA(1, 0), a3, voffA);
;             PG8_WAIT_V(8); PG8_WAIT_L(0); PG8_BAR; PG8_MMA(1, 0, At, B0); PG8_MMA(1, 1, At, B1); PG8_BAR; PG8_SCHED;
;         }
	s_setprio 0
	s_add_i32 s30, s34, s5
	s_mov_b32 m0, s30
	ds_read_b128 v[160:163], v225 offset:49152
	ds_read_b128 v[164:167], v225 offset:50176
	ds_read_b128 v[168:171], v225 offset:51200
	ds_read_b128 v[172:175], v225 offset:52224
	ds_read_b128 v[176:179], v225 offset:53248
	ds_read_b128 v[180:183], v225 offset:54272
	ds_read_b128 v[184:187], v225 offset:55296
	ds_read_b128 v[188:191], v225 offset:56320
	global_load_lds_dwordx4 v196, s[98:99]
	s_add_i32 m0, s30, 0x2000
	s_add_u32 s28, s28, 0x80080
	s_addc_u32 s29, s29, 0
	s_add_i32 s30, s35, s5
	global_load_lds_dwordx4 v192, s[98:99]
	s_mov_b32 m0, s30
	s_nop 0
	global_load_lds_dwordx4 v196, s[28:29]
	s_waitcnt vmcnt(5)
	s_waitcnt lgkmcnt(0)
	s_setprio 1
	s_barrier
	v_mfma_f32_16x16x32_bf16 v[60:63], v[128:131], v[160:163], v[60:63]
	v_mfma_f32_16x16x32_bf16 v[52:55], v[136:139], v[160:163], v[52:55]
	v_mfma_f32_16x16x32_bf16 v[44:47], v[128:131], v[168:171], v[44:47]
	v_mfma_f32_16x16x32_bf16 v[36:39], v[136:139], v[168:171], v[36:39]
	v_mfma_f32_16x16x32_bf16 v[28:31], v[128:131], v[176:179], v[28:31]
	v_mfma_f32_16x16x32_bf16 v[20:23], v[136:139], v[176:179], v[20:23]
	v_mfma_f32_16x16x32_bf16 v[12:15], v[128:131], v[184:187], v[12:15]
	v_mfma_f32_16x16x32_bf16 v[4:7], v[136:139], v[184:187], v[4:7]
	v_mfma_f32_16x16x32_bf16 v[60:63], v[132:135], v[164:167], v[60:63]
	v_mfma_f32_16x16x32_bf16 v[52:55], v[140:143], v[164:167], v[52:55]
	v_mfma_f32_16x16x32_bf16 v[44:47], v[132:135], v[172:175], v[44:47]
	v_mfma_f32_16x16x32_bf16 v[36:39], v[140:143], v[172:175], v[36:39]
	v_mfma_f32_16x16x32_bf16 v[28:31], v[132:135], v[180:183], v[28:31]
	v_mfma_f32_16x16x32_bf16 v[20:23], v[140:143], v[180:183], v[20:23]
	v_mfma_f32_16x16x32_bf16 v[12:15], v[132:135], v[188:191], v[12:15]
	v_mfma_f32_16x16x32_bf16 v[4:7], v[140:143], v[188:191], v[4:7]
	s_add_i32 m0, s30, 0x2000
	s_nop 0
	global_load_lds_dwordx4 v192, s[28:29]
	v_mfma_f32_16x16x32_bf16 v[56:59], v[144:147], v[160:163], v[56:59]
	v_mfma_f32_16x16x32_bf16 v[48:51], v[152:155], v[160:163], v[48:51]
	v_mfma_f32_16x16x32_bf16 v[40:43], v[144:147], v[168:171], v[40:43]
	v_mfma_f32_16x16x32_bf16 v[32:35], v[152:155], v[168:171], v[32:35]
	v_mfma_f32_16x16x32_bf16 v[24:27], v[144:147], v[176:179], v[24:27]
	v_mfma_f32_16x16x32_bf16 v[16:19], v[152:155], v[176:179], v[16:19]
	v_mfma_f32_16x16x32_bf16 v[8:11], v[144:147], v[184:187], v[8:11]
	v_mfma_f32_16x16x32_bf16 v[0:3], v[152:155], v[184:187], v[0:3]
	v_mfma_f32_16x16x32_bf16 v[56:59], v[148:151], v[164:167], v[56:59]
	v_mfma_f32_16x16x32_bf16 v[48:51], v[156:159], v[164:167], v[48:51]
	v_mfma_f32_16x16x32_bf16 v[40:43], v[148:151], v[172:175], v[40:43]
	v_mfma_f32_16x16x32_bf16 v[32:35], v[156:159], v[172:175], v[32:35]
	v_mfma_f32_16x16x32_bf16 v[24:27], v[148:151], v[180:183], v[24:27]
	v_mfma_f32_16x16x32_bf16 v[16:19], v[156:159], v[180:183], v[16:19]
	v_mfma_f32_16x16x32_bf16 v[8:11], v[148:151], v[188:191], v[8:11]
	v_mfma_f32_16x16x32_bf16 v[0:3], v[156:159], v[188:191], v[0:3]
	s_barrier
	s_setprio 0
	s_add_u32 s26, s26, 0x100
	s_addc_u32 s27, s27, 0
	s_add_u32 s59, s59, 0x100
	s_addc_u32 s60, s60, 0
	s_cmp_ge_i32 s61, s49
	s_cbranch_scc1 .LBB0_1365
.LBB0_1356:
	s_add_u32 s98, s26, 0xfff80000
	s_addc_u32 s99, s27, -1
	s_mov_b32 m0, s50
	s_nop 0
	global_load_lds_dwordx4 v198, s[98:99]
	s_mov_b32 m0, s51
	s_nop 0
	global_load_lds_dwordx4 v194, s[98:99]
	ds_read_b128 v[144:147], v223
	ds_read_b128 v[148:151], v223 offset:1024
	ds_read_b128 v[152:155], v223 offset:2048
	ds_read_b128 v[156:159], v223 offset:3072
	ds_read_b128 v[128:131], v224
	ds_read_b128 v[132:135], v224 offset:1024
	ds_read_b128 v[136:139], v224 offset:2048
	ds_read_b128 v[140:143], v224 offset:3072
	s_cmp_eq_u32 s52, s61
	s_cselect_b64 s[28:29], -1, 0
	s_cmp_lg_u32 s52, s61
	s_cselect_b64 s[34:35], -1, 0
	s_add_i32 m0, s40, 0xc000
	ds_read_b128 v[184:187], v225
	ds_read_b128 v[188:191], v225 offset:1024
	ds_read_b128 v[176:179], v225 offset:2048
	ds_read_b128 v[180:183], v225 offset:3072
	ds_read_b128 v[168:171], v225 offset:4096
	ds_read_b128 v[172:175], v225 offset:5120
	ds_read_b128 v[160:163], v225 offset:6144
	ds_read_b128 v[164:167], v225 offset:7168
	global_load_lds_dwordx4 v200, s[26:27]
	s_mov_b64 s[30:31], -1
	s_and_b64 vcc, exec, s[34:35]
	s_cbranch_vccz .LBB0_1358
	s_waitcnt vmcnt(7)
	s_mov_b64 s[30:31], 0
; #define PG8_STAGE(bufoff, gbase, voff) do { _Pragma("unroll") for (int _i = 0; _i < 2; ++_i) \
;         __builtin_amdgcn_global_load_lds((const unsigned*)((const char*)(gbase) + (voff)[_i]), (LAS unsigned*)(lds + (bufoff) + ldsw + _i * 8192), 16, 0, ((voff) == voffA ? AUXA : 0)); } while (0)
; #define PG8_LDA(dst, b, h) do { _Pragma("unroll") for (int m = 0; m < 4; ++m) _Pragma("unroll") for (int k = 0; k < 2; ++k) dst[m][k] = *(const LAS bf16x8*)(lds + PG8_SA(b, h) + aoff + m * 2048 + k * 1024); } while (0)
; #define PG8_MMA(ai, bj, At, Bt) do { __builtin_amdgcn_s_setprio(1); _Pragma("unroll") for (int m = 0; m < 4; ++m) _Pragma("unroll") for (int n = 0; n < 2; ++n) _Pragma("unroll") for (int k = 0; k < 2; ++k) \
;         acc[ai][bj][m][n] = __builtin_amdgcn_mfma_f32_16x16x32_bf16(Bt[n][k], At[m][k], acc[ai][bj][m][n], 0, 0, 0); __builtin_amdgcn_s_setprio(0); } while (0)
; #define PG8_WAIT_V(n) asm volatile("s_waitcnt vmcnt(" #n ")" ::: "memory")
; #define PG8_WAIT_L(n) asm volatile("s_waitcnt lgkmcnt(" #n ")" ::: "memory")
; #define PG8_BAR __builtin_amdgcn_s_barrier()
; #define PG8_SCHED __builtin_amdgcn_sched_barrier(0)
;     ...
;             if (Epi::NPRE != 0 && last) { E.pre(sv, cur, wr, fr); PG8_WAIT_V(16); } else { PG8_WAIT_V(8); }
;             PG8_WAIT_L(0); PG8_BAR; PG8_MMA(0, 0, At, B0); PG8_MMA(0, 1, At, B1); PG8_BAR; PG8_SCHED;
;             PG8_LDA(At, 0, 1); PG8_STAGE(PG8_SB(0, 0), b2, voffB); PG8_STAGE(PG8_SB(0, 1), b2 + hsB, voffB); PG8_STAGE(PG8_SA(0, 0), a2, voffA);
;             if (Epi::NPRE != 0 && last) { PG8_WAIT_V(16); } else { PG8_WAIT_V(8); }
;             PG8_WAIT_L(0); PG8_BAR; PG8_MMA(1, 0, At, B0); PG8_MMA(1, 1, At, B1); PG8_BAR; PG8_SCHED;
;     __device__ __forceinline__ void pre(float (&sv)[8], const Unit& u, int wr, int fr) const {
; #pragma unroll
;         for (int i = 0; i < 8; ++i) sv[i] = ss[u.pm * 256 + wr * 64 + fr + (i >> 2) * 128 + (i & 3) * 16]; }
.LBB0_1358:
	s_andn2_b64 vcc, exec, s[30:31]
	s_cbranch_vccnz .LBB0_1360
	global_load_dword v235, v[210:211], off
	global_load_dword v233, v[210:211], off offset:64
	global_load_dword v232, v[210:211], off offset:128
	global_load_dword v231, v[210:211], off offset:192
	global_load_dword v230, v[210:211], off offset:512
	global_load_dword v229, v[210:211], off offset:576
	global_load_dword v228, v[210:211], off offset:640
	global_load_dword v227, v[210:211], off offset:704
	s_waitcnt vmcnt(15)
.LBB0_1360:
	s_add_u32 s30, s26, 0xfff80080
	s_addc_u32 s31, s27, -1
	s_waitcnt lgkmcnt(0)
	s_and_b64 s[28:29], s[28:29], exec
	s_cselect_b32 s31, s19, s31
	s_cselect_b32 s30, s21, s30
	s_cselect_b32 s29, s57, s60
	s_cselect_b32 s28, s58, s59
	s_setprio 1
	s_barrier
	v_mfma_f32_16x16x32_bf16 v[124:127], v[144:147], v[184:187], v[124:127]
	v_mfma_f32_16x16x32_bf16 v[116:119], v[152:155], v[184:187], v[116:119]
	v_mfma_f32_16x16x32_bf16 v[108:111], v[144:147], v[176:179], v[108:111]
	v_mfma_f32_16x16x32_bf16 v[100:103], v[152:155], v[176:179], v[100:103]
	v_mfma_f32_16x16x32_bf16 v[92:95], v[144:147], v[168:171], v[92:95]
	v_mfma_f32_16x16x32_bf16 v[84:87], v[152:155], v[168:171], v[84:87]
	v_mfma_f32_16x16x32_bf16 v[76:79], v[144:147], v[160:163], v[76:79]
	v_mfma_f32_16x16x32_bf16 v[68:71], v[152:155], v[160:163], v[68:71]
	v_mfma_f32_16x16x32_bf16 v[124:127], v[148:151], v[188:191], v[124:127]
	v_mfma_f32_16x16x32_bf16 v[116:119], v[156:159], v[188:191], v[116:119]
	v_mfma_f32_16x16x32_bf16 v[108:111], v[148:151], v[180:183], v[108:111]
	v_mfma_f32_16x16x32_bf16 v[100:103], v[156:159], v[180:183], v[100:103]
	v_mfma_f32_16x16x32_bf16 v[92:95], v[148:151], v[172:175], v[92:95]
	v_mfma_f32_16x16x32_bf16 v[84:87], v[156:159], v[172:175], v[84:87]
	v_mfma_f32_16x16x32_bf16 v[76:79], v[148:151], v[164:167], v[76:79]
	v_mfma_f32_16x16x32_bf16 v[68:71], v[156:159], v[164:167], v[68:71]
	s_add_i32 m0, s40, 0xe000
	s_nop 0
	global_load_lds_dwordx4 v202, s[26:27]
	v_mfma_f32_16x16x32_bf16 v[120:123], v[128:131], v[184:187], v[120:123]
	v_mfma_f32_16x16x32_bf16 v[112:115], v[136:139], v[184:187], v[112:115]
	v_mfma_f32_16x16x32_bf16 v[104:107], v[128:131], v[176:179], v[104:107]
	v_mfma_f32_16x16x32_bf16 v[96:99], v[136:139], v[176:179], v[96:99]
	v_mfma_f32_16x16x32_bf16 v[88:91], v[128:131], v[168:171], v[88:91]
	v_mfma_f32_16x16x32_bf16 v[80:83], v[136:139], v[168:171], v[80:83]
	v_mfma_f32_16x16x32_bf16 v[72:75], v[128:131], v[160:163], v[72:75]
	v_mfma_f32_16x16x32_bf16 v[64:67], v[136:139], v[160:163], v[64:67]
	v_mfma_f32_16x16x32_bf16 v[120:123], v[132:135], v[188:191], v[120:123]
	v_mfma_f32_16x16x32_bf16 v[112:115], v[140:143], v[188:191], v[112:115]
	v_mfma_f32_16x16x32_bf16 v[104:107], v[132:135], v[180:183], v[104:107]
	v_mfma_f32_16x16x32_bf16 v[96:99], v[140:143], v[180:183], v[96:99]
	v_mfma_f32_16x16x32_bf16 v[88:91], v[132:135], v[172:175], v[88:91]
	v_mfma_f32_16x16x32_bf16 v[80:83], v[140:143], v[172:175], v[80:83]
	v_mfma_f32_16x16x32_bf16 v[72:75], v[132:135], v[164:167], v[72:75]
	v_mfma_f32_16x16x32_bf16 v[64:67], v[140:143], v[164:167], v[64:67]
	s_barrier
	s_setprio 0
	s_add_u32 s98, s28, s14
	s_addc_u32 s99, s29, s15
	s_add_u32 s100, s30, s14
	s_addc_u32 s101, s31, s15
	s_mov_b32 m0, s41
	s_add_u32 s36, s28, 0x80000
	ds_read_b128 v[184:187], v225 offset:16384
	ds_read_b128 v[188:191], v225 offset:17408
	ds_read_b128 v[176:179], v225 offset:18432
	ds_read_b128 v[180:183], v225 offset:19456
	ds_read_b128 v[168:171], v225 offset:20480
	ds_read_b128 v[172:175], v225 offset:21504
	ds_read_b128 v[160:163], v225 offset:22528
	ds_read_b128 v[164:167], v225 offset:23552
	global_load_lds_dwordx4 v196, s[28:29]
	s_mov_b32 m0, s42
	s_addc_u32 s37, s29, 0
	global_load_lds_dwordx4 v192, s[28:29]
	s_mov_b32 m0, s43
	s_nop 0
	global_load_lds_dwordx4 v196, s[36:37]
	s_mov_b64 s[100:101], s[36:37]
	s_mov_b64 s[36:37], -1
	s_and_b64 vcc, exec, s[34:35]
	s_cbranch_vccz .LBB0_1362
	s_waitcnt vmcnt(5)
	s_mov_b64 s[36:37], 0
.LBB0_1362:
	s_andn2_b64 vcc, exec, s[36:37]
	s_cbranch_vccnz .LBB0_1355
	s_waitcnt vmcnt(13)
	s_branch .LBB0_1355

; #define PG8_STAGE(bufoff, gbase, voff) do { _Pragma("unroll") for (int _i = 0; _i < 2; ++_i) \
;         __builtin_amdgcn_global_load_lds((const unsigned*)((const char*)(gbase) + (voff)[_i]), (LAS unsigned*)(lds + (bufoff) + ldsw + _i * 8192), 16, 0, ((voff) == voffA ? AUXA : 0)); } while (0)
; #define PG8_LDA(dst, b, h) do { _Pragma("unroll") for (int m = 0; m < 4; ++m) _Pragma("unroll") for (int k = 0; k < 2; ++k) dst[m][k] = *(const LAS bf16x8*)(lds + PG8_SA(b, h) + aoff + m * 2048 + k * 1024); } while (0)
; #define PG8_LDB(dst, b, h) do { _Pragma("unroll") for (int n = 0; n < 2; ++n) _Pragma("unroll") for (int k = 0; k < 2; ++k) dst[n][k] = *(const LAS bf16x8*)(lds + PG8_SB(b, h) + boff + n * 2048 + k * 1024); } while (0)
; #define PG8_MMA(ai, bj, At, Bt) do { __builtin_amdgcn_s_setprio(1); _Pragma("unroll") for (int m = 0; m < 4; ++m) _Pragma("unroll") for (int n = 0; n < 2; ++n) _Pragma("unroll") for (int k = 0; k < 2; ++k) \
;         acc[ai][bj][m][n] = __builtin_amdgcn_mfma_f32_16x16x32_bf16(Bt[n][k], At[m][k], acc[ai][bj][m][n], 0, 0, 0); __builtin_amdgcn_s_setprio(0); } while (0)
; #define PG8_WAIT_V(n) asm volatile("s_waitcnt vmcnt(" #n ")" ::: "memory")
; #define PG8_WAIT_L(n) asm volatile("s_waitcnt lgkmcnt(" #n ")" ::: "memory")
; #define PG8_BAR __builtin_amdgcn_s_barrier()
; #define PG8_SCHED __builtin_amdgcn_sched_barrier(0)
;     ...
;             PG8_LDB(B0, 0, 0); PG8_LDB(B1, 0, 1); PG8_SCHED; PG8_LDA(At, 0, 0); PG8_STAGE(PG8_SA(1, 1), a1 + hsA, voffA);
;             if (Epi::NPRE != 0 && last) { E.pre(sv, cur, wr, fr); PG8_WAIT_V(16); } else { PG8_WAIT_V(8); }
;             PG8_WAIT_L(0); PG8_BAR; PG8_MMA(0, 0, At, B0); PG8_MMA(0, 1, At, B1); PG8_BAR; PG8_SCHED;
;             PG8_LDA(At, 0, 1); PG8_STAGE(PG8_SB(0, 0), b2, voffB); PG8_STAGE(PG8_SB(0, 1), b2 + hsB, voffB); PG8_STAGE(PG8_SA(0, 0), a2, voffA);
;             if (Epi::NPRE != 0 && last) { PG8_WAIT_V(16); } else { PG8_WAIT_V(8); }
;             PG8_WAIT_L(0); PG8_BAR; PG8_MMA(1, 0, At, B0); PG8_MMA(1, 1, At, B1); PG8_BAR; PG8_SCHED;
.LBB0_1440:
	s_add_u32 s98, s16, 0xffea0000
	s_addc_u32 s99, s17, -1
	s_mov_b32 m0, s34
	s_nop 0
	global_load_lds_dwordx4 v134, s[98:99]
	s_mov_b32 m0, s35
	s_nop 0
	global_load_lds_dwordx4 v130, s[98:99]
	ds_read_b128 v[144:147], v159
	ds_read_b128 v[148:151], v159 offset:1024
	ds_read_b128 v[152:155], v159 offset:2048
	ds_read_b128 v[162:165], v159 offset:3072
	ds_read_b128 v[166:169], v160
	ds_read_b128 v[170:173], v160 offset:1024
	ds_read_b128 v[174:177], v160 offset:2048
	ds_read_b128 v[178:181], v160 offset:3072
	s_add_i32 s46, s18, 2
	s_add_u32 s19, s16, 0xffea0080
	s_addc_u32 s20, s17, -1
	s_cmp_eq_u32 s36, s18
	s_cselect_b32 s18, s14, s44
	s_cselect_b32 s21, s5, s20
	s_cselect_b32 s20, s4, s19
	s_cselect_b32 s19, s15, s45
	s_add_i32 m0, s26, 0xc000
	ds_read_b128 v[182:185], v161
	ds_read_b128 v[186:189], v161 offset:1024
	ds_read_b128 v[190:193], v161 offset:2048
	ds_read_b128 v[194:197], v161 offset:3072
	ds_read_b128 v[198:201], v161 offset:4096
	ds_read_b128 v[202:205], v161 offset:5120
	ds_read_b128 v[206:209], v161 offset:6144
	ds_read_b128 v[210:213], v161 offset:7168
	global_load_lds_dwordx4 v136, s[16:17]
	s_waitcnt vmcnt(7)
	s_waitcnt lgkmcnt(0)
	s_setprio 1
	s_barrier
	v_mfma_f32_16x16x32_bf16 v[124:127], v[144:147], v[182:185], v[124:127]
	v_mfma_f32_16x16x32_bf16 v[120:123], v[152:155], v[182:185], v[120:123]
	v_mfma_f32_16x16x32_bf16 v[116:119], v[144:147], v[190:193], v[116:119]
	v_mfma_f32_16x16x32_bf16 v[112:115], v[152:155], v[190:193], v[112:115]
	v_mfma_f32_16x16x32_bf16 v[104:107], v[144:147], v[198:201], v[104:107]
	v_mfma_f32_16x16x32_bf16 v[96:99], v[152:155], v[198:201], v[96:99]
	v_mfma_f32_16x16x32_bf16 v[88:91], v[144:147], v[206:209], v[88:91]
	v_mfma_f32_16x16x32_bf16 v[80:83], v[152:155], v[206:209], v[80:83]
	v_mfma_f32_16x16x32_bf16 v[124:127], v[148:151], v[186:189], v[124:127]
	v_mfma_f32_16x16x32_bf16 v[120:123], v[162:165], v[186:189], v[120:123]
	v_mfma_f32_16x16x32_bf16 v[116:119], v[148:151], v[194:197], v[116:119]
	v_mfma_f32_16x16x32_bf16 v[112:115], v[162:165], v[194:197], v[112:115]
	v_mfma_f32_16x16x32_bf16 v[104:107], v[148:151], v[202:205], v[104:107]
	v_mfma_f32_16x16x32_bf16 v[96:99], v[162:165], v[202:205], v[96:99]
	v_mfma_f32_16x16x32_bf16 v[88:91], v[148:151], v[210:213], v[88:91]
	v_mfma_f32_16x16x32_bf16 v[80:83], v[162:165], v[210:213], v[80:83]
	s_add_i32 m0, s26, 0xe000
	s_nop 0
	global_load_lds_dwordx4 v138, s[16:17]
	v_mfma_f32_16x16x32_bf16 v[108:111], v[166:169], v[182:185], v[108:111]
	v_mfma_f32_16x16x32_bf16 v[100:103], v[174:177], v[182:185], v[100:103]
	v_mfma_f32_16x16x32_bf16 v[92:95], v[166:169], v[190:193], v[92:95]
	v_mfma_f32_16x16x32_bf16 v[84:87], v[174:177], v[190:193], v[84:87]
	v_mfma_f32_16x16x32_bf16 v[76:79], v[166:169], v[198:201], v[76:79]
	v_mfma_f32_16x16x32_bf16 v[72:75], v[174:177], v[198:201], v[72:75]
	v_mfma_f32_16x16x32_bf16 v[68:71], v[166:169], v[206:209], v[68:71]
	v_mfma_f32_16x16x32_bf16 v[64:67], v[174:177], v[206:209], v[64:67]
	v_mfma_f32_16x16x32_bf16 v[108:111], v[170:173], v[186:189], v[108:111]
	v_mfma_f32_16x16x32_bf16 v[100:103], v[178:181], v[186:189], v[100:103]
	v_mfma_f32_16x16x32_bf16 v[92:95], v[170:173], v[194:197], v[92:95]
	v_mfma_f32_16x16x32_bf16 v[84:87], v[178:181], v[194:197], v[84:87]
	v_mfma_f32_16x16x32_bf16 v[76:79], v[170:173], v[202:205], v[76:79]
	v_mfma_f32_16x16x32_bf16 v[72:75], v[178:181], v[202:205], v[72:75]
	v_mfma_f32_16x16x32_bf16 v[68:71], v[170:173], v[210:213], v[68:71]
	v_mfma_f32_16x16x32_bf16 v[64:67], v[178:181], v[210:213], v[64:67]
	s_barrier
	s_setprio 0
	s_add_u32 s98, s18, s8
	s_addc_u32 s99, s19, s9
	s_add_u32 s100, s20, s8
	s_addc_u32 s101, s21, s9
	s_add_i32 s47, s38, s23
	s_mov_b32 m0, s47
	ds_read_b128 v[182:185], v161 offset:16384
	ds_read_b128 v[186:189], v161 offset:17408
	ds_read_b128 v[190:193], v161 offset:18432
	ds_read_b128 v[194:197], v161 offset:19456
	ds_read_b128 v[198:201], v161 offset:20480
	ds_read_b128 v[202:205], v161 offset:21504
	ds_read_b128 v[206:209], v161 offset:22528
	ds_read_b128 v[210:213], v161 offset:23552
	global_load_lds_dwordx4 v132, s[18:19]
	s_add_i32 m0, s47, 0x2000
	s_add_u32 s48, s18, 0x160000
	s_addc_u32 s49, s19, 0
	s_add_i32 s47, s39, s23
	global_load_lds_dwordx4 v128, s[18:19]
	s_mov_b32 m0, s47
	s_nop 0
	global_load_lds_dwordx4 v132, s[48:49]
	s_waitcnt vmcnt(5)
	s_waitcnt lgkmcnt(0)
	s_setprio 1
	s_barrier
	v_mfma_f32_16x16x32_bf16 v[60:63], v[144:147], v[182:185], v[60:63]
	v_mfma_f32_16x16x32_bf16 v[56:59], v[152:155], v[182:185], v[56:59]
	v_mfma_f32_16x16x32_bf16 v[52:55], v[144:147], v[190:193], v[52:55]
	v_mfma_f32_16x16x32_bf16 v[48:51], v[152:155], v[190:193], v[48:51]
	v_mfma_f32_16x16x32_bf16 v[40:43], v[144:147], v[198:201], v[40:43]
	v_mfma_f32_16x16x32_bf16 v[32:35], v[152:155], v[198:201], v[32:35]
	v_mfma_f32_16x16x32_bf16 v[24:27], v[144:147], v[206:209], v[24:27]
	v_mfma_f32_16x16x32_bf16 v[16:19], v[152:155], v[206:209], v[16:19]
	v_mfma_f32_16x16x32_bf16 v[60:63], v[148:151], v[186:189], v[60:63]
	v_mfma_f32_16x16x32_bf16 v[56:59], v[162:165], v[186:189], v[56:59]
	v_mfma_f32_16x16x32_bf16 v[52:55], v[148:151], v[194:197], v[52:55]
	v_mfma_f32_16x16x32_bf16 v[48:51], v[162:165], v[194:197], v[48:51]
	v_mfma_f32_16x16x32_bf16 v[40:43], v[148:151], v[202:205], v[40:43]
	v_mfma_f32_16x16x32_bf16 v[32:35], v[162:165], v[202:205], v[32:35]
	v_mfma_f32_16x16x32_bf16 v[24:27], v[148:151], v[210:213], v[24:27]
	v_mfma_f32_16x16x32_bf16 v[16:19], v[162:165], v[210:213], v[16:19]
	s_add_i32 m0, s47, 0x2000
	s_nop 0
	global_load_lds_dwordx4 v128, s[48:49]
	v_mfma_f32_16x16x32_bf16 v[44:47], v[166:169], v[182:185], v[44:47]
	v_mfma_f32_16x16x32_bf16 v[36:39], v[174:177], v[182:185], v[36:39]
	v_mfma_f32_16x16x32_bf16 v[28:31], v[166:169], v[190:193], v[28:31]
	v_mfma_f32_16x16x32_bf16 v[20:23], v[174:177], v[190:193], v[20:23]
	v_mfma_f32_16x16x32_bf16 v[12:15], v[166:169], v[198:201], v[12:15]
	v_mfma_f32_16x16x32_bf16 v[8:11], v[174:177], v[198:201], v[8:11]
	v_mfma_f32_16x16x32_bf16 v[4:7], v[166:169], v[206:209], v[4:7]
	v_mfma_f32_16x16x32_bf16 v[0:3], v[174:177], v[206:209], v[0:3]
	v_mfma_f32_16x16x32_bf16 v[44:47], v[170:173], v[186:189], v[44:47]
	v_mfma_f32_16x16x32_bf16 v[36:39], v[178:181], v[186:189], v[36:39]
	v_mfma_f32_16x16x32_bf16 v[28:31], v[170:173], v[194:197], v[28:31]
	v_mfma_f32_16x16x32_bf16 v[20:23], v[178:181], v[194:197], v[20:23]
	v_mfma_f32_16x16x32_bf16 v[12:15], v[170:173], v[202:205], v[12:15]
	v_mfma_f32_16x16x32_bf16 v[8:11], v[178:181], v[202:205], v[8:11]
	v_mfma_f32_16x16x32_bf16 v[4:7], v[170:173], v[210:213], v[4:7]
	v_mfma_f32_16x16x32_bf16 v[0:3], v[178:181], v[210:213], v[0:3]
	s_barrier
; #define PG8_STAGE(bufoff, gbase, voff) do { _Pragma("unroll") for (int _i = 0; _i < 2; ++_i) \
;         __builtin_amdgcn_global_load_lds((const unsigned*)((const char*)(gbase) + (voff)[_i]), (LAS unsigned*)(lds + (bufoff) + ldsw + _i * 8192), 16, 0, ((voff) == voffA ? AUXA : 0)); } while (0)
; #define PG8_LDA(dst, b, h) do { _Pragma("unroll") for (int m = 0; m < 4; ++m) _Pragma("unroll") for (int k = 0; k < 2; ++k) dst[m][k] = *(const LAS bf16x8*)(lds + PG8_SA(b, h) + aoff + m * 2048 + k * 1024); } while (0)
; #define PG8_LDB(dst, b, h) do { _Pragma("unroll") for (int n = 0; n < 2; ++n) _Pragma("unroll") for (int k = 0; k < 2; ++k) dst[n][k] = *(const LAS bf16x8*)(lds + PG8_SB(b, h) + boff + n * 2048 + k * 1024); } while (0)
; #define PG8_MMA(ai, bj, At, Bt) do { __builtin_amdgcn_s_setprio(1); _Pragma("unroll") for (int m = 0; m < 4; ++m) _Pragma("unroll") for (int n = 0; n < 2; ++n) _Pragma("unroll") for (int k = 0; k < 2; ++k) \
;         acc[ai][bj][m][n] = __builtin_amdgcn_mfma_f32_16x16x32_bf16(Bt[n][k], At[m][k], acc[ai][bj][m][n], 0, 0, 0); __builtin_amdgcn_s_setprio(0); } while (0)
; #define PG8_WAIT_V(n) asm volatile("s_waitcnt vmcnt(" #n ")" ::: "memory")
; #define PG8_WAIT_L(n) asm volatile("s_waitcnt lgkmcnt(" #n ")" ::: "memory")
; #define PG8_BAR __builtin_amdgcn_s_barrier()
; #define PG8_SCHED __builtin_amdgcn_sched_barrier(0)
;     ...
;             PG8_LDB(B0, 1, 0); PG8_LDB(B1, 1, 1); PG8_SCHED; PG8_LDA(At, 1, 0); PG8_STAGE(PG8_SA(0, 1), a2 + hsA, voffA);
;             PG8_WAIT_V(8); PG8_WAIT_L(0); PG8_BAR; PG8_MMA(0, 0, At, B0); PG8_MMA(0, 1, At, B1); PG8_BAR; PG8_SCHED;
;             PG8_LDA(At, 1, 1); PG8_STAGE(PG8_SB(1, 0), b3, voffB); PG8_STAGE(PG8_SB(1, 1), b3 + hsB, voffB); PG8_STAGE(PG8_SA(1, 0), a3, voffA);
;             PG8_WAIT_V(8); PG8_WAIT_L(0); PG8_BAR; PG8_MMA(1, 0, At, B0); PG8_MMA(1, 1, At, B1); PG8_BAR; PG8_SCHED;
	s_mov_b32 m0, s26
	s_nop 0
	global_load_lds_dwordx4 v134, s[20:21]
	s_mov_b32 m0, s27
	s_nop 0
	global_load_lds_dwordx4 v130, s[20:21]
	s_setprio 0
	s_add_i32 s47, 0, 0x18000
	s_add_i32 s48, 0, 0x1c000
	v_add_u32_e32 v162, s47, v157
	v_add_u32_e32 v178, s48, v157
	ds_read_b128 v[144:147], v162
	ds_read_b128 v[148:151], v162 offset:1024
	ds_read_b128 v[152:155], v162 offset:2048
	ds_read_b128 v[162:165], v162 offset:3072
	ds_read_b128 v[166:169], v178
	ds_read_b128 v[170:173], v178 offset:1024
	ds_read_b128 v[174:177], v178 offset:2048
	ds_read_b128 v[178:181], v178 offset:3072
	s_add_u32 s20, s20, 0x160000
	s_addc_u32 s21, s21, 0
	s_mov_b32 m0, s28
	ds_read_b128 v[182:185], v161 offset:32768
	ds_read_b128 v[186:189], v161 offset:33792
	ds_read_b128 v[190:193], v161 offset:34816
	ds_read_b128 v[194:197], v161 offset:35840
	ds_read_b128 v[198:201], v161 offset:36864
	ds_read_b128 v[202:205], v161 offset:37888
	ds_read_b128 v[206:209], v161 offset:38912
	ds_read_b128 v[210:213], v161 offset:39936
	global_load_lds_dwordx4 v134, s[20:21]
	s_waitcnt vmcnt(7)
	s_waitcnt lgkmcnt(0)
	s_setprio 1
	s_barrier
	v_mfma_f32_16x16x32_bf16 v[124:127], v[144:147], v[182:185], v[124:127]
	v_mfma_f32_16x16x32_bf16 v[120:123], v[152:155], v[182:185], v[120:123]
	v_mfma_f32_16x16x32_bf16 v[116:119], v[144:147], v[190:193], v[116:119]
	v_mfma_f32_16x16x32_bf16 v[112:115], v[152:155], v[190:193], v[112:115]
	v_mfma_f32_16x16x32_bf16 v[104:107], v[144:147], v[198:201], v[104:107]
	v_mfma_f32_16x16x32_bf16 v[96:99], v[152:155], v[198:201], v[96:99]
	v_mfma_f32_16x16x32_bf16 v[88:91], v[144:147], v[206:209], v[88:91]
	v_mfma_f32_16x16x32_bf16 v[80:83], v[152:155], v[206:209], v[80:83]
	v_mfma_f32_16x16x32_bf16 v[124:127], v[148:151], v[186:189], v[124:127]
	v_mfma_f32_16x16x32_bf16 v[120:123], v[162:165], v[186:189], v[120:123]
	v_mfma_f32_16x16x32_bf16 v[116:119], v[148:151], v[194:197], v[116:119]
	v_mfma_f32_16x16x32_bf16 v[112:115], v[162:165], v[194:197], v[112:115]
	v_mfma_f32_16x16x32_bf16 v[104:107], v[148:151], v[202:205], v[104:107]
	v_mfma_f32_16x16x32_bf16 v[96:99], v[162:165], v[202:205], v[96:99]
	v_mfma_f32_16x16x32_bf16 v[88:91], v[148:151], v[210:213], v[88:91]
	v_mfma_f32_16x16x32_bf16 v[80:83], v[162:165], v[210:213], v[80:83]
	s_mov_b32 m0, s29
	s_nop 0
	global_load_lds_dwordx4 v130, s[20:21]
	v_mfma_f32_16x16x32_bf16 v[108:111], v[166:169], v[182:185], v[108:111]
	v_mfma_f32_16x16x32_bf16 v[100:103], v[174:177], v[182:185], v[100:103]
	v_mfma_f32_16x16x32_bf16 v[92:95], v[166:169], v[190:193], v[92:95]
	v_mfma_f32_16x16x32_bf16 v[84:87], v[174:177], v[190:193], v[84:87]
	v_mfma_f32_16x16x32_bf16 v[76:79], v[166:169], v[198:201], v[76:79]
	v_mfma_f32_16x16x32_bf16 v[72:75], v[174:177], v[198:201], v[72:75]
	v_mfma_f32_16x16x32_bf16 v[68:71], v[166:169], v[206:209], v[68:71]
	v_mfma_f32_16x16x32_bf16 v[64:67], v[174:177], v[206:209], v[64:67]
	v_mfma_f32_16x16x32_bf16 v[108:111], v[170:173], v[186:189], v[108:111]
	v_mfma_f32_16x16x32_bf16 v[100:103], v[178:181], v[186:189], v[100:103]
	v_mfma_f32_16x16x32_bf16 v[92:95], v[170:173], v[194:197], v[92:95]
	v_mfma_f32_16x16x32_bf16 v[84:87], v[178:181], v[194:197], v[84:87]
	v_mfma_f32_16x16x32_bf16 v[76:79], v[170:173], v[202:205], v[76:79]
	v_mfma_f32_16x16x32_bf16 v[72:75], v[178:181], v[202:205], v[72:75]
	v_mfma_f32_16x16x32_bf16 v[68:71], v[170:173], v[210:213], v[68:71]
	v_mfma_f32_16x16x32_bf16 v[64:67], v[178:181], v[210:213], v[64:67]
	s_barrier
	s_setprio 0
	s_add_i32 s20, s47, s23
	s_mov_b32 m0, s20
	ds_read_b128 v[182:185], v161 offset:49152
	ds_read_b128 v[186:189], v161 offset:50176
	ds_read_b128 v[190:193], v161 offset:51200
	ds_read_b128 v[194:197], v161 offset:52224
	ds_read_b128 v[198:201], v161 offset:53248
	ds_read_b128 v[202:205], v161 offset:54272
	ds_read_b128 v[206:209], v161 offset:55296
	ds_read_b128 v[210:213], v161 offset:56320
	global_load_lds_dwordx4 v132, s[98:99]
	s_add_i32 m0, s20, 0x2000
	s_add_u32 s18, s18, 0x160080
	s_addc_u32 s19, s19, 0
	s_add_i32 s20, s48, s23
	global_load_lds_dwordx4 v128, s[98:99]
	s_mov_b32 m0, s20
	s_nop 0
	global_load_lds_dwordx4 v132, s[18:19]
	s_waitcnt vmcnt(5)
	s_waitcnt lgkmcnt(0)
	s_setprio 1
	s_barrier
; #define PG8_MMA(ai, bj, At, Bt) do { __builtin_amdgcn_s_setprio(1); _Pragma("unroll") for (int m = 0; m < 4; ++m) _Pragma("unroll") for (int n = 0; n < 2; ++n) _Pragma("unroll") for (int k = 0; k < 2; ++k) \
;         acc[ai][bj][m][n] = __builtin_amdgcn_mfma_f32_16x16x32_bf16(Bt[n][k], At[m][k], acc[ai][bj][m][n], 0, 0, 0); __builtin_amdgcn_s_setprio(0); } while (0)
; #define PG8_WAIT_V(n) asm volatile("s_waitcnt vmcnt(" #n ")" ::: "memory")
; #define PG8_WAIT_L(n) asm volatile("s_waitcnt lgkmcnt(" #n ")" ::: "memory")
; #define PG8_BAR __builtin_amdgcn_s_barrier()
; #define PG8_SCHED __builtin_amdgcn_sched_barrier(0)
;     ...
;             PG8_WAIT_V(8); PG8_WAIT_L(0); PG8_BAR; PG8_MMA(1, 0, At, B0); PG8_MMA(1, 1, At, B1); PG8_BAR; PG8_SCHED;
;         }
;     __device__ __forceinline__ void operator()(const Acc& acc, const Unit& u, int wr, int wc, int fr, int fq, const float (&sv8)[8]) const {
;     ...
;                     const int col = colb + bj * 128;
;                     const f32x4 y0 = xr[m][bj][0] + acc[ai][bj][m][0] * scale, y1 = xr[m][bj][1] + acc[ai][bj][m][1] * scale;
	v_mfma_f32_16x16x32_bf16 v[60:63], v[144:147], v[182:185], v[60:63]
	v_mfma_f32_16x16x32_bf16 v[56:59], v[152:155], v[182:185], v[56:59]
	v_mfma_f32_16x16x32_bf16 v[52:55], v[144:147], v[190:193], v[52:55]
	v_mfma_f32_16x16x32_bf16 v[48:51], v[152:155], v[190:193], v[48:51]
	v_mfma_f32_16x16x32_bf16 v[40:43], v[144:147], v[198:201], v[40:43]
	v_mfma_f32_16x16x32_bf16 v[32:35], v[152:155], v[198:201], v[32:35]
	v_mfma_f32_16x16x32_bf16 v[24:27], v[144:147], v[206:209], v[24:27]
	v_mfma_f32_16x16x32_bf16 v[16:19], v[152:155], v[206:209], v[16:19]
	v_mfma_f32_16x16x32_bf16 v[60:63], v[148:151], v[186:189], v[60:63]
	v_mfma_f32_16x16x32_bf16 v[56:59], v[162:165], v[186:189], v[56:59]
	v_mfma_f32_16x16x32_bf16 v[52:55], v[148:151], v[194:197], v[52:55]
	v_mfma_f32_16x16x32_bf16 v[48:51], v[162:165], v[194:197], v[48:51]
	v_mfma_f32_16x16x32_bf16 v[40:43], v[148:151], v[202:205], v[40:43]
	v_mfma_f32_16x16x32_bf16 v[32:35], v[162:165], v[202:205], v[32:35]
	v_mfma_f32_16x16x32_bf16 v[24:27], v[148:151], v[210:213], v[24:27]
	v_mfma_f32_16x16x32_bf16 v[16:19], v[162:165], v[210:213], v[16:19]
	s_add_i32 m0, s20, 0x2000
	s_nop 0
	global_load_lds_dwordx4 v128, s[18:19]
	v_mfma_f32_16x16x32_bf16 v[44:47], v[166:169], v[182:185], v[44:47]
	v_mfma_f32_16x16x32_bf16 v[36:39], v[174:177], v[182:185], v[36:39]
	v_mfma_f32_16x16x32_bf16 v[28:31], v[166:169], v[190:193], v[28:31]
	v_mfma_f32_16x16x32_bf16 v[20:23], v[174:177], v[190:193], v[20:23]
	v_mfma_f32_16x16x32_bf16 v[12:15], v[166:169], v[198:201], v[12:15]
	v_mfma_f32_16x16x32_bf16 v[8:11], v[174:177], v[198:201], v[8:11]
	v_mfma_f32_16x16x32_bf16 v[4:7], v[166:169], v[206:209], v[4:7]
	v_mfma_f32_16x16x32_bf16 v[0:3], v[174:177], v[206:209], v[0:3]
	v_mfma_f32_16x16x32_bf16 v[44:47], v[170:173], v[186:189], v[44:47]
	v_mfma_f32_16x16x32_bf16 v[36:39], v[178:181], v[186:189], v[36:39]
	v_mfma_f32_16x16x32_bf16 v[28:31], v[170:173], v[194:197], v[28:31]
	v_mfma_f32_16x16x32_bf16 v[20:23], v[178:181], v[194:197], v[20:23]
	v_mfma_f32_16x16x32_bf16 v[12:15], v[170:173], v[202:205], v[12:15]
	v_mfma_f32_16x16x32_bf16 v[8:11], v[178:181], v[202:205], v[8:11]
	v_mfma_f32_16x16x32_bf16 v[4:7], v[170:173], v[210:213], v[4:7]
	v_mfma_f32_16x16x32_bf16 v[0:3], v[178:181], v[210:213], v[0:3]
	s_barrier
	s_setprio 0
	s_add_u32 s16, s16, 0x100
	s_addc_u32 s17, s17, 0
	s_add_u32 s44, s44, 0x100
	s_addc_u32 s45, s45, 0
	s_cmp_ge_i32 s46, s31
	s_mov_b32 s18, s46
	s_cbranch_scc0 .LBB0_1440
	v_pk_mul_f32 v[126:127], v[126:127], 0.5 op_sel_hi:[1,0]
	v_pk_mul_f32 v[146:147], v[124:125], 0.5 op_sel_hi:[1,0]
	v_pk_mul_f32 v[144:145], v[122:123], 0.5 op_sel_hi:[1,0]
	v_pk_mul_f32 v[124:125], v[120:121], 0.5 op_sel_hi:[1,0]
	v_pk_mul_f32 v[154:155], v[110:111], 0.5 op_sel_hi:[1,0]
	v_pk_mul_f32 v[152:153], v[108:109], 0.5 op_sel_hi:[1,0]
	v_pk_mul_f32 v[150:151], v[102:103], 0.5 op_sel_hi:[1,0]
	v_pk_mul_f32 v[148:149], v[100:101], 0.5 op_sel_hi:[1,0]
	v_pk_mul_f32 v[118:119], v[118:119], 0.5 op_sel_hi:[1,0]
	v_pk_mul_f32 v[116:117], v[116:117], 0.5 op_sel_hi:[1,0]
	v_pk_mul_f32 v[110:111], v[114:115], 0.5 op_sel_hi:[1,0]
	v_pk_mul_f32 v[108:109], v[112:113], 0.5 op_sel_hi:[1,0]
	v_pk_mul_f32 v[122:123], v[94:95], 0.5 op_sel_hi:[1,0]
	v_pk_mul_f32 v[120:121], v[92:93], 0.5 op_sel_hi:[1,0]
	v_pk_mul_f32 v[114:115], v[86:87], 0.5 op_sel_hi:[1,0]
	v_pk_mul_f32 v[112:113], v[84:85], 0.5 op_sel_hi:[1,0]
	v_pk_mul_f32 v[102:103], v[106:107], 0.5 op_sel_hi:[1,0]
	v_pk_mul_f32 v[100:101], v[104:105], 0.5 op_sel_hi:[1,0]
	v_pk_mul_f32 v[94:95], v[98:99], 0.5 op_sel_hi:[1,0]
	v_pk_mul_f32 v[92:93], v[96:97], 0.5 op_sel_hi:[1,0]
	v_pk_mul_f32 v[106:107], v[78:79], 0.5 op_sel_hi:[1,0]
	v_pk_mul_f32 v[104:105], v[76:77], 0.5 op_sel_hi:[1,0]
	v_pk_mul_f32 v[98:99], v[74:75], 0.5 op_sel_hi:[1,0]
	v_pk_mul_f32 v[96:97], v[72:73], 0.5 op_sel_hi:[1,0]
	v_pk_mul_f32 v[86:87], v[90:91], 0.5 op_sel_hi:[1,0]
	v_pk_mul_f32 v[84:85], v[88:89], 0.5 op_sel_hi:[1,0]
	v_pk_mul_f32 v[78:79], v[82:83], 0.5 op_sel_hi:[1,0]
	v_pk_mul_f32 v[76:77], v[80:81], 0.5 op_sel_hi:[1,0]
	v_pk_mul_f32 v[90:91], v[70:71], 0.5 op_sel_hi:[1,0]
	v_pk_mul_f32 v[88:89], v[68:69], 0.5 op_sel_hi:[1,0]
	v_pk_mul_f32 v[82:83], v[66:67], 0.5 op_sel_hi:[1,0]
	v_pk_mul_f32 v[80:81], v[64:65], 0.5 op_sel_hi:[1,0]
	v_pk_mul_f32 v[66:67], v[62:63], 0.5 op_sel_hi:[1,0]
	v_pk_mul_f32 v[64:65], v[60:61], 0.5 op_sel_hi:[1,0]
	v_pk_mul_f32 v[62:63], v[58:59], 0.5 op_sel_hi:[1,0]
	v_pk_mul_f32 v[60:61], v[56:57], 0.5 op_sel_hi:[1,0]
	v_pk_mul_f32 v[74:75], v[46:47], 0.5 op_sel_hi:[1,0]
	v_pk_mul_f32 v[72:73], v[44:45], 0.5 op_sel_hi:[1,0]
	v_pk_mul_f32 v[70:71], v[38:39], 0.5 op_sel_hi:[1,0]
	v_pk_mul_f32 v[68:69], v[36:37], 0.5 op_sel_hi:[1,0]
	v_pk_mul_f32 v[54:55], v[54:55], 0.5 op_sel_hi:[1,0]
	v_pk_mul_f32 v[52:53], v[52:53], 0.5 op_sel_hi:[1,0]
	v_pk_mul_f32 v[46:47], v[50:51], 0.5 op_sel_hi:[1,0]
	v_pk_mul_f32 v[44:45], v[48:49], 0.5 op_sel_hi:[1,0]
	v_pk_mul_f32 v[58:59], v[30:31], 0.5 op_sel_hi:[1,0]
	v_pk_mul_f32 v[56:57], v[28:29], 0.5 op_sel_hi:[1,0]
	v_pk_mul_f32 v[50:51], v[22:23], 0.5 op_sel_hi:[1,0]
	v_pk_mul_f32 v[48:49], v[20:21], 0.5 op_sel_hi:[1,0]
	v_pk_mul_f32 v[30:31], v[42:43], 0.5 op_sel_hi:[1,0]
	v_pk_mul_f32 v[28:29], v[40:41], 0.5 op_sel_hi:[1,0]
	v_pk_mul_f32 v[22:23], v[34:35], 0.5 op_sel_hi:[1,0]
	v_pk_mul_f32 v[20:21], v[32:33], 0.5 op_sel_hi:[1,0]
	v_pk_mul_f32 v[38:39], v[14:15], 0.5 op_sel_hi:[1,0]
	v_pk_mul_f32 v[36:37], v[12:13], 0.5 op_sel_hi:[1,0]
	v_pk_mul_f32 v[34:35], v[10:11], 0.5 op_sel_hi:[1,0]
	v_pk_mul_f32 v[32:33], v[8:9], 0.5 op_sel_hi:[1,0]
	v_pk_mul_f32 v[14:15], v[26:27], 0.5 op_sel_hi:[1,0]
	v_pk_mul_f32 v[12:13], v[24:25], 0.5 op_sel_hi:[1,0]
	v_pk_mul_f32 v[10:11], v[18:19], 0.5 op_sel_hi:[1,0]
	v_pk_mul_f32 v[8:9], v[16:17], 0.5 op_sel_hi:[1,0]
	v_pk_mul_f32 v[6:7], v[6:7], 0.5 op_sel_hi:[1,0]
	v_pk_mul_f32 v[4:5], v[4:5], 0.5 op_sel_hi:[1,0]
	v_pk_mul_f32 v[2:3], v[2:3], 0.5 op_sel_hi:[1,0]
	v_pk_mul_f32 v[0:1], v[0:1], 0.5 op_sel_hi:[1,0]
